# qk_epilogue rewrite: batched cos/sin/gain loads issued before the ss pass, rope math from registers (10 sites), on top of epi+ada+cmpd+kmean+cmp2
# speedup vs baseline: 1.0471x; 1.0026x over previous
; DI int otid() { int t = threadIdx.x; asm volatile("" : "+v"(t)); return t; }
; DI void qk_epilogue(const float* st  , int m0, const float* __restrict__ gain, float scale, bf16_t* __restrict__ dst, int dstride, int dcol0,
;                     const float* __restrict__ COS, const float* __restrict__ SIN) {
;   const int tid = otid(), row = tid & 127, hd = tid >> 7;
;   const float* sp = st + row * 132 + hd * 64;
;   float ss = 0.f;
; #pragma unroll 4
;   for (int j = 0; j < 64; j += 4) { const float4 v = *(const float4*)(sp + j); ss += v.x * v.x + v.y * v.y + v.z * v.z + v.w * v.w; }
;   const float rr = rsqrtf(ss * (1.f / 64.f) + 1e-6f);
;   const size_t tok = (size_t)(m0 + row);
;   bf16_t* dp = dst + tok * dstride + dcol0 + hd * 64;
; #pragma unroll 2
;   for (int j = 0; j < 32; j += 8) {
;     float o1[8], o2[8];
; #pragma unroll
;     for (int q = 0; q < 8; ++q) {
;       const float x1 = sp[j + q] * rr * gain[j + q], x2 = sp[j + q + 32] * rr * gain[j + q + 32];
;       const float cs = COS[tok * 32 + j + q], sn = SIN[tok * 32 + j + q];
.LBB0_345:
	s_and_b64 vcc, exec, s[50:51]
	s_cbranch_vccz .LBB0_350
	v_lshlrev_b32_e32 v136, 2, v231
	s_mov_b32 vcc_lo, s53
	s_mov_b32 vcc_hi, s54
	global_load_dword v182, v136, vcc
	s_add_i32 s98, s64, s65
	v_and_b32_e32 v134, 0x7f, v216
	v_add_lshl_u32 v134, v134, s98, 7
	v_add_u32_e32 v135, 0x2178000, v134
	v_add_u32_e32 v134, 0x1f78000, v134
	global_load_dwordx4 v[150:153], v134, s[82:83]
	global_load_dwordx4 v[154:157], v135, s[82:83]
	global_load_dwordx4 v[164:167], v134, s[82:83] offset:16
	global_load_dwordx4 v[168:171], v135, s[82:83] offset:16
	global_load_dwordx4 v[174:177], v134, s[82:83] offset:32
	global_load_dwordx4 v[178:181], v135, s[82:83] offset:32
	global_load_dwordx4 v[186:189], v134, s[82:83] offset:48
	global_load_dwordx4 v[190:193], v135, s[82:83] offset:48
	global_load_dwordx4 v[194:197], v134, s[82:83] offset:64
	global_load_dwordx4 v[198:201], v135, s[82:83] offset:64
	global_load_dwordx4 v[202:205], v134, s[82:83] offset:80
	global_load_dwordx4 v[210:213], v135, s[82:83] offset:80
	global_load_dwordx4 v[236:239], v134, s[82:83] offset:96
	global_load_dwordx4 v[248:251], v135, s[82:83] offset:96
	global_load_dwordx4 v[252:255], v134, s[82:83] offset:112
	v_mov_b32_e32 v130, v216
	s_mov_b32 s9, -4
	v_and_b32_e32 v0, 0x7f, v130
	v_ashrrev_i32_e32 v130, 1, v130
	v_and_b32_e32 v130, 0xffffffc0, v130
	v_lshlrev_b32_e32 v131, 2, v130
	v_mad_u32_u24 v172, v0, s8, v131
	v_mov_b32_e32 v131, 0
	v_mov_b32_e32 v132, v172

; DI uint4 pack8(const float* v) { uint4 r; r.x = pk2(v[0], v[1]); r.y = pk2(v[2], v[3]); r.z = pk2(v[4], v[5]); r.w = pk2(v[6], v[7]); return r; }
; DI void qk_epilogue(const float* st  , int m0, const float* __restrict__ gain, float scale, bf16_t* __restrict__ dst, int dstride, int dcol0,
;                     const float* __restrict__ COS, const float* __restrict__ SIN) {
;     ...
;   for (int j = 0; j < 32; j += 8) {
;     float o1[8], o2[8];
; #pragma unroll
;     for (int q = 0; q < 8; ++q) {
;       const float x1 = sp[j + q] * rr * gain[j + q], x2 = sp[j + q + 32] * rr * gain[j + q + 32];
;       const float cs = COS[tok * 32 + j + q], sn = SIN[tok * 32 + j + q];
;       o1[q] = (x1 * cs - x2 * sn) * scale;
;       o2[q] = (x2 * cs + x1 * sn) * scale;
;     }
;     *(uint4*)(dp + j) = pack8(o1);
;     *(uint4*)(dp + j + 32) = pack8(o2);
;   }
.LBB0_349:
	s_add_i32 s98, s64, s65
	v_and_b32_e32 v134, 0x7f, v216
	v_add_lshl_u32 v134, v134, s98, 7
	v_add_u32_e32 v135, 0x2178000, v134
	v_add_u32_e32 v134, 0x1f78000, v134
	global_load_dwordx4 v[130:133], v135, s[82:83] offset:112
	v_lshl_add_u64 v[160:161], s[82:83], 0, v[160:161]
	v_add_co_u32_e32 v160, vcc, s26, v160
	v_addc_co_u32_e32 v161, vcc, 0, v161, vcc
	ds_read_b64 v[142:143], v173
	ds_read_b64 v[146:147], v173 offset:128
	ds_read_b64 v[144:145], v173 offset:8
	ds_read_b64 v[148:149], v173 offset:136
	s_waitcnt vmcnt(14)
	s_waitcnt lgkmcnt(2)
	v_readlane_b32 s98, v182, 0
	v_readlane_b32 s99, v182, 1
	v_readlane_b32 vcc_lo, v182, 32
	v_readlane_b32 vcc_hi, v182, 33
	v_pk_mul_f32 v[142:143], v[158:159], v[142:143]
	v_pk_mul_f32 v[146:147], v[158:159], v[146:147]
	v_pk_mul_f32 v[142:143], v[142:143], s[98:99]
	v_pk_mul_f32 v[146:147], v[146:147], vcc
	v_pk_mul_f32 v[162:163], v[142:143], v[154:155]
	s_nop 0
	v_pk_fma_f32 v[162:163], v[146:147], v[150:151], v[162:163]
	v_pk_mul_f32 v[146:147], v[146:147], v[154:155]
	s_nop 0
	v_pk_fma_f32 v[142:143], v[142:143], v[150:151], v[146:147] neg_lo:[0,0,1] neg_hi:[0,0,1]
	v_cvt_pk_bf16_f32 v138, v162, v163
	v_cvt_pk_bf16_f32 v134, v142, v143
	ds_read_b64 v[142:143], v173 offset:16
	ds_read_b64 v[146:147], v173 offset:144
	s_waitcnt lgkmcnt(2)
	v_readlane_b32 s98, v182, 2
	v_readlane_b32 s99, v182, 3
	v_readlane_b32 vcc_lo, v182, 34
	v_readlane_b32 vcc_hi, v182, 35
	v_pk_mul_f32 v[144:145], v[158:159], v[144:145]
	v_pk_mul_f32 v[148:149], v[158:159], v[148:149]
	v_pk_mul_f32 v[144:145], v[144:145], s[98:99]
	v_pk_mul_f32 v[148:149], v[148:149], vcc
	v_pk_mul_f32 v[162:163], v[144:145], v[156:157]
	s_nop 0
	v_pk_fma_f32 v[162:163], v[148:149], v[152:153], v[162:163]
	v_pk_mul_f32 v[148:149], v[148:149], v[156:157]
	s_nop 0
	v_pk_fma_f32 v[144:145], v[144:145], v[152:153], v[148:149] neg_lo:[0,0,1] neg_hi:[0,0,1]
	v_cvt_pk_bf16_f32 v139, v162, v163
	v_cvt_pk_bf16_f32 v135, v144, v145
	ds_read_b64 v[144:145], v173 offset:24
	ds_read_b64 v[148:149], v173 offset:152
	s_waitcnt vmcnt(12)
	s_waitcnt lgkmcnt(2)
	v_readlane_b32 s98, v182, 4
	v_readlane_b32 s99, v182, 5
	v_readlane_b32 vcc_lo, v182, 36
	v_readlane_b32 vcc_hi, v182, 37
	v_pk_mul_f32 v[142:143], v[158:159], v[142:143]
	v_pk_mul_f32 v[146:147], v[158:159], v[146:147]
	v_pk_mul_f32 v[142:143], v[142:143], s[98:99]
	v_pk_mul_f32 v[146:147], v[146:147], vcc
	v_pk_mul_f32 v[162:163], v[142:143], v[168:169]
	s_nop 0
	v_pk_fma_f32 v[162:163], v[146:147], v[164:165], v[162:163]
	v_pk_mul_f32 v[146:147], v[146:147], v[168:169]
	s_nop 0
	v_pk_fma_f32 v[142:143], v[142:143], v[164:165], v[146:147] neg_lo:[0,0,1] neg_hi:[0,0,1]
	v_cvt_pk_bf16_f32 v140, v162, v163
	v_cvt_pk_bf16_f32 v136, v142, v143
	ds_read_b64 v[142:143], v173 offset:32
	ds_read_b64 v[146:147], v173 offset:160
	s_waitcnt lgkmcnt(2)
	v_readlane_b32 s98, v182, 6
	v_readlane_b32 s99, v182, 7
	v_readlane_b32 vcc_lo, v182, 38
	v_readlane_b32 vcc_hi, v182, 39
	v_pk_mul_f32 v[144:145], v[158:159], v[144:145]
	v_pk_mul_f32 v[148:149], v[158:159], v[148:149]
	v_pk_mul_f32 v[144:145], v[144:145], s[98:99]
	v_pk_mul_f32 v[148:149], v[148:149], vcc
	v_pk_mul_f32 v[162:163], v[144:145], v[170:171]
	s_nop 0
	v_pk_fma_f32 v[162:163], v[148:149], v[166:167], v[162:163]
	v_pk_mul_f32 v[148:149], v[148:149], v[170:171]
	s_nop 0
	v_pk_fma_f32 v[144:145], v[144:145], v[166:167], v[148:149] neg_lo:[0,0,1] neg_hi:[0,0,1]
	v_cvt_pk_bf16_f32 v141, v162, v163
	v_cvt_pk_bf16_f32 v137, v144, v145
	ds_read_b64 v[144:145], v173 offset:40
	ds_read_b64 v[148:149], v173 offset:168
	global_store_dwordx4 v[160:161], v[134:137], off
	global_store_dwordx4 v[160:161], v[138:141], off offset:64
	s_waitcnt vmcnt(12)
	s_waitcnt lgkmcnt(2)
	v_readlane_b32 s98, v182, 8
	v_readlane_b32 s99, v182, 9
	v_readlane_b32 vcc_lo, v182, 40
	v_readlane_b32 vcc_hi, v182, 41
	v_pk_mul_f32 v[142:143], v[158:159], v[142:143]
	v_pk_mul_f32 v[146:147], v[158:159], v[146:147]
	v_pk_mul_f32 v[142:143], v[142:143], s[98:99]
	v_pk_mul_f32 v[146:147], v[146:147], vcc
	v_pk_mul_f32 v[162:163], v[142:143], v[178:179]
	s_nop 0
	v_pk_fma_f32 v[162:163], v[146:147], v[174:175], v[162:163]
	v_pk_mul_f32 v[146:147], v[146:147], v[178:179]
	s_nop 0
	v_pk_fma_f32 v[142:143], v[142:143], v[174:175], v[146:147] neg_lo:[0,0,1] neg_hi:[0,0,1]
	v_cvt_pk_bf16_f32 v138, v162, v163
	v_cvt_pk_bf16_f32 v134, v142, v143
	ds_read_b64 v[142:143], v173 offset:48
	ds_read_b64 v[146:147], v173 offset:176
	s_waitcnt lgkmcnt(2)
	v_readlane_b32 s98, v182, 10
	v_readlane_b32 s99, v182, 11
	v_readlane_b32 vcc_lo, v182, 42
	v_readlane_b32 vcc_hi, v182, 43
	v_pk_mul_f32 v[144:145], v[158:159], v[144:145]
	v_pk_mul_f32 v[148:149], v[158:159], v[148:149]
	v_pk_mul_f32 v[144:145], v[144:145], s[98:99]
	v_pk_mul_f32 v[148:149], v[148:149], vcc
	v_pk_mul_f32 v[162:163], v[144:145], v[180:181]
	s_nop 0
	v_pk_fma_f32 v[162:163], v[148:149], v[176:177], v[162:163]
	v_pk_mul_f32 v[148:149], v[148:149], v[180:181]
	s_nop 0
	v_pk_fma_f32 v[144:145], v[144:145], v[176:177], v[148:149] neg_lo:[0,0,1] neg_hi:[0,0,1]
	v_cvt_pk_bf16_f32 v139, v162, v163
	v_cvt_pk_bf16_f32 v135, v144, v145
	ds_read_b64 v[144:145], v173 offset:56
	ds_read_b64 v[148:149], v173 offset:184
	s_waitcnt vmcnt(10)
	s_waitcnt lgkmcnt(2)
; DI uint4 pack8(const float* v) { uint4 r; r.x = pk2(v[0], v[1]); r.y = pk2(v[2], v[3]); r.z = pk2(v[4], v[5]); r.w = pk2(v[6], v[7]); return r; }
; DI void qk_epilogue(const float* st  , int m0, const float* __restrict__ gain, float scale, bf16_t* __restrict__ dst, int dstride, int dcol0,
;                     const float* __restrict__ COS, const float* __restrict__ SIN) {
;     ...
;   for (int j = 0; j < 32; j += 8) {
;     float o1[8], o2[8];
; #pragma unroll
;     for (int q = 0; q < 8; ++q) {
;       const float x1 = sp[j + q] * rr * gain[j + q], x2 = sp[j + q + 32] * rr * gain[j + q + 32];
;       const float cs = COS[tok * 32 + j + q], sn = SIN[tok * 32 + j + q];
;       o1[q] = (x1 * cs - x2 * sn) * scale;
;       o2[q] = (x2 * cs + x1 * sn) * scale;
;     }
;     *(uint4*)(dp + j) = pack8(o1);
;     *(uint4*)(dp + j + 32) = pack8(o2);
;   }
	v_readlane_b32 s98, v182, 12
	v_readlane_b32 s99, v182, 13
	v_readlane_b32 vcc_lo, v182, 44
	v_readlane_b32 vcc_hi, v182, 45
	v_pk_mul_f32 v[142:143], v[158:159], v[142:143]
	v_pk_mul_f32 v[146:147], v[158:159], v[146:147]
	v_pk_mul_f32 v[142:143], v[142:143], s[98:99]
	v_pk_mul_f32 v[146:147], v[146:147], vcc
	v_pk_mul_f32 v[162:163], v[142:143], v[190:191]
	s_nop 0
	v_pk_fma_f32 v[162:163], v[146:147], v[186:187], v[162:163]
	v_pk_mul_f32 v[146:147], v[146:147], v[190:191]
	s_nop 0
	v_pk_fma_f32 v[142:143], v[142:143], v[186:187], v[146:147] neg_lo:[0,0,1] neg_hi:[0,0,1]
	v_cvt_pk_bf16_f32 v140, v162, v163
	v_cvt_pk_bf16_f32 v136, v142, v143
	ds_read_b64 v[142:143], v173 offset:64
	ds_read_b64 v[146:147], v173 offset:192
	s_waitcnt lgkmcnt(2)
	v_readlane_b32 s98, v182, 14
	v_readlane_b32 s99, v182, 15
	v_readlane_b32 vcc_lo, v182, 46
	v_readlane_b32 vcc_hi, v182, 47
	v_pk_mul_f32 v[144:145], v[158:159], v[144:145]
	v_pk_mul_f32 v[148:149], v[158:159], v[148:149]
	v_pk_mul_f32 v[144:145], v[144:145], s[98:99]
	v_pk_mul_f32 v[148:149], v[148:149], vcc
	v_pk_mul_f32 v[162:163], v[144:145], v[192:193]
	s_nop 0
	v_pk_fma_f32 v[162:163], v[148:149], v[188:189], v[162:163]
	v_pk_mul_f32 v[148:149], v[148:149], v[192:193]
	s_nop 0
	v_pk_fma_f32 v[144:145], v[144:145], v[188:189], v[148:149] neg_lo:[0,0,1] neg_hi:[0,0,1]
	v_cvt_pk_bf16_f32 v141, v162, v163
	v_cvt_pk_bf16_f32 v137, v144, v145
	ds_read_b64 v[144:145], v173 offset:72
	ds_read_b64 v[148:149], v173 offset:200
	global_store_dwordx4 v[160:161], v[134:137], off offset:16
	global_store_dwordx4 v[160:161], v[138:141], off offset:80
	s_waitcnt vmcnt(10)
	s_waitcnt lgkmcnt(2)
	v_readlane_b32 s98, v182, 16
	v_readlane_b32 s99, v182, 17
	v_readlane_b32 vcc_lo, v182, 48
	v_readlane_b32 vcc_hi, v182, 49
	v_pk_mul_f32 v[142:143], v[158:159], v[142:143]
	v_pk_mul_f32 v[146:147], v[158:159], v[146:147]
	v_pk_mul_f32 v[142:143], v[142:143], s[98:99]
	v_pk_mul_f32 v[146:147], v[146:147], vcc
	v_pk_mul_f32 v[162:163], v[142:143], v[198:199]
	s_nop 0
	v_pk_fma_f32 v[162:163], v[146:147], v[194:195], v[162:163]
	v_pk_mul_f32 v[146:147], v[146:147], v[198:199]
	s_nop 0
	v_pk_fma_f32 v[142:143], v[142:143], v[194:195], v[146:147] neg_lo:[0,0,1] neg_hi:[0,0,1]
	v_cvt_pk_bf16_f32 v138, v162, v163
	v_cvt_pk_bf16_f32 v134, v142, v143
	ds_read_b64 v[142:143], v173 offset:80
	ds_read_b64 v[146:147], v173 offset:208
	s_waitcnt lgkmcnt(2)
	v_readlane_b32 s98, v182, 18
	v_readlane_b32 s99, v182, 19
	v_readlane_b32 vcc_lo, v182, 50
	v_readlane_b32 vcc_hi, v182, 51
	v_pk_mul_f32 v[144:145], v[158:159], v[144:145]
	v_pk_mul_f32 v[148:149], v[158:159], v[148:149]
	v_pk_mul_f32 v[144:145], v[144:145], s[98:99]
	v_pk_mul_f32 v[148:149], v[148:149], vcc
	v_pk_mul_f32 v[162:163], v[144:145], v[200:201]
	s_nop 0
	v_pk_fma_f32 v[162:163], v[148:149], v[196:197], v[162:163]
	v_pk_mul_f32 v[148:149], v[148:149], v[200:201]
	s_nop 0
	v_pk_fma_f32 v[144:145], v[144:145], v[196:197], v[148:149] neg_lo:[0,0,1] neg_hi:[0,0,1]
	v_cvt_pk_bf16_f32 v139, v162, v163
	v_cvt_pk_bf16_f32 v135, v144, v145
	ds_read_b64 v[144:145], v173 offset:88
	ds_read_b64 v[148:149], v173 offset:216
	s_waitcnt vmcnt(8)
	s_waitcnt lgkmcnt(2)
	v_readlane_b32 s98, v182, 20
	v_readlane_b32 s99, v182, 21
	v_readlane_b32 vcc_lo, v182, 52
	v_readlane_b32 vcc_hi, v182, 53
	v_pk_mul_f32 v[142:143], v[158:159], v[142:143]
	v_pk_mul_f32 v[146:147], v[158:159], v[146:147]
	v_pk_mul_f32 v[142:143], v[142:143], s[98:99]
	v_pk_mul_f32 v[146:147], v[146:147], vcc
	v_pk_mul_f32 v[162:163], v[142:143], v[210:211]
	s_nop 0
	v_pk_fma_f32 v[162:163], v[146:147], v[202:203], v[162:163]
	v_pk_mul_f32 v[146:147], v[146:147], v[210:211]
	s_nop 0
	v_pk_fma_f32 v[142:143], v[142:143], v[202:203], v[146:147] neg_lo:[0,0,1] neg_hi:[0,0,1]
	v_cvt_pk_bf16_f32 v140, v162, v163
	v_cvt_pk_bf16_f32 v136, v142, v143
	ds_read_b64 v[142:143], v173 offset:96
	ds_read_b64 v[146:147], v173 offset:224
	s_waitcnt lgkmcnt(2)
; DI uint4 pack8(const float* v) { uint4 r; r.x = pk2(v[0], v[1]); r.y = pk2(v[2], v[3]); r.z = pk2(v[4], v[5]); r.w = pk2(v[6], v[7]); return r; }
; DI void qk_epilogue(const float* st  , int m0, const float* __restrict__ gain, float scale, bf16_t* __restrict__ dst, int dstride, int dcol0,
;                     const float* __restrict__ COS, const float* __restrict__ SIN) {
;     ...
;   for (int j = 0; j < 32; j += 8) {
;     float o1[8], o2[8];
; #pragma unroll
;     for (int q = 0; q < 8; ++q) {
;       const float x1 = sp[j + q] * rr * gain[j + q], x2 = sp[j + q + 32] * rr * gain[j + q + 32];
;       const float cs = COS[tok * 32 + j + q], sn = SIN[tok * 32 + j + q];
;       o1[q] = (x1 * cs - x2 * sn) * scale;
;       o2[q] = (x2 * cs + x1 * sn) * scale;
;     }
;     *(uint4*)(dp + j) = pack8(o1);
;     *(uint4*)(dp + j + 32) = pack8(o2);
;   }
	v_readlane_b32 s98, v182, 22
	v_readlane_b32 s99, v182, 23
	v_readlane_b32 vcc_lo, v182, 54
	v_readlane_b32 vcc_hi, v182, 55
	v_pk_mul_f32 v[144:145], v[158:159], v[144:145]
	v_pk_mul_f32 v[148:149], v[158:159], v[148:149]
	v_pk_mul_f32 v[144:145], v[144:145], s[98:99]
	v_pk_mul_f32 v[148:149], v[148:149], vcc
	v_pk_mul_f32 v[162:163], v[144:145], v[212:213]
	s_nop 0
	v_pk_fma_f32 v[162:163], v[148:149], v[204:205], v[162:163]
	v_pk_mul_f32 v[148:149], v[148:149], v[212:213]
	s_nop 0
	v_pk_fma_f32 v[144:145], v[144:145], v[204:205], v[148:149] neg_lo:[0,0,1] neg_hi:[0,0,1]
	v_cvt_pk_bf16_f32 v141, v162, v163
	v_cvt_pk_bf16_f32 v137, v144, v145
	ds_read_b64 v[144:145], v173 offset:104
	ds_read_b64 v[148:149], v173 offset:232
	global_store_dwordx4 v[160:161], v[134:137], off offset:32
	global_store_dwordx4 v[160:161], v[138:141], off offset:96
	s_waitcnt vmcnt(8)
	s_waitcnt lgkmcnt(2)
	v_readlane_b32 s98, v182, 24
	v_readlane_b32 s99, v182, 25
	v_readlane_b32 vcc_lo, v182, 56
	v_readlane_b32 vcc_hi, v182, 57
	v_pk_mul_f32 v[142:143], v[158:159], v[142:143]
	v_pk_mul_f32 v[146:147], v[158:159], v[146:147]
	v_pk_mul_f32 v[142:143], v[142:143], s[98:99]
	v_pk_mul_f32 v[146:147], v[146:147], vcc
	v_pk_mul_f32 v[162:163], v[142:143], v[248:249]
	s_nop 0
	v_pk_fma_f32 v[162:163], v[146:147], v[236:237], v[162:163]
	v_pk_mul_f32 v[146:147], v[146:147], v[248:249]
	s_nop 0
	v_pk_fma_f32 v[142:143], v[142:143], v[236:237], v[146:147] neg_lo:[0,0,1] neg_hi:[0,0,1]
	v_cvt_pk_bf16_f32 v138, v162, v163
	v_cvt_pk_bf16_f32 v134, v142, v143
	ds_read_b64 v[142:143], v173 offset:112
	ds_read_b64 v[146:147], v173 offset:240
	s_waitcnt lgkmcnt(2)
	v_readlane_b32 s98, v182, 26
	v_readlane_b32 s99, v182, 27
	v_readlane_b32 vcc_lo, v182, 58
	v_readlane_b32 vcc_hi, v182, 59
	v_pk_mul_f32 v[144:145], v[158:159], v[144:145]
	v_pk_mul_f32 v[148:149], v[158:159], v[148:149]
	v_pk_mul_f32 v[144:145], v[144:145], s[98:99]
	v_pk_mul_f32 v[148:149], v[148:149], vcc
	v_pk_mul_f32 v[162:163], v[144:145], v[250:251]
	s_nop 0
	v_pk_fma_f32 v[162:163], v[148:149], v[238:239], v[162:163]
	v_pk_mul_f32 v[148:149], v[148:149], v[250:251]
	s_nop 0
	v_pk_fma_f32 v[144:145], v[144:145], v[238:239], v[148:149] neg_lo:[0,0,1] neg_hi:[0,0,1]
	v_cvt_pk_bf16_f32 v139, v162, v163
	v_cvt_pk_bf16_f32 v135, v144, v145
	ds_read_b64 v[144:145], v173 offset:120
	ds_read_b64 v[148:149], v173 offset:248
	s_waitcnt vmcnt(6)
	s_waitcnt lgkmcnt(2)
	v_readlane_b32 s98, v182, 28
	v_readlane_b32 s99, v182, 29
	v_readlane_b32 vcc_lo, v182, 60
	v_readlane_b32 vcc_hi, v182, 61
	v_pk_mul_f32 v[142:143], v[158:159], v[142:143]
	v_pk_mul_f32 v[146:147], v[158:159], v[146:147]
	v_pk_mul_f32 v[142:143], v[142:143], s[98:99]
	v_pk_mul_f32 v[146:147], v[146:147], vcc
	v_pk_mul_f32 v[162:163], v[142:143], v[130:131]
	s_nop 0
	v_pk_fma_f32 v[162:163], v[146:147], v[252:253], v[162:163]
	v_pk_mul_f32 v[146:147], v[146:147], v[130:131]
	s_nop 0
	v_pk_fma_f32 v[142:143], v[142:143], v[252:253], v[146:147] neg_lo:[0,0,1] neg_hi:[0,0,1]
	v_cvt_pk_bf16_f32 v140, v162, v163
	v_cvt_pk_bf16_f32 v136, v142, v143
	s_waitcnt lgkmcnt(0)
	v_readlane_b32 s98, v182, 30
	v_readlane_b32 s99, v182, 31
	v_readlane_b32 vcc_lo, v182, 62
	v_readlane_b32 vcc_hi, v182, 63
	v_pk_mul_f32 v[144:145], v[158:159], v[144:145]
	v_pk_mul_f32 v[148:149], v[158:159], v[148:149]
	v_pk_mul_f32 v[144:145], v[144:145], s[98:99]
	v_pk_mul_f32 v[148:149], v[148:149], vcc
	v_pk_mul_f32 v[162:163], v[144:145], v[132:133]
	s_nop 0
	v_pk_fma_f32 v[162:163], v[148:149], v[254:255], v[162:163]
	v_pk_mul_f32 v[148:149], v[148:149], v[132:133]
	s_nop 0
	v_pk_fma_f32 v[144:145], v[144:145], v[254:255], v[148:149] neg_lo:[0,0,1] neg_hi:[0,0,1]
	v_cvt_pk_bf16_f32 v141, v162, v163
	v_cvt_pk_bf16_f32 v137, v144, v145
	global_store_dwordx4 v[160:161], v[134:137], off offset:48
	global_store_dwordx4 v[160:161], v[138:141], off offset:112

; DI int otid() { int t = threadIdx.x; asm volatile("" : "+v"(t)); return t; }
; DI void qk_epilogue(const float* st  , int m0, const float* __restrict__ gain, float scale, bf16_t* __restrict__ dst, int dstride, int dcol0,
;                     const float* __restrict__ COS, const float* __restrict__ SIN) {
;   const int tid = otid(), row = tid & 127, hd = tid >> 7;
;   const float* sp = st + row * 132 + hd * 64;
;   float ss = 0.f;
; #pragma unroll 4
;   for (int j = 0; j < 64; j += 4) { const float4 v = *(const float4*)(sp + j); ss += v.x * v.x + v.y * v.y + v.z * v.z + v.w * v.w; }
;   const float rr = rsqrtf(ss * (1.f / 64.f) + 1e-6f);
;   const size_t tok = (size_t)(m0 + row);
;   bf16_t* dp = dst + tok * dstride + dcol0 + hd * 64;
; #pragma unroll 2
;   for (int j = 0; j < 32; j += 8) {
;     float o1[8], o2[8];
; #pragma unroll
;     for (int q = 0; q < 8; ++q) {
;       const float x1 = sp[j + q] * rr * gain[j + q], x2 = sp[j + q + 32] * rr * gain[j + q + 32];
;       const float cs = COS[tok * 32 + j + q], sn = SIN[tok * 32 + j + q];
.LBB0_355:
	s_and_b64 vcc, exec, s[50:51]
	s_cbranch_vccz .LBB0_395
	s_cmp_gt_i32 s0, 4
	s_mov_b64 s[48:49], -1
	s_mov_b32 s50, 0x9b78000
	s_cbranch_scc0 .LBB0_475
	s_cmp_gt_i32 s0, 5
	s_cbranch_scc0 .LBB0_363
	v_lshlrev_b32_e32 v136, 2, v231
	s_mov_b32 vcc_lo, s53
	s_mov_b32 vcc_hi, s54
	global_load_dword v182, v136, vcc
	s_add_i32 s98, s64, s65
	v_and_b32_e32 v134, 0x7f, v216
	v_add_lshl_u32 v134, v134, s98, 7
	v_add_u32_e32 v135, 0x2178000, v134
	v_add_u32_e32 v134, 0x1f78000, v134
	global_load_dwordx4 v[150:153], v134, s[82:83]
	global_load_dwordx4 v[154:157], v135, s[82:83]
	global_load_dwordx4 v[164:167], v134, s[82:83] offset:16
	global_load_dwordx4 v[168:171], v135, s[82:83] offset:16
	global_load_dwordx4 v[174:177], v134, s[82:83] offset:32
	global_load_dwordx4 v[178:181], v135, s[82:83] offset:32
	global_load_dwordx4 v[186:189], v134, s[82:83] offset:48
	global_load_dwordx4 v[190:193], v135, s[82:83] offset:48
	global_load_dwordx4 v[194:197], v134, s[82:83] offset:64
	global_load_dwordx4 v[198:201], v135, s[82:83] offset:64
	global_load_dwordx4 v[202:205], v134, s[82:83] offset:80
	global_load_dwordx4 v[210:213], v135, s[82:83] offset:80
	global_load_dwordx4 v[236:239], v134, s[82:83] offset:96
	global_load_dwordx4 v[248:251], v135, s[82:83] offset:96
	global_load_dwordx4 v[252:255], v134, s[82:83] offset:112
	v_mov_b32_e32 v130, v216
	s_mov_b32 s9, -4
	v_and_b32_e32 v0, 0x7f, v130
	v_ashrrev_i32_e32 v130, 1, v130
	v_and_b32_e32 v130, 0xffffffc0, v130
	v_lshlrev_b32_e32 v131, 2, v130
	v_mad_u32_u24 v172, v0, s8, v131
	v_mov_b32_e32 v131, 0
	v_mov_b32_e32 v132, v172

; DI uint4 pack8(const float* v) { uint4 r; r.x = pk2(v[0], v[1]); r.y = pk2(v[2], v[3]); r.z = pk2(v[4], v[5]); r.w = pk2(v[6], v[7]); return r; }
; DI void qk_epilogue(const float* st  , int m0, const float* __restrict__ gain, float scale, bf16_t* __restrict__ dst, int dstride, int dcol0,
;                     const float* __restrict__ COS, const float* __restrict__ SIN) {
;     ...
;   for (int j = 0; j < 32; j += 8) {
;     float o1[8], o2[8];
; #pragma unroll
;     for (int q = 0; q < 8; ++q) {
;       const float x1 = sp[j + q] * rr * gain[j + q], x2 = sp[j + q + 32] * rr * gain[j + q + 32];
;       const float cs = COS[tok * 32 + j + q], sn = SIN[tok * 32 + j + q];
;       o1[q] = (x1 * cs - x2 * sn) * scale;
;       o2[q] = (x2 * cs + x1 * sn) * scale;
;     }
;     *(uint4*)(dp + j) = pack8(o1);
;     *(uint4*)(dp + j + 32) = pack8(o2);
;   }
.LBB0_361:
	s_add_i32 s98, s64, s65
	v_and_b32_e32 v134, 0x7f, v216
	v_add_lshl_u32 v134, v134, s98, 7
	v_add_u32_e32 v135, 0x2178000, v134
	v_add_u32_e32 v134, 0x1f78000, v134
	global_load_dwordx4 v[130:133], v135, s[82:83] offset:112
	v_lshl_add_u64 v[160:161], s[82:83], 0, v[160:161]
	v_add_co_u32_e32 v160, vcc, s26, v160
	v_addc_co_u32_e32 v161, vcc, 0, v161, vcc
	ds_read_b64 v[142:143], v173
	ds_read_b64 v[146:147], v173 offset:128
	ds_read_b64 v[144:145], v173 offset:8
	ds_read_b64 v[148:149], v173 offset:136
	s_waitcnt vmcnt(14)
	s_waitcnt lgkmcnt(2)
	v_readlane_b32 s98, v182, 0
	v_readlane_b32 s99, v182, 1
	v_readlane_b32 vcc_lo, v182, 32
	v_readlane_b32 vcc_hi, v182, 33
	v_pk_mul_f32 v[142:143], v[158:159], v[142:143]
	v_pk_mul_f32 v[146:147], v[158:159], v[146:147]
	v_pk_mul_f32 v[142:143], v[142:143], s[98:99]
	v_pk_mul_f32 v[146:147], v[146:147], vcc
	v_pk_mul_f32 v[162:163], v[142:143], v[154:155]
	s_nop 0
	v_pk_fma_f32 v[162:163], v[146:147], v[150:151], v[162:163]
	v_pk_mul_f32 v[146:147], v[146:147], v[154:155]
	s_nop 0
	v_pk_fma_f32 v[142:143], v[142:143], v[150:151], v[146:147] neg_lo:[0,0,1] neg_hi:[0,0,1]
	v_cvt_pk_bf16_f32 v138, v162, v163
	v_cvt_pk_bf16_f32 v134, v142, v143
	ds_read_b64 v[142:143], v173 offset:16
	ds_read_b64 v[146:147], v173 offset:144
	s_waitcnt lgkmcnt(2)
	v_readlane_b32 s98, v182, 2
	v_readlane_b32 s99, v182, 3
	v_readlane_b32 vcc_lo, v182, 34
	v_readlane_b32 vcc_hi, v182, 35
	v_pk_mul_f32 v[144:145], v[158:159], v[144:145]
	v_pk_mul_f32 v[148:149], v[158:159], v[148:149]
	v_pk_mul_f32 v[144:145], v[144:145], s[98:99]
	v_pk_mul_f32 v[148:149], v[148:149], vcc
	v_pk_mul_f32 v[162:163], v[144:145], v[156:157]
	s_nop 0
	v_pk_fma_f32 v[162:163], v[148:149], v[152:153], v[162:163]
	v_pk_mul_f32 v[148:149], v[148:149], v[156:157]
	s_nop 0
	v_pk_fma_f32 v[144:145], v[144:145], v[152:153], v[148:149] neg_lo:[0,0,1] neg_hi:[0,0,1]
	v_cvt_pk_bf16_f32 v139, v162, v163
	v_cvt_pk_bf16_f32 v135, v144, v145
	ds_read_b64 v[144:145], v173 offset:24
	ds_read_b64 v[148:149], v173 offset:152
	s_waitcnt vmcnt(12)
	s_waitcnt lgkmcnt(2)
	v_readlane_b32 s98, v182, 4
	v_readlane_b32 s99, v182, 5
	v_readlane_b32 vcc_lo, v182, 36
	v_readlane_b32 vcc_hi, v182, 37
	v_pk_mul_f32 v[142:143], v[158:159], v[142:143]
	v_pk_mul_f32 v[146:147], v[158:159], v[146:147]
	v_pk_mul_f32 v[142:143], v[142:143], s[98:99]
	v_pk_mul_f32 v[146:147], v[146:147], vcc
	v_pk_mul_f32 v[162:163], v[142:143], v[168:169]
	s_nop 0
	v_pk_fma_f32 v[162:163], v[146:147], v[164:165], v[162:163]
	v_pk_mul_f32 v[146:147], v[146:147], v[168:169]
	s_nop 0
	v_pk_fma_f32 v[142:143], v[142:143], v[164:165], v[146:147] neg_lo:[0,0,1] neg_hi:[0,0,1]
	v_cvt_pk_bf16_f32 v140, v162, v163
	v_cvt_pk_bf16_f32 v136, v142, v143
	ds_read_b64 v[142:143], v173 offset:32
	ds_read_b64 v[146:147], v173 offset:160
	s_waitcnt lgkmcnt(2)
	v_readlane_b32 s98, v182, 6
	v_readlane_b32 s99, v182, 7
	v_readlane_b32 vcc_lo, v182, 38
	v_readlane_b32 vcc_hi, v182, 39
	v_pk_mul_f32 v[144:145], v[158:159], v[144:145]
	v_pk_mul_f32 v[148:149], v[158:159], v[148:149]
	v_pk_mul_f32 v[144:145], v[144:145], s[98:99]
	v_pk_mul_f32 v[148:149], v[148:149], vcc
	v_pk_mul_f32 v[162:163], v[144:145], v[170:171]
	s_nop 0
	v_pk_fma_f32 v[162:163], v[148:149], v[166:167], v[162:163]
	v_pk_mul_f32 v[148:149], v[148:149], v[170:171]
	s_nop 0
	v_pk_fma_f32 v[144:145], v[144:145], v[166:167], v[148:149] neg_lo:[0,0,1] neg_hi:[0,0,1]
	v_cvt_pk_bf16_f32 v141, v162, v163
	v_cvt_pk_bf16_f32 v137, v144, v145
	ds_read_b64 v[144:145], v173 offset:40
	ds_read_b64 v[148:149], v173 offset:168
	global_store_dwordx4 v[160:161], v[134:137], off
	global_store_dwordx4 v[160:161], v[138:141], off offset:64
	s_waitcnt vmcnt(12)
	s_waitcnt lgkmcnt(2)
	v_readlane_b32 s98, v182, 8
	v_readlane_b32 s99, v182, 9
	v_readlane_b32 vcc_lo, v182, 40
	v_readlane_b32 vcc_hi, v182, 41
	v_pk_mul_f32 v[142:143], v[158:159], v[142:143]
	v_pk_mul_f32 v[146:147], v[158:159], v[146:147]
	v_pk_mul_f32 v[142:143], v[142:143], s[98:99]
	v_pk_mul_f32 v[146:147], v[146:147], vcc
	v_pk_mul_f32 v[162:163], v[142:143], v[178:179]
	s_nop 0
	v_pk_fma_f32 v[162:163], v[146:147], v[174:175], v[162:163]
	v_pk_mul_f32 v[146:147], v[146:147], v[178:179]
	s_nop 0
	v_pk_fma_f32 v[142:143], v[142:143], v[174:175], v[146:147] neg_lo:[0,0,1] neg_hi:[0,0,1]
	v_cvt_pk_bf16_f32 v138, v162, v163
	v_cvt_pk_bf16_f32 v134, v142, v143
	ds_read_b64 v[142:143], v173 offset:48
	ds_read_b64 v[146:147], v173 offset:176
	s_waitcnt lgkmcnt(2)
	v_readlane_b32 s98, v182, 10
	v_readlane_b32 s99, v182, 11
	v_readlane_b32 vcc_lo, v182, 42
	v_readlane_b32 vcc_hi, v182, 43
	v_pk_mul_f32 v[144:145], v[158:159], v[144:145]
	v_pk_mul_f32 v[148:149], v[158:159], v[148:149]
	v_pk_mul_f32 v[144:145], v[144:145], s[98:99]
	v_pk_mul_f32 v[148:149], v[148:149], vcc
	v_pk_mul_f32 v[162:163], v[144:145], v[180:181]
	s_nop 0
	v_pk_fma_f32 v[162:163], v[148:149], v[176:177], v[162:163]
	v_pk_mul_f32 v[148:149], v[148:149], v[180:181]
	s_nop 0
	v_pk_fma_f32 v[144:145], v[144:145], v[176:177], v[148:149] neg_lo:[0,0,1] neg_hi:[0,0,1]
	v_cvt_pk_bf16_f32 v139, v162, v163
	v_cvt_pk_bf16_f32 v135, v144, v145
	ds_read_b64 v[144:145], v173 offset:56
	ds_read_b64 v[148:149], v173 offset:184
	s_waitcnt vmcnt(10)
	s_waitcnt lgkmcnt(2)
; DI uint4 pack8(const float* v) { uint4 r; r.x = pk2(v[0], v[1]); r.y = pk2(v[2], v[3]); r.z = pk2(v[4], v[5]); r.w = pk2(v[6], v[7]); return r; }
; DI void qk_epilogue(const float* st  , int m0, const float* __restrict__ gain, float scale, bf16_t* __restrict__ dst, int dstride, int dcol0,
;                     const float* __restrict__ COS, const float* __restrict__ SIN) {
;     ...
;   for (int j = 0; j < 32; j += 8) {
;     float o1[8], o2[8];
; #pragma unroll
;     for (int q = 0; q < 8; ++q) {
;       const float x1 = sp[j + q] * rr * gain[j + q], x2 = sp[j + q + 32] * rr * gain[j + q + 32];
;       const float cs = COS[tok * 32 + j + q], sn = SIN[tok * 32 + j + q];
;       o1[q] = (x1 * cs - x2 * sn) * scale;
;       o2[q] = (x2 * cs + x1 * sn) * scale;
;     }
;     *(uint4*)(dp + j) = pack8(o1);
;     *(uint4*)(dp + j + 32) = pack8(o2);
;   }
	v_readlane_b32 s98, v182, 12
	v_readlane_b32 s99, v182, 13
	v_readlane_b32 vcc_lo, v182, 44
	v_readlane_b32 vcc_hi, v182, 45
	v_pk_mul_f32 v[142:143], v[158:159], v[142:143]
	v_pk_mul_f32 v[146:147], v[158:159], v[146:147]
	v_pk_mul_f32 v[142:143], v[142:143], s[98:99]
	v_pk_mul_f32 v[146:147], v[146:147], vcc
	v_pk_mul_f32 v[162:163], v[142:143], v[190:191]
	s_nop 0
	v_pk_fma_f32 v[162:163], v[146:147], v[186:187], v[162:163]
	v_pk_mul_f32 v[146:147], v[146:147], v[190:191]
	s_nop 0
	v_pk_fma_f32 v[142:143], v[142:143], v[186:187], v[146:147] neg_lo:[0,0,1] neg_hi:[0,0,1]
	v_cvt_pk_bf16_f32 v140, v162, v163
	v_cvt_pk_bf16_f32 v136, v142, v143
	ds_read_b64 v[142:143], v173 offset:64
	ds_read_b64 v[146:147], v173 offset:192
	s_waitcnt lgkmcnt(2)
	v_readlane_b32 s98, v182, 14
	v_readlane_b32 s99, v182, 15
	v_readlane_b32 vcc_lo, v182, 46
	v_readlane_b32 vcc_hi, v182, 47
	v_pk_mul_f32 v[144:145], v[158:159], v[144:145]
	v_pk_mul_f32 v[148:149], v[158:159], v[148:149]
	v_pk_mul_f32 v[144:145], v[144:145], s[98:99]
	v_pk_mul_f32 v[148:149], v[148:149], vcc
	v_pk_mul_f32 v[162:163], v[144:145], v[192:193]
	s_nop 0
	v_pk_fma_f32 v[162:163], v[148:149], v[188:189], v[162:163]
	v_pk_mul_f32 v[148:149], v[148:149], v[192:193]
	s_nop 0
	v_pk_fma_f32 v[144:145], v[144:145], v[188:189], v[148:149] neg_lo:[0,0,1] neg_hi:[0,0,1]
	v_cvt_pk_bf16_f32 v141, v162, v163
	v_cvt_pk_bf16_f32 v137, v144, v145
	ds_read_b64 v[144:145], v173 offset:72
	ds_read_b64 v[148:149], v173 offset:200
	global_store_dwordx4 v[160:161], v[134:137], off offset:16
	global_store_dwordx4 v[160:161], v[138:141], off offset:80
	s_waitcnt vmcnt(10)
	s_waitcnt lgkmcnt(2)
	v_readlane_b32 s98, v182, 16
	v_readlane_b32 s99, v182, 17
	v_readlane_b32 vcc_lo, v182, 48
	v_readlane_b32 vcc_hi, v182, 49
	v_pk_mul_f32 v[142:143], v[158:159], v[142:143]
	v_pk_mul_f32 v[146:147], v[158:159], v[146:147]
	v_pk_mul_f32 v[142:143], v[142:143], s[98:99]
	v_pk_mul_f32 v[146:147], v[146:147], vcc
	v_pk_mul_f32 v[162:163], v[142:143], v[198:199]
	s_nop 0
	v_pk_fma_f32 v[162:163], v[146:147], v[194:195], v[162:163]
	v_pk_mul_f32 v[146:147], v[146:147], v[198:199]
	s_nop 0
	v_pk_fma_f32 v[142:143], v[142:143], v[194:195], v[146:147] neg_lo:[0,0,1] neg_hi:[0,0,1]
	v_cvt_pk_bf16_f32 v138, v162, v163
	v_cvt_pk_bf16_f32 v134, v142, v143
	ds_read_b64 v[142:143], v173 offset:80
	ds_read_b64 v[146:147], v173 offset:208
	s_waitcnt lgkmcnt(2)
	v_readlane_b32 s98, v182, 18
	v_readlane_b32 s99, v182, 19
	v_readlane_b32 vcc_lo, v182, 50
	v_readlane_b32 vcc_hi, v182, 51
	v_pk_mul_f32 v[144:145], v[158:159], v[144:145]
	v_pk_mul_f32 v[148:149], v[158:159], v[148:149]
	v_pk_mul_f32 v[144:145], v[144:145], s[98:99]
	v_pk_mul_f32 v[148:149], v[148:149], vcc
	v_pk_mul_f32 v[162:163], v[144:145], v[200:201]
	s_nop 0
	v_pk_fma_f32 v[162:163], v[148:149], v[196:197], v[162:163]
	v_pk_mul_f32 v[148:149], v[148:149], v[200:201]
	s_nop 0
	v_pk_fma_f32 v[144:145], v[144:145], v[196:197], v[148:149] neg_lo:[0,0,1] neg_hi:[0,0,1]
	v_cvt_pk_bf16_f32 v139, v162, v163
	v_cvt_pk_bf16_f32 v135, v144, v145
	ds_read_b64 v[144:145], v173 offset:88
	ds_read_b64 v[148:149], v173 offset:216
	s_waitcnt vmcnt(8)
	s_waitcnt lgkmcnt(2)
	v_readlane_b32 s98, v182, 20
	v_readlane_b32 s99, v182, 21
	v_readlane_b32 vcc_lo, v182, 52
	v_readlane_b32 vcc_hi, v182, 53
	v_pk_mul_f32 v[142:143], v[158:159], v[142:143]
	v_pk_mul_f32 v[146:147], v[158:159], v[146:147]
	v_pk_mul_f32 v[142:143], v[142:143], s[98:99]
	v_pk_mul_f32 v[146:147], v[146:147], vcc
	v_pk_mul_f32 v[162:163], v[142:143], v[210:211]
	s_nop 0
	v_pk_fma_f32 v[162:163], v[146:147], v[202:203], v[162:163]
	v_pk_mul_f32 v[146:147], v[146:147], v[210:211]
	s_nop 0
	v_pk_fma_f32 v[142:143], v[142:143], v[202:203], v[146:147] neg_lo:[0,0,1] neg_hi:[0,0,1]
	v_cvt_pk_bf16_f32 v140, v162, v163
	v_cvt_pk_bf16_f32 v136, v142, v143
	ds_read_b64 v[142:143], v173 offset:96
	ds_read_b64 v[146:147], v173 offset:224
	s_waitcnt lgkmcnt(2)
; DI uint4 pack8(const float* v) { uint4 r; r.x = pk2(v[0], v[1]); r.y = pk2(v[2], v[3]); r.z = pk2(v[4], v[5]); r.w = pk2(v[6], v[7]); return r; }
; DI void qk_epilogue(const float* st  , int m0, const float* __restrict__ gain, float scale, bf16_t* __restrict__ dst, int dstride, int dcol0,
;                     const float* __restrict__ COS, const float* __restrict__ SIN) {
;     ...
;   for (int j = 0; j < 32; j += 8) {
;     float o1[8], o2[8];
; #pragma unroll
;     for (int q = 0; q < 8; ++q) {
;       const float x1 = sp[j + q] * rr * gain[j + q], x2 = sp[j + q + 32] * rr * gain[j + q + 32];
;       const float cs = COS[tok * 32 + j + q], sn = SIN[tok * 32 + j + q];
;       o1[q] = (x1 * cs - x2 * sn) * scale;
;       o2[q] = (x2 * cs + x1 * sn) * scale;
;     }
;     *(uint4*)(dp + j) = pack8(o1);
;     *(uint4*)(dp + j + 32) = pack8(o2);
;   }
	v_readlane_b32 s98, v182, 22
	v_readlane_b32 s99, v182, 23
	v_readlane_b32 vcc_lo, v182, 54
	v_readlane_b32 vcc_hi, v182, 55
	v_pk_mul_f32 v[144:145], v[158:159], v[144:145]
	v_pk_mul_f32 v[148:149], v[158:159], v[148:149]
	v_pk_mul_f32 v[144:145], v[144:145], s[98:99]
	v_pk_mul_f32 v[148:149], v[148:149], vcc
	v_pk_mul_f32 v[162:163], v[144:145], v[212:213]
	s_nop 0
	v_pk_fma_f32 v[162:163], v[148:149], v[204:205], v[162:163]
	v_pk_mul_f32 v[148:149], v[148:149], v[212:213]
	s_nop 0
	v_pk_fma_f32 v[144:145], v[144:145], v[204:205], v[148:149] neg_lo:[0,0,1] neg_hi:[0,0,1]
	v_cvt_pk_bf16_f32 v141, v162, v163
	v_cvt_pk_bf16_f32 v137, v144, v145
	ds_read_b64 v[144:145], v173 offset:104
	ds_read_b64 v[148:149], v173 offset:232
	global_store_dwordx4 v[160:161], v[134:137], off offset:32
	global_store_dwordx4 v[160:161], v[138:141], off offset:96
	s_waitcnt vmcnt(8)
	s_waitcnt lgkmcnt(2)
	v_readlane_b32 s98, v182, 24
	v_readlane_b32 s99, v182, 25
	v_readlane_b32 vcc_lo, v182, 56
	v_readlane_b32 vcc_hi, v182, 57
	v_pk_mul_f32 v[142:143], v[158:159], v[142:143]
	v_pk_mul_f32 v[146:147], v[158:159], v[146:147]
	v_pk_mul_f32 v[142:143], v[142:143], s[98:99]
	v_pk_mul_f32 v[146:147], v[146:147], vcc
	v_pk_mul_f32 v[162:163], v[142:143], v[248:249]
	s_nop 0
	v_pk_fma_f32 v[162:163], v[146:147], v[236:237], v[162:163]
	v_pk_mul_f32 v[146:147], v[146:147], v[248:249]
	s_nop 0
	v_pk_fma_f32 v[142:143], v[142:143], v[236:237], v[146:147] neg_lo:[0,0,1] neg_hi:[0,0,1]
	v_cvt_pk_bf16_f32 v138, v162, v163
	v_cvt_pk_bf16_f32 v134, v142, v143
	ds_read_b64 v[142:143], v173 offset:112
	ds_read_b64 v[146:147], v173 offset:240
	s_waitcnt lgkmcnt(2)
	v_readlane_b32 s98, v182, 26
	v_readlane_b32 s99, v182, 27
	v_readlane_b32 vcc_lo, v182, 58
	v_readlane_b32 vcc_hi, v182, 59
	v_pk_mul_f32 v[144:145], v[158:159], v[144:145]
	v_pk_mul_f32 v[148:149], v[158:159], v[148:149]
	v_pk_mul_f32 v[144:145], v[144:145], s[98:99]
	v_pk_mul_f32 v[148:149], v[148:149], vcc
	v_pk_mul_f32 v[162:163], v[144:145], v[250:251]
	s_nop 0
	v_pk_fma_f32 v[162:163], v[148:149], v[238:239], v[162:163]
	v_pk_mul_f32 v[148:149], v[148:149], v[250:251]
	s_nop 0
	v_pk_fma_f32 v[144:145], v[144:145], v[238:239], v[148:149] neg_lo:[0,0,1] neg_hi:[0,0,1]
	v_cvt_pk_bf16_f32 v139, v162, v163
	v_cvt_pk_bf16_f32 v135, v144, v145
	ds_read_b64 v[144:145], v173 offset:120
	ds_read_b64 v[148:149], v173 offset:248
	s_waitcnt vmcnt(6)
	s_waitcnt lgkmcnt(2)
	v_readlane_b32 s98, v182, 28
	v_readlane_b32 s99, v182, 29
	v_readlane_b32 vcc_lo, v182, 60
	v_readlane_b32 vcc_hi, v182, 61
	v_pk_mul_f32 v[142:143], v[158:159], v[142:143]
	v_pk_mul_f32 v[146:147], v[158:159], v[146:147]
	v_pk_mul_f32 v[142:143], v[142:143], s[98:99]
	v_pk_mul_f32 v[146:147], v[146:147], vcc
	v_pk_mul_f32 v[162:163], v[142:143], v[130:131]
	s_nop 0
	v_pk_fma_f32 v[162:163], v[146:147], v[252:253], v[162:163]
	v_pk_mul_f32 v[146:147], v[146:147], v[130:131]
	s_nop 0
	v_pk_fma_f32 v[142:143], v[142:143], v[252:253], v[146:147] neg_lo:[0,0,1] neg_hi:[0,0,1]
	v_cvt_pk_bf16_f32 v140, v162, v163
	v_cvt_pk_bf16_f32 v136, v142, v143
	s_waitcnt lgkmcnt(0)
	v_readlane_b32 s98, v182, 30
	v_readlane_b32 s99, v182, 31
	v_readlane_b32 vcc_lo, v182, 62
	v_readlane_b32 vcc_hi, v182, 63
	v_pk_mul_f32 v[144:145], v[158:159], v[144:145]
	v_pk_mul_f32 v[148:149], v[158:159], v[148:149]
	v_pk_mul_f32 v[144:145], v[144:145], s[98:99]
	v_pk_mul_f32 v[148:149], v[148:149], vcc
	v_pk_mul_f32 v[162:163], v[144:145], v[132:133]
	s_nop 0
	v_pk_fma_f32 v[162:163], v[148:149], v[254:255], v[162:163]
	v_pk_mul_f32 v[148:149], v[148:149], v[132:133]
	s_nop 0
	v_pk_fma_f32 v[144:145], v[144:145], v[254:255], v[148:149] neg_lo:[0,0,1] neg_hi:[0,0,1]
	v_cvt_pk_bf16_f32 v141, v162, v163
	v_cvt_pk_bf16_f32 v137, v144, v145
	global_store_dwordx4 v[160:161], v[134:137], off offset:48
	global_store_dwordx4 v[160:161], v[138:141], off offset:112
	s_mov_b64 s[48:49], 0
	s_mov_b32 s50, 0x9b78000

; DI int otid() { int t = threadIdx.x; asm volatile("" : "+v"(t)); return t; }
; DI void qk_epilogue(const float* st  , int m0, const float* __restrict__ gain, float scale, bf16_t* __restrict__ dst, int dstride, int dcol0,
;                     const float* __restrict__ COS, const float* __restrict__ SIN) {
;   const int tid = otid(), row = tid & 127, hd = tid >> 7;
;   const float* sp = st + row * 132 + hd * 64;
;   float ss = 0.f;
; #pragma unroll 4
;   for (int j = 0; j < 64; j += 4) { const float4 v = *(const float4*)(sp + j); ss += v.x * v.x + v.y * v.y + v.z * v.z + v.w * v.w; }
;   const float rr = rsqrtf(ss * (1.f / 64.f) + 1e-6f);
;   const size_t tok = (size_t)(m0 + row);
;   bf16_t* dp = dst + tok * dstride + dcol0 + hd * 64;
; #pragma unroll 2
;   for (int j = 0; j < 32; j += 8) {
;     float o1[8], o2[8];
; #pragma unroll
;     for (int q = 0; q < 8; ++q) {
;       const float x1 = sp[j + q] * rr * gain[j + q], x2 = sp[j + q + 32] * rr * gain[j + q + 32];
;       const float cs = COS[tok * 32 + j + q], sn = SIN[tok * 32 + j + q];
.LBB0_383:
	s_andn2_b64 vcc, exec, s[28:29]
	s_cbranch_vccnz .LBB0_388
	v_lshlrev_b32_e32 v136, 2, v231
	s_mov_b32 vcc_lo, s55
	s_mov_b32 vcc_hi, s56
	global_load_dword v165, v136, vcc
	s_add_i32 s98, s64, s65
	v_and_b32_e32 v134, 0x7f, v216
	v_add_lshl_u32 v134, v134, s98, 7
	v_add_u32_e32 v135, 0x2178000, v134
	v_add_u32_e32 v134, 0x1f78000, v134
	global_load_dwordx4 v[150:153], v134, s[82:83]
	global_load_dwordx4 v[160:163], v135, s[82:83]
	global_load_dwordx4 v[166:169], v134, s[82:83] offset:16
	global_load_dwordx4 v[170:173], v135, s[82:83] offset:16
	global_load_dwordx4 v[174:177], v134, s[82:83] offset:32
	global_load_dwordx4 v[178:181], v135, s[82:83] offset:32
	global_load_dwordx4 v[186:189], v134, s[82:83] offset:48
	global_load_dwordx4 v[190:193], v135, s[82:83] offset:48
	global_load_dwordx4 v[194:197], v134, s[82:83] offset:64
	global_load_dwordx4 v[198:201], v135, s[82:83] offset:64
	global_load_dwordx4 v[202:205], v134, s[82:83] offset:80
	global_load_dwordx4 v[210:213], v135, s[82:83] offset:80
	global_load_dwordx4 v[236:239], v134, s[82:83] offset:96
	global_load_dwordx4 v[248:251], v135, s[82:83] offset:96
	global_load_dwordx4 v[252:255], v134, s[82:83] offset:112
	v_mov_b32_e32 v130, v216
	s_mov_b32 s9, -4
	v_and_b32_e32 v0, 0x7f, v130
	v_ashrrev_i32_e32 v130, 1, v130
	v_and_b32_e32 v130, 0xffffffc0, v130
	v_lshlrev_b32_e32 v131, 2, v130
	v_mad_u32_u24 v164, v0, s8, v131
	v_mov_b32_e32 v131, 0
	v_mov_b32_e32 v132, v164

; DI uint4 pack8(const float* v) { uint4 r; r.x = pk2(v[0], v[1]); r.y = pk2(v[2], v[3]); r.z = pk2(v[4], v[5]); r.w = pk2(v[6], v[7]); return r; }
; DI void qk_epilogue(const float* st  , int m0, const float* __restrict__ gain, float scale, bf16_t* __restrict__ dst, int dstride, int dcol0,
;                     const float* __restrict__ COS, const float* __restrict__ SIN) {
;     ...
;   for (int j = 0; j < 32; j += 8) {
;     float o1[8], o2[8];
; #pragma unroll
;     for (int q = 0; q < 8; ++q) {
;       const float x1 = sp[j + q] * rr * gain[j + q], x2 = sp[j + q + 32] * rr * gain[j + q + 32];
;       const float cs = COS[tok * 32 + j + q], sn = SIN[tok * 32 + j + q];
;       o1[q] = (x1 * cs - x2 * sn) * scale;
;       o2[q] = (x2 * cs + x1 * sn) * scale;
;     }
;     *(uint4*)(dp + j) = pack8(o1);
;     *(uint4*)(dp + j + 32) = pack8(o2);
;   }
.LBB0_387:
	s_add_i32 s98, s64, s65
	v_and_b32_e32 v134, 0x7f, v216
	v_add_lshl_u32 v134, v134, s98, 7
	v_add_u32_e32 v135, 0x2178000, v134
	v_add_u32_e32 v134, 0x1f78000, v134
	global_load_dwordx4 v[130:133], v135, s[82:83] offset:112
	ds_read_b64 v[142:143], v0
	ds_read_b64 v[146:147], v0 offset:128
	ds_read_b64 v[144:145], v0 offset:8
	ds_read_b64 v[148:149], v0 offset:136
	s_waitcnt vmcnt(14)
	s_waitcnt lgkmcnt(2)
	v_readlane_b32 s98, v165, 0
	v_readlane_b32 s99, v165, 1
	v_readlane_b32 vcc_lo, v165, 32
	v_readlane_b32 vcc_hi, v165, 33
	v_pk_mul_f32 v[142:143], v[154:155], v[142:143]
	v_pk_mul_f32 v[146:147], v[154:155], v[146:147]
	v_pk_mul_f32 v[142:143], v[142:143], s[98:99]
	v_pk_mul_f32 v[146:147], v[146:147], vcc
	v_pk_mul_f32 v[214:215], v[142:143], v[160:161]
	s_nop 0
	v_pk_fma_f32 v[214:215], v[146:147], v[150:151], v[214:215]
	v_pk_mul_f32 v[146:147], v[146:147], v[160:161]
	s_nop 0
	v_pk_fma_f32 v[142:143], v[142:143], v[150:151], v[146:147] neg_lo:[0,0,1] neg_hi:[0,0,1]
	v_cvt_pk_bf16_f32 v138, v214, v215
	v_cvt_pk_bf16_f32 v134, v142, v143
	ds_read_b64 v[142:143], v0 offset:16
	ds_read_b64 v[146:147], v0 offset:144
	s_waitcnt lgkmcnt(2)
	v_readlane_b32 s98, v165, 2
	v_readlane_b32 s99, v165, 3
	v_readlane_b32 vcc_lo, v165, 34
	v_readlane_b32 vcc_hi, v165, 35
	v_pk_mul_f32 v[144:145], v[154:155], v[144:145]
	v_pk_mul_f32 v[148:149], v[154:155], v[148:149]
	v_pk_mul_f32 v[144:145], v[144:145], s[98:99]
	v_pk_mul_f32 v[148:149], v[148:149], vcc
	v_pk_mul_f32 v[214:215], v[144:145], v[162:163]
	s_nop 0
	v_pk_fma_f32 v[214:215], v[148:149], v[152:153], v[214:215]
	v_pk_mul_f32 v[148:149], v[148:149], v[162:163]
	s_nop 0
	v_pk_fma_f32 v[144:145], v[144:145], v[152:153], v[148:149] neg_lo:[0,0,1] neg_hi:[0,0,1]
	v_cvt_pk_bf16_f32 v139, v214, v215
	v_cvt_pk_bf16_f32 v135, v144, v145
	ds_read_b64 v[144:145], v0 offset:24
	ds_read_b64 v[148:149], v0 offset:152
	s_waitcnt vmcnt(12)
	s_waitcnt lgkmcnt(2)
	v_readlane_b32 s98, v165, 4
	v_readlane_b32 s99, v165, 5
	v_readlane_b32 vcc_lo, v165, 36
	v_readlane_b32 vcc_hi, v165, 37
	v_pk_mul_f32 v[142:143], v[154:155], v[142:143]
	v_pk_mul_f32 v[146:147], v[154:155], v[146:147]
	v_pk_mul_f32 v[142:143], v[142:143], s[98:99]
	v_pk_mul_f32 v[146:147], v[146:147], vcc
	v_pk_mul_f32 v[214:215], v[142:143], v[170:171]
	s_nop 0
	v_pk_fma_f32 v[214:215], v[146:147], v[166:167], v[214:215]
	v_pk_mul_f32 v[146:147], v[146:147], v[170:171]
	s_nop 0
	v_pk_fma_f32 v[142:143], v[142:143], v[166:167], v[146:147] neg_lo:[0,0,1] neg_hi:[0,0,1]
	v_cvt_pk_bf16_f32 v140, v214, v215
	v_cvt_pk_bf16_f32 v136, v142, v143
	ds_read_b64 v[142:143], v0 offset:32
	ds_read_b64 v[146:147], v0 offset:160
	s_waitcnt lgkmcnt(2)
	v_readlane_b32 s98, v165, 6
	v_readlane_b32 s99, v165, 7
	v_readlane_b32 vcc_lo, v165, 38
	v_readlane_b32 vcc_hi, v165, 39
	v_pk_mul_f32 v[144:145], v[154:155], v[144:145]
	v_pk_mul_f32 v[148:149], v[154:155], v[148:149]
	v_pk_mul_f32 v[144:145], v[144:145], s[98:99]
	v_pk_mul_f32 v[148:149], v[148:149], vcc
	v_pk_mul_f32 v[214:215], v[144:145], v[172:173]
	s_nop 0
	v_pk_fma_f32 v[214:215], v[148:149], v[168:169], v[214:215]
	v_pk_mul_f32 v[148:149], v[148:149], v[172:173]
	s_nop 0
	v_pk_fma_f32 v[144:145], v[144:145], v[168:169], v[148:149] neg_lo:[0,0,1] neg_hi:[0,0,1]
	v_cvt_pk_bf16_f32 v141, v214, v215
	v_cvt_pk_bf16_f32 v137, v144, v145
	ds_read_b64 v[144:145], v0 offset:40
	ds_read_b64 v[148:149], v0 offset:168
	global_store_dwordx4 v[158:159], v[134:137], off offset:-64
	global_store_dwordx4 v[158:159], v[138:141], off
	s_waitcnt vmcnt(12)
	s_waitcnt lgkmcnt(2)
	v_readlane_b32 s98, v165, 8
	v_readlane_b32 s99, v165, 9
	v_readlane_b32 vcc_lo, v165, 40
	v_readlane_b32 vcc_hi, v165, 41
	v_pk_mul_f32 v[142:143], v[154:155], v[142:143]
	v_pk_mul_f32 v[146:147], v[154:155], v[146:147]
	v_pk_mul_f32 v[142:143], v[142:143], s[98:99]
	v_pk_mul_f32 v[146:147], v[146:147], vcc
	v_pk_mul_f32 v[214:215], v[142:143], v[178:179]
	s_nop 0
	v_pk_fma_f32 v[214:215], v[146:147], v[174:175], v[214:215]
	v_pk_mul_f32 v[146:147], v[146:147], v[178:179]
	s_nop 0
	v_pk_fma_f32 v[142:143], v[142:143], v[174:175], v[146:147] neg_lo:[0,0,1] neg_hi:[0,0,1]
	v_cvt_pk_bf16_f32 v138, v214, v215
	v_cvt_pk_bf16_f32 v134, v142, v143
	ds_read_b64 v[142:143], v0 offset:48
	ds_read_b64 v[146:147], v0 offset:176
	s_waitcnt lgkmcnt(2)
	v_readlane_b32 s98, v165, 10
	v_readlane_b32 s99, v165, 11
	v_readlane_b32 vcc_lo, v165, 42
	v_readlane_b32 vcc_hi, v165, 43
	v_pk_mul_f32 v[144:145], v[154:155], v[144:145]
	v_pk_mul_f32 v[148:149], v[154:155], v[148:149]
	v_pk_mul_f32 v[144:145], v[144:145], s[98:99]
	v_pk_mul_f32 v[148:149], v[148:149], vcc
	v_pk_mul_f32 v[214:215], v[144:145], v[180:181]
	s_nop 0
	v_pk_fma_f32 v[214:215], v[148:149], v[176:177], v[214:215]
	v_pk_mul_f32 v[148:149], v[148:149], v[180:181]
	s_nop 0
	v_pk_fma_f32 v[144:145], v[144:145], v[176:177], v[148:149] neg_lo:[0,0,1] neg_hi:[0,0,1]
	v_cvt_pk_bf16_f32 v139, v214, v215
	v_cvt_pk_bf16_f32 v135, v144, v145
	ds_read_b64 v[144:145], v0 offset:56
	ds_read_b64 v[148:149], v0 offset:184
	s_waitcnt vmcnt(10)
	s_waitcnt lgkmcnt(2)
	v_readlane_b32 s98, v165, 12
	v_readlane_b32 s99, v165, 13
	v_readlane_b32 vcc_lo, v165, 44
	v_readlane_b32 vcc_hi, v165, 45
	v_pk_mul_f32 v[142:143], v[154:155], v[142:143]
	v_pk_mul_f32 v[146:147], v[154:155], v[146:147]
	v_pk_mul_f32 v[142:143], v[142:143], s[98:99]
	v_pk_mul_f32 v[146:147], v[146:147], vcc
	v_pk_mul_f32 v[214:215], v[142:143], v[190:191]
	s_nop 0
	v_pk_fma_f32 v[214:215], v[146:147], v[186:187], v[214:215]
	v_pk_mul_f32 v[146:147], v[146:147], v[190:191]
	s_nop 0
	v_pk_fma_f32 v[142:143], v[142:143], v[186:187], v[146:147] neg_lo:[0,0,1] neg_hi:[0,0,1]
	v_cvt_pk_bf16_f32 v140, v214, v215
	v_cvt_pk_bf16_f32 v136, v142, v143
	ds_read_b64 v[142:143], v0 offset:64
	ds_read_b64 v[146:147], v0 offset:192
	s_waitcnt lgkmcnt(2)
; DI uint4 pack8(const float* v) { uint4 r; r.x = pk2(v[0], v[1]); r.y = pk2(v[2], v[3]); r.z = pk2(v[4], v[5]); r.w = pk2(v[6], v[7]); return r; }
; DI void qk_epilogue(const float* st  , int m0, const float* __restrict__ gain, float scale, bf16_t* __restrict__ dst, int dstride, int dcol0,
;                     const float* __restrict__ COS, const float* __restrict__ SIN) {
;     ...
;   for (int j = 0; j < 32; j += 8) {
;     float o1[8], o2[8];
; #pragma unroll
;     for (int q = 0; q < 8; ++q) {
;       const float x1 = sp[j + q] * rr * gain[j + q], x2 = sp[j + q + 32] * rr * gain[j + q + 32];
;       const float cs = COS[tok * 32 + j + q], sn = SIN[tok * 32 + j + q];
;       o1[q] = (x1 * cs - x2 * sn) * scale;
;       o2[q] = (x2 * cs + x1 * sn) * scale;
;     }
;     *(uint4*)(dp + j) = pack8(o1);
;     *(uint4*)(dp + j + 32) = pack8(o2);
;   }
	v_readlane_b32 s98, v165, 14
	v_readlane_b32 s99, v165, 15
	v_readlane_b32 vcc_lo, v165, 46
	v_readlane_b32 vcc_hi, v165, 47
	v_pk_mul_f32 v[144:145], v[154:155], v[144:145]
	v_pk_mul_f32 v[148:149], v[154:155], v[148:149]
	v_pk_mul_f32 v[144:145], v[144:145], s[98:99]
	v_pk_mul_f32 v[148:149], v[148:149], vcc
	v_pk_mul_f32 v[214:215], v[144:145], v[192:193]
	s_nop 0
	v_pk_fma_f32 v[214:215], v[148:149], v[188:189], v[214:215]
	v_pk_mul_f32 v[148:149], v[148:149], v[192:193]
	s_nop 0
	v_pk_fma_f32 v[144:145], v[144:145], v[188:189], v[148:149] neg_lo:[0,0,1] neg_hi:[0,0,1]
	v_cvt_pk_bf16_f32 v141, v214, v215
	v_cvt_pk_bf16_f32 v137, v144, v145
	ds_read_b64 v[144:145], v0 offset:72
	ds_read_b64 v[148:149], v0 offset:200
	global_store_dwordx4 v[158:159], v[134:137], off offset:-48
	global_store_dwordx4 v[158:159], v[138:141], off offset:16
	s_waitcnt vmcnt(10)
	s_waitcnt lgkmcnt(2)
	v_readlane_b32 s98, v165, 16
	v_readlane_b32 s99, v165, 17
	v_readlane_b32 vcc_lo, v165, 48
	v_readlane_b32 vcc_hi, v165, 49
	v_pk_mul_f32 v[142:143], v[154:155], v[142:143]
	v_pk_mul_f32 v[146:147], v[154:155], v[146:147]
	v_pk_mul_f32 v[142:143], v[142:143], s[98:99]
	v_pk_mul_f32 v[146:147], v[146:147], vcc
	v_pk_mul_f32 v[214:215], v[142:143], v[198:199]
	s_nop 0
	v_pk_fma_f32 v[214:215], v[146:147], v[194:195], v[214:215]
	v_pk_mul_f32 v[146:147], v[146:147], v[198:199]
	s_nop 0
	v_pk_fma_f32 v[142:143], v[142:143], v[194:195], v[146:147] neg_lo:[0,0,1] neg_hi:[0,0,1]
	v_cvt_pk_bf16_f32 v138, v214, v215
	v_cvt_pk_bf16_f32 v134, v142, v143
	ds_read_b64 v[142:143], v0 offset:80
	ds_read_b64 v[146:147], v0 offset:208
	s_waitcnt lgkmcnt(2)
	v_readlane_b32 s98, v165, 18
	v_readlane_b32 s99, v165, 19
	v_readlane_b32 vcc_lo, v165, 50
	v_readlane_b32 vcc_hi, v165, 51
	v_pk_mul_f32 v[144:145], v[154:155], v[144:145]
	v_pk_mul_f32 v[148:149], v[154:155], v[148:149]
	v_pk_mul_f32 v[144:145], v[144:145], s[98:99]
	v_pk_mul_f32 v[148:149], v[148:149], vcc
	v_pk_mul_f32 v[214:215], v[144:145], v[200:201]
	s_nop 0
	v_pk_fma_f32 v[214:215], v[148:149], v[196:197], v[214:215]
	v_pk_mul_f32 v[148:149], v[148:149], v[200:201]
	s_nop 0
	v_pk_fma_f32 v[144:145], v[144:145], v[196:197], v[148:149] neg_lo:[0,0,1] neg_hi:[0,0,1]
	v_cvt_pk_bf16_f32 v139, v214, v215
	v_cvt_pk_bf16_f32 v135, v144, v145
	ds_read_b64 v[144:145], v0 offset:88
	ds_read_b64 v[148:149], v0 offset:216
	s_waitcnt vmcnt(8)
	s_waitcnt lgkmcnt(2)
	v_readlane_b32 s98, v165, 20
	v_readlane_b32 s99, v165, 21
	v_readlane_b32 vcc_lo, v165, 52
	v_readlane_b32 vcc_hi, v165, 53
	v_pk_mul_f32 v[142:143], v[154:155], v[142:143]
	v_pk_mul_f32 v[146:147], v[154:155], v[146:147]
	v_pk_mul_f32 v[142:143], v[142:143], s[98:99]
	v_pk_mul_f32 v[146:147], v[146:147], vcc
	v_pk_mul_f32 v[214:215], v[142:143], v[210:211]
	s_nop 0
	v_pk_fma_f32 v[214:215], v[146:147], v[202:203], v[214:215]
	v_pk_mul_f32 v[146:147], v[146:147], v[210:211]
	s_nop 0
	v_pk_fma_f32 v[142:143], v[142:143], v[202:203], v[146:147] neg_lo:[0,0,1] neg_hi:[0,0,1]
	v_cvt_pk_bf16_f32 v140, v214, v215
	v_cvt_pk_bf16_f32 v136, v142, v143
	ds_read_b64 v[142:143], v0 offset:96
	ds_read_b64 v[146:147], v0 offset:224
	s_waitcnt lgkmcnt(2)
	v_readlane_b32 s98, v165, 22
	v_readlane_b32 s99, v165, 23
	v_readlane_b32 vcc_lo, v165, 54
	v_readlane_b32 vcc_hi, v165, 55
	v_pk_mul_f32 v[144:145], v[154:155], v[144:145]
	v_pk_mul_f32 v[148:149], v[154:155], v[148:149]
	v_pk_mul_f32 v[144:145], v[144:145], s[98:99]
	v_pk_mul_f32 v[148:149], v[148:149], vcc
	v_pk_mul_f32 v[214:215], v[144:145], v[212:213]
	s_nop 0
	v_pk_fma_f32 v[214:215], v[148:149], v[204:205], v[214:215]
	v_pk_mul_f32 v[148:149], v[148:149], v[212:213]
	s_nop 0
	v_pk_fma_f32 v[144:145], v[144:145], v[204:205], v[148:149] neg_lo:[0,0,1] neg_hi:[0,0,1]
	v_cvt_pk_bf16_f32 v141, v214, v215
	v_cvt_pk_bf16_f32 v137, v144, v145
	ds_read_b64 v[144:145], v0 offset:104
	ds_read_b64 v[148:149], v0 offset:232
	global_store_dwordx4 v[158:159], v[134:137], off offset:-32
	global_store_dwordx4 v[158:159], v[138:141], off offset:32
	s_waitcnt vmcnt(8)
	s_waitcnt lgkmcnt(2)
	v_readlane_b32 s98, v165, 24
	v_readlane_b32 s99, v165, 25
	v_readlane_b32 vcc_lo, v165, 56
	v_readlane_b32 vcc_hi, v165, 57
	v_pk_mul_f32 v[142:143], v[154:155], v[142:143]
	v_pk_mul_f32 v[146:147], v[154:155], v[146:147]
	v_pk_mul_f32 v[142:143], v[142:143], s[98:99]
	v_pk_mul_f32 v[146:147], v[146:147], vcc
	v_pk_mul_f32 v[214:215], v[142:143], v[248:249]
	s_nop 0
	v_pk_fma_f32 v[214:215], v[146:147], v[236:237], v[214:215]
	v_pk_mul_f32 v[146:147], v[146:147], v[248:249]
	s_nop 0
	v_pk_fma_f32 v[142:143], v[142:143], v[236:237], v[146:147] neg_lo:[0,0,1] neg_hi:[0,0,1]
	v_cvt_pk_bf16_f32 v138, v214, v215
	v_cvt_pk_bf16_f32 v134, v142, v143
	ds_read_b64 v[142:143], v0 offset:112
	ds_read_b64 v[146:147], v0 offset:240
	s_waitcnt lgkmcnt(2)
	v_readlane_b32 s98, v165, 26
	v_readlane_b32 s99, v165, 27
	v_readlane_b32 vcc_lo, v165, 58
	v_readlane_b32 vcc_hi, v165, 59
	v_pk_mul_f32 v[144:145], v[154:155], v[144:145]
	v_pk_mul_f32 v[148:149], v[154:155], v[148:149]
	v_pk_mul_f32 v[144:145], v[144:145], s[98:99]
	v_pk_mul_f32 v[148:149], v[148:149], vcc
	v_pk_mul_f32 v[214:215], v[144:145], v[250:251]
	s_nop 0
	v_pk_fma_f32 v[214:215], v[148:149], v[238:239], v[214:215]
	v_pk_mul_f32 v[148:149], v[148:149], v[250:251]
	s_nop 0
	v_pk_fma_f32 v[144:145], v[144:145], v[238:239], v[148:149] neg_lo:[0,0,1] neg_hi:[0,0,1]
	v_cvt_pk_bf16_f32 v139, v214, v215
	v_cvt_pk_bf16_f32 v135, v144, v145
	ds_read_b64 v[144:145], v0 offset:120
	ds_read_b64 v[148:149], v0 offset:248
	s_waitcnt vmcnt(6)
	s_waitcnt lgkmcnt(2)
	v_readlane_b32 s98, v165, 28
	v_readlane_b32 s99, v165, 29
	v_readlane_b32 vcc_lo, v165, 60
	v_readlane_b32 vcc_hi, v165, 61
	v_pk_mul_f32 v[142:143], v[154:155], v[142:143]
	v_pk_mul_f32 v[146:147], v[154:155], v[146:147]
	v_pk_mul_f32 v[142:143], v[142:143], s[98:99]
	v_pk_mul_f32 v[146:147], v[146:147], vcc
	v_pk_mul_f32 v[214:215], v[142:143], v[130:131]
	s_nop 0
	v_pk_fma_f32 v[214:215], v[146:147], v[252:253], v[214:215]
	v_pk_mul_f32 v[146:147], v[146:147], v[130:131]
	s_nop 0
	v_pk_fma_f32 v[142:143], v[142:143], v[252:253], v[146:147] neg_lo:[0,0,1] neg_hi:[0,0,1]
	v_cvt_pk_bf16_f32 v140, v214, v215
	v_cvt_pk_bf16_f32 v136, v142, v143
	s_waitcnt lgkmcnt(0)
	v_readlane_b32 s98, v165, 30
	v_readlane_b32 s99, v165, 31
	v_readlane_b32 vcc_lo, v165, 62
	v_readlane_b32 vcc_hi, v165, 63
	v_pk_mul_f32 v[144:145], v[154:155], v[144:145]
	v_pk_mul_f32 v[148:149], v[154:155], v[148:149]
	v_pk_mul_f32 v[144:145], v[144:145], s[98:99]
	v_pk_mul_f32 v[148:149], v[148:149], vcc
	v_pk_mul_f32 v[214:215], v[144:145], v[132:133]
	s_nop 0
	v_pk_fma_f32 v[214:215], v[148:149], v[254:255], v[214:215]
	v_pk_mul_f32 v[148:149], v[148:149], v[132:133]
	s_nop 0
	v_pk_fma_f32 v[144:145], v[144:145], v[254:255], v[148:149] neg_lo:[0,0,1] neg_hi:[0,0,1]
	v_cvt_pk_bf16_f32 v141, v214, v215
	v_cvt_pk_bf16_f32 v137, v144, v145
	global_store_dwordx4 v[158:159], v[134:137], off offset:-16
	global_store_dwordx4 v[158:159], v[138:141], off offset:48

; DI int otid() { int t = threadIdx.x; asm volatile("" : "+v"(t)); return t; }
; DI void qk_epilogue(const float* st  , int m0, const float* __restrict__ gain, float scale, bf16_t* __restrict__ dst, int dstride, int dcol0,
;                     const float* __restrict__ COS, const float* __restrict__ SIN) {
;   const int tid = otid(), row = tid & 127, hd = tid >> 7;
;   const float* sp = st + row * 132 + hd * 64;
;   float ss = 0.f;
; #pragma unroll 4
;   for (int j = 0; j < 64; j += 4) { const float4 v = *(const float4*)(sp + j); ss += v.x * v.x + v.y * v.y + v.z * v.z + v.w * v.w; }
;   const float rr = rsqrtf(ss * (1.f / 64.f) + 1e-6f);
;   const size_t tok = (size_t)(m0 + row);
;   bf16_t* dp = dst + tok * dstride + dcol0 + hd * 64;
; #pragma unroll 2
;   for (int j = 0; j < 32; j += 8) {
;     float o1[8], o2[8];
; #pragma unroll
;     for (int q = 0; q < 8; ++q) {
;       const float x1 = sp[j + q] * rr * gain[j + q], x2 = sp[j + q + 32] * rr * gain[j + q + 32];
;       const float cs = COS[tok * 32 + j + q], sn = SIN[tok * 32 + j + q];
.LBB0_389:
	s_andn2_b64 vcc, exec, s[28:29]
	s_cbranch_vccnz .LBB0_394
	v_lshlrev_b32_e32 v136, 2, v231
	s_mov_b32 vcc_lo, s57
	s_mov_b32 vcc_hi, s58
	global_load_dword v165, v136, vcc
	s_add_i32 s98, s64, s65
	v_and_b32_e32 v134, 0x7f, v216
	v_add_lshl_u32 v134, v134, s98, 7
	v_add_u32_e32 v135, 0x2178000, v134
	v_add_u32_e32 v134, 0x1f78000, v134
	global_load_dwordx4 v[150:153], v134, s[82:83]
	global_load_dwordx4 v[160:163], v135, s[82:83]
	global_load_dwordx4 v[166:169], v134, s[82:83] offset:16
	global_load_dwordx4 v[170:173], v135, s[82:83] offset:16
	global_load_dwordx4 v[174:177], v134, s[82:83] offset:32
	global_load_dwordx4 v[178:181], v135, s[82:83] offset:32
	global_load_dwordx4 v[186:189], v134, s[82:83] offset:48
	global_load_dwordx4 v[190:193], v135, s[82:83] offset:48
	global_load_dwordx4 v[194:197], v134, s[82:83] offset:64
	global_load_dwordx4 v[198:201], v135, s[82:83] offset:64
	global_load_dwordx4 v[202:205], v134, s[82:83] offset:80
	global_load_dwordx4 v[210:213], v135, s[82:83] offset:80
	global_load_dwordx4 v[236:239], v134, s[82:83] offset:96
	global_load_dwordx4 v[248:251], v135, s[82:83] offset:96
	global_load_dwordx4 v[252:255], v134, s[82:83] offset:112
	v_mov_b32_e32 v130, v216
	s_mov_b32 s9, -4
	v_and_b32_e32 v0, 0x7f, v130
	v_ashrrev_i32_e32 v130, 1, v130
	v_and_b32_e32 v130, 0xffffffc0, v130
	v_lshlrev_b32_e32 v131, 2, v130
	v_mad_u32_u24 v164, v0, s8, v131
	v_mov_b32_e32 v131, 0
	v_mov_b32_e32 v132, v164

; DI uint4 pack8(const float* v) { uint4 r; r.x = pk2(v[0], v[1]); r.y = pk2(v[2], v[3]); r.z = pk2(v[4], v[5]); r.w = pk2(v[6], v[7]); return r; }
; DI void qk_epilogue(const float* st  , int m0, const float* __restrict__ gain, float scale, bf16_t* __restrict__ dst, int dstride, int dcol0,
;                     const float* __restrict__ COS, const float* __restrict__ SIN) {
;     ...
;   for (int j = 0; j < 32; j += 8) {
;     float o1[8], o2[8];
; #pragma unroll
;     for (int q = 0; q < 8; ++q) {
;       const float x1 = sp[j + q] * rr * gain[j + q], x2 = sp[j + q + 32] * rr * gain[j + q + 32];
;       const float cs = COS[tok * 32 + j + q], sn = SIN[tok * 32 + j + q];
;       o1[q] = (x1 * cs - x2 * sn) * scale;
;       o2[q] = (x2 * cs + x1 * sn) * scale;
;     }
;     *(uint4*)(dp + j) = pack8(o1);
;     *(uint4*)(dp + j + 32) = pack8(o2);
;   }
.LBB0_393:
	s_add_i32 s98, s64, s65
	v_and_b32_e32 v134, 0x7f, v216
	v_add_lshl_u32 v134, v134, s98, 7
	v_add_u32_e32 v135, 0x2178000, v134
	v_add_u32_e32 v134, 0x1f78000, v134
	global_load_dwordx4 v[130:133], v135, s[82:83] offset:112
	ds_read_b64 v[142:143], v0
	ds_read_b64 v[146:147], v0 offset:128
	ds_read_b64 v[144:145], v0 offset:8
	ds_read_b64 v[148:149], v0 offset:136
	s_waitcnt vmcnt(14)
	s_waitcnt lgkmcnt(2)
	v_readlane_b32 s98, v165, 0
	v_readlane_b32 s99, v165, 1
	v_readlane_b32 vcc_lo, v165, 32
	v_readlane_b32 vcc_hi, v165, 33
	v_pk_mul_f32 v[142:143], v[154:155], v[142:143]
	v_pk_mul_f32 v[146:147], v[154:155], v[146:147]
	v_pk_mul_f32 v[142:143], v[142:143], s[98:99]
	v_pk_mul_f32 v[146:147], v[146:147], vcc
	v_pk_mul_f32 v[214:215], v[142:143], v[160:161]
	s_nop 0
	v_pk_fma_f32 v[214:215], v[146:147], v[150:151], v[214:215]
	v_pk_mul_f32 v[146:147], v[146:147], v[160:161]
	s_nop 0
	v_pk_fma_f32 v[142:143], v[142:143], v[150:151], v[146:147] neg_lo:[0,0,1] neg_hi:[0,0,1]
	v_pk_mul_f32 v[214:215], v[214:215], s[16:17] op_sel_hi:[1,0]
	v_pk_mul_f32 v[142:143], v[142:143], s[16:17] op_sel_hi:[1,0]
	v_cvt_pk_bf16_f32 v138, v214, v215
	v_cvt_pk_bf16_f32 v134, v142, v143
	ds_read_b64 v[142:143], v0 offset:16
	ds_read_b64 v[146:147], v0 offset:144
	s_waitcnt lgkmcnt(2)
	v_readlane_b32 s98, v165, 2
	v_readlane_b32 s99, v165, 3
	v_readlane_b32 vcc_lo, v165, 34
	v_readlane_b32 vcc_hi, v165, 35
	v_pk_mul_f32 v[144:145], v[154:155], v[144:145]
	v_pk_mul_f32 v[148:149], v[154:155], v[148:149]
	v_pk_mul_f32 v[144:145], v[144:145], s[98:99]
	v_pk_mul_f32 v[148:149], v[148:149], vcc
	v_pk_mul_f32 v[214:215], v[144:145], v[162:163]
	s_nop 0
	v_pk_fma_f32 v[214:215], v[148:149], v[152:153], v[214:215]
	v_pk_mul_f32 v[148:149], v[148:149], v[162:163]
	s_nop 0
	v_pk_fma_f32 v[144:145], v[144:145], v[152:153], v[148:149] neg_lo:[0,0,1] neg_hi:[0,0,1]
	v_pk_mul_f32 v[214:215], v[214:215], s[16:17] op_sel_hi:[1,0]
	v_pk_mul_f32 v[144:145], v[144:145], s[16:17] op_sel_hi:[1,0]
	v_cvt_pk_bf16_f32 v139, v214, v215
	v_cvt_pk_bf16_f32 v135, v144, v145
	ds_read_b64 v[144:145], v0 offset:24
	ds_read_b64 v[148:149], v0 offset:152
	s_waitcnt vmcnt(12)
	s_waitcnt lgkmcnt(2)
	v_readlane_b32 s98, v165, 4
	v_readlane_b32 s99, v165, 5
	v_readlane_b32 vcc_lo, v165, 36
	v_readlane_b32 vcc_hi, v165, 37
	v_pk_mul_f32 v[142:143], v[154:155], v[142:143]
	v_pk_mul_f32 v[146:147], v[154:155], v[146:147]
	v_pk_mul_f32 v[142:143], v[142:143], s[98:99]
	v_pk_mul_f32 v[146:147], v[146:147], vcc
	v_pk_mul_f32 v[214:215], v[142:143], v[170:171]
	s_nop 0
	v_pk_fma_f32 v[214:215], v[146:147], v[166:167], v[214:215]
	v_pk_mul_f32 v[146:147], v[146:147], v[170:171]
	s_nop 0
	v_pk_fma_f32 v[142:143], v[142:143], v[166:167], v[146:147] neg_lo:[0,0,1] neg_hi:[0,0,1]
	v_pk_mul_f32 v[214:215], v[214:215], s[16:17] op_sel_hi:[1,0]
	v_pk_mul_f32 v[142:143], v[142:143], s[16:17] op_sel_hi:[1,0]
	v_cvt_pk_bf16_f32 v140, v214, v215
	v_cvt_pk_bf16_f32 v136, v142, v143
	ds_read_b64 v[142:143], v0 offset:32
	ds_read_b64 v[146:147], v0 offset:160
	s_waitcnt lgkmcnt(2)
	v_readlane_b32 s98, v165, 6
	v_readlane_b32 s99, v165, 7
	v_readlane_b32 vcc_lo, v165, 38
	v_readlane_b32 vcc_hi, v165, 39
	v_pk_mul_f32 v[144:145], v[154:155], v[144:145]
	v_pk_mul_f32 v[148:149], v[154:155], v[148:149]
	v_pk_mul_f32 v[144:145], v[144:145], s[98:99]
	v_pk_mul_f32 v[148:149], v[148:149], vcc
	v_pk_mul_f32 v[214:215], v[144:145], v[172:173]
	s_nop 0
	v_pk_fma_f32 v[214:215], v[148:149], v[168:169], v[214:215]
	v_pk_mul_f32 v[148:149], v[148:149], v[172:173]
	s_nop 0
	v_pk_fma_f32 v[144:145], v[144:145], v[168:169], v[148:149] neg_lo:[0,0,1] neg_hi:[0,0,1]
	v_pk_mul_f32 v[214:215], v[214:215], s[16:17] op_sel_hi:[1,0]
	v_pk_mul_f32 v[144:145], v[144:145], s[16:17] op_sel_hi:[1,0]
	v_cvt_pk_bf16_f32 v141, v214, v215
	v_cvt_pk_bf16_f32 v137, v144, v145
	ds_read_b64 v[144:145], v0 offset:40
	ds_read_b64 v[148:149], v0 offset:168
	global_store_dwordx4 v[158:159], v[134:137], off offset:-64
	global_store_dwordx4 v[158:159], v[138:141], off
	s_waitcnt vmcnt(12)
	s_waitcnt lgkmcnt(2)
	v_readlane_b32 s98, v165, 8
	v_readlane_b32 s99, v165, 9
	v_readlane_b32 vcc_lo, v165, 40
	v_readlane_b32 vcc_hi, v165, 41
	v_pk_mul_f32 v[142:143], v[154:155], v[142:143]
	v_pk_mul_f32 v[146:147], v[154:155], v[146:147]
	v_pk_mul_f32 v[142:143], v[142:143], s[98:99]
	v_pk_mul_f32 v[146:147], v[146:147], vcc
	v_pk_mul_f32 v[214:215], v[142:143], v[178:179]
	s_nop 0
	v_pk_fma_f32 v[214:215], v[146:147], v[174:175], v[214:215]
	v_pk_mul_f32 v[146:147], v[146:147], v[178:179]
	s_nop 0
	v_pk_fma_f32 v[142:143], v[142:143], v[174:175], v[146:147] neg_lo:[0,0,1] neg_hi:[0,0,1]
	v_pk_mul_f32 v[214:215], v[214:215], s[16:17] op_sel_hi:[1,0]
	v_pk_mul_f32 v[142:143], v[142:143], s[16:17] op_sel_hi:[1,0]
	v_cvt_pk_bf16_f32 v138, v214, v215
	v_cvt_pk_bf16_f32 v134, v142, v143
	ds_read_b64 v[142:143], v0 offset:48
	ds_read_b64 v[146:147], v0 offset:176
	s_waitcnt lgkmcnt(2)
	v_readlane_b32 s98, v165, 10
	v_readlane_b32 s99, v165, 11
	v_readlane_b32 vcc_lo, v165, 42
	v_readlane_b32 vcc_hi, v165, 43
	v_pk_mul_f32 v[144:145], v[154:155], v[144:145]
	v_pk_mul_f32 v[148:149], v[154:155], v[148:149]
	v_pk_mul_f32 v[144:145], v[144:145], s[98:99]
	v_pk_mul_f32 v[148:149], v[148:149], vcc
	v_pk_mul_f32 v[214:215], v[144:145], v[180:181]
	s_nop 0
	v_pk_fma_f32 v[214:215], v[148:149], v[176:177], v[214:215]
	v_pk_mul_f32 v[148:149], v[148:149], v[180:181]
	s_nop 0
	v_pk_fma_f32 v[144:145], v[144:145], v[176:177], v[148:149] neg_lo:[0,0,1] neg_hi:[0,0,1]
	v_pk_mul_f32 v[214:215], v[214:215], s[16:17] op_sel_hi:[1,0]
	v_pk_mul_f32 v[144:145], v[144:145], s[16:17] op_sel_hi:[1,0]
	v_cvt_pk_bf16_f32 v139, v214, v215
	v_cvt_pk_bf16_f32 v135, v144, v145
	ds_read_b64 v[144:145], v0 offset:56
	ds_read_b64 v[148:149], v0 offset:184
	s_waitcnt vmcnt(10)
; DI uint4 pack8(const float* v) { uint4 r; r.x = pk2(v[0], v[1]); r.y = pk2(v[2], v[3]); r.z = pk2(v[4], v[5]); r.w = pk2(v[6], v[7]); return r; }
; DI void qk_epilogue(const float* st  , int m0, const float* __restrict__ gain, float scale, bf16_t* __restrict__ dst, int dstride, int dcol0,
;                     const float* __restrict__ COS, const float* __restrict__ SIN) {
;     ...
;   for (int j = 0; j < 32; j += 8) {
;     float o1[8], o2[8];
; #pragma unroll
;     for (int q = 0; q < 8; ++q) {
;       const float x1 = sp[j + q] * rr * gain[j + q], x2 = sp[j + q + 32] * rr * gain[j + q + 32];
;       const float cs = COS[tok * 32 + j + q], sn = SIN[tok * 32 + j + q];
;       o1[q] = (x1 * cs - x2 * sn) * scale;
;       o2[q] = (x2 * cs + x1 * sn) * scale;
;     }
;     *(uint4*)(dp + j) = pack8(o1);
;     *(uint4*)(dp + j + 32) = pack8(o2);
;   }
	s_waitcnt lgkmcnt(2)
	v_readlane_b32 s98, v165, 12
	v_readlane_b32 s99, v165, 13
	v_readlane_b32 vcc_lo, v165, 44
	v_readlane_b32 vcc_hi, v165, 45
	v_pk_mul_f32 v[142:143], v[154:155], v[142:143]
	v_pk_mul_f32 v[146:147], v[154:155], v[146:147]
	v_pk_mul_f32 v[142:143], v[142:143], s[98:99]
	v_pk_mul_f32 v[146:147], v[146:147], vcc
	v_pk_mul_f32 v[214:215], v[142:143], v[190:191]
	s_nop 0
	v_pk_fma_f32 v[214:215], v[146:147], v[186:187], v[214:215]
	v_pk_mul_f32 v[146:147], v[146:147], v[190:191]
	s_nop 0
	v_pk_fma_f32 v[142:143], v[142:143], v[186:187], v[146:147] neg_lo:[0,0,1] neg_hi:[0,0,1]
	v_pk_mul_f32 v[214:215], v[214:215], s[16:17] op_sel_hi:[1,0]
	v_pk_mul_f32 v[142:143], v[142:143], s[16:17] op_sel_hi:[1,0]
	v_cvt_pk_bf16_f32 v140, v214, v215
	v_cvt_pk_bf16_f32 v136, v142, v143
	ds_read_b64 v[142:143], v0 offset:64
	ds_read_b64 v[146:147], v0 offset:192
	s_waitcnt lgkmcnt(2)
	v_readlane_b32 s98, v165, 14
	v_readlane_b32 s99, v165, 15
	v_readlane_b32 vcc_lo, v165, 46
	v_readlane_b32 vcc_hi, v165, 47
	v_pk_mul_f32 v[144:145], v[154:155], v[144:145]
	v_pk_mul_f32 v[148:149], v[154:155], v[148:149]
	v_pk_mul_f32 v[144:145], v[144:145], s[98:99]
	v_pk_mul_f32 v[148:149], v[148:149], vcc
	v_pk_mul_f32 v[214:215], v[144:145], v[192:193]
	s_nop 0
	v_pk_fma_f32 v[214:215], v[148:149], v[188:189], v[214:215]
	v_pk_mul_f32 v[148:149], v[148:149], v[192:193]
	s_nop 0
	v_pk_fma_f32 v[144:145], v[144:145], v[188:189], v[148:149] neg_lo:[0,0,1] neg_hi:[0,0,1]
	v_pk_mul_f32 v[214:215], v[214:215], s[16:17] op_sel_hi:[1,0]
	v_pk_mul_f32 v[144:145], v[144:145], s[16:17] op_sel_hi:[1,0]
	v_cvt_pk_bf16_f32 v141, v214, v215
	v_cvt_pk_bf16_f32 v137, v144, v145
	ds_read_b64 v[144:145], v0 offset:72
	ds_read_b64 v[148:149], v0 offset:200
	global_store_dwordx4 v[158:159], v[134:137], off offset:-48
	global_store_dwordx4 v[158:159], v[138:141], off offset:16
	s_waitcnt vmcnt(10)
	s_waitcnt lgkmcnt(2)
	v_readlane_b32 s98, v165, 16
	v_readlane_b32 s99, v165, 17
	v_readlane_b32 vcc_lo, v165, 48
	v_readlane_b32 vcc_hi, v165, 49
	v_pk_mul_f32 v[142:143], v[154:155], v[142:143]
	v_pk_mul_f32 v[146:147], v[154:155], v[146:147]
	v_pk_mul_f32 v[142:143], v[142:143], s[98:99]
	v_pk_mul_f32 v[146:147], v[146:147], vcc
	v_pk_mul_f32 v[214:215], v[142:143], v[198:199]
	s_nop 0
	v_pk_fma_f32 v[214:215], v[146:147], v[194:195], v[214:215]
	v_pk_mul_f32 v[146:147], v[146:147], v[198:199]
	s_nop 0
	v_pk_fma_f32 v[142:143], v[142:143], v[194:195], v[146:147] neg_lo:[0,0,1] neg_hi:[0,0,1]
	v_pk_mul_f32 v[214:215], v[214:215], s[16:17] op_sel_hi:[1,0]
	v_pk_mul_f32 v[142:143], v[142:143], s[16:17] op_sel_hi:[1,0]
	v_cvt_pk_bf16_f32 v138, v214, v215
	v_cvt_pk_bf16_f32 v134, v142, v143
	ds_read_b64 v[142:143], v0 offset:80
	ds_read_b64 v[146:147], v0 offset:208
	s_waitcnt lgkmcnt(2)
	v_readlane_b32 s98, v165, 18
	v_readlane_b32 s99, v165, 19
	v_readlane_b32 vcc_lo, v165, 50
	v_readlane_b32 vcc_hi, v165, 51
	v_pk_mul_f32 v[144:145], v[154:155], v[144:145]
	v_pk_mul_f32 v[148:149], v[154:155], v[148:149]
	v_pk_mul_f32 v[144:145], v[144:145], s[98:99]
	v_pk_mul_f32 v[148:149], v[148:149], vcc
	v_pk_mul_f32 v[214:215], v[144:145], v[200:201]
	s_nop 0
	v_pk_fma_f32 v[214:215], v[148:149], v[196:197], v[214:215]
	v_pk_mul_f32 v[148:149], v[148:149], v[200:201]
	s_nop 0
	v_pk_fma_f32 v[144:145], v[144:145], v[196:197], v[148:149] neg_lo:[0,0,1] neg_hi:[0,0,1]
	v_pk_mul_f32 v[214:215], v[214:215], s[16:17] op_sel_hi:[1,0]
	v_pk_mul_f32 v[144:145], v[144:145], s[16:17] op_sel_hi:[1,0]
	v_cvt_pk_bf16_f32 v139, v214, v215
	v_cvt_pk_bf16_f32 v135, v144, v145
	ds_read_b64 v[144:145], v0 offset:88
	ds_read_b64 v[148:149], v0 offset:216
	s_waitcnt vmcnt(8)
	s_waitcnt lgkmcnt(2)
	v_readlane_b32 s98, v165, 20
	v_readlane_b32 s99, v165, 21
	v_readlane_b32 vcc_lo, v165, 52
	v_readlane_b32 vcc_hi, v165, 53
	v_pk_mul_f32 v[142:143], v[154:155], v[142:143]
	v_pk_mul_f32 v[146:147], v[154:155], v[146:147]
	v_pk_mul_f32 v[142:143], v[142:143], s[98:99]
	v_pk_mul_f32 v[146:147], v[146:147], vcc
	v_pk_mul_f32 v[214:215], v[142:143], v[210:211]
	s_nop 0
	v_pk_fma_f32 v[214:215], v[146:147], v[202:203], v[214:215]
	v_pk_mul_f32 v[146:147], v[146:147], v[210:211]
	s_nop 0
	v_pk_fma_f32 v[142:143], v[142:143], v[202:203], v[146:147] neg_lo:[0,0,1] neg_hi:[0,0,1]
	v_pk_mul_f32 v[214:215], v[214:215], s[16:17] op_sel_hi:[1,0]
	v_pk_mul_f32 v[142:143], v[142:143], s[16:17] op_sel_hi:[1,0]
	v_cvt_pk_bf16_f32 v140, v214, v215
	v_cvt_pk_bf16_f32 v136, v142, v143
	ds_read_b64 v[142:143], v0 offset:96
	ds_read_b64 v[146:147], v0 offset:224
	s_waitcnt lgkmcnt(2)
; DI uint4 pack8(const float* v) { uint4 r; r.x = pk2(v[0], v[1]); r.y = pk2(v[2], v[3]); r.z = pk2(v[4], v[5]); r.w = pk2(v[6], v[7]); return r; }
; DI void qk_epilogue(const float* st  , int m0, const float* __restrict__ gain, float scale, bf16_t* __restrict__ dst, int dstride, int dcol0,
;                     const float* __restrict__ COS, const float* __restrict__ SIN) {
;     ...
;   for (int j = 0; j < 32; j += 8) {
;     float o1[8], o2[8];
; #pragma unroll
;     for (int q = 0; q < 8; ++q) {
;       const float x1 = sp[j + q] * rr * gain[j + q], x2 = sp[j + q + 32] * rr * gain[j + q + 32];
;       const float cs = COS[tok * 32 + j + q], sn = SIN[tok * 32 + j + q];
;       o1[q] = (x1 * cs - x2 * sn) * scale;
;       o2[q] = (x2 * cs + x1 * sn) * scale;
;     }
;     *(uint4*)(dp + j) = pack8(o1);
;     *(uint4*)(dp + j + 32) = pack8(o2);
;   }
	v_readlane_b32 s98, v165, 22
	v_readlane_b32 s99, v165, 23
	v_readlane_b32 vcc_lo, v165, 54
	v_readlane_b32 vcc_hi, v165, 55
	v_pk_mul_f32 v[144:145], v[154:155], v[144:145]
	v_pk_mul_f32 v[148:149], v[154:155], v[148:149]
	v_pk_mul_f32 v[144:145], v[144:145], s[98:99]
	v_pk_mul_f32 v[148:149], v[148:149], vcc
	v_pk_mul_f32 v[214:215], v[144:145], v[212:213]
	s_nop 0
	v_pk_fma_f32 v[214:215], v[148:149], v[204:205], v[214:215]
	v_pk_mul_f32 v[148:149], v[148:149], v[212:213]
	s_nop 0
	v_pk_fma_f32 v[144:145], v[144:145], v[204:205], v[148:149] neg_lo:[0,0,1] neg_hi:[0,0,1]
	v_pk_mul_f32 v[214:215], v[214:215], s[16:17] op_sel_hi:[1,0]
	v_pk_mul_f32 v[144:145], v[144:145], s[16:17] op_sel_hi:[1,0]
	v_cvt_pk_bf16_f32 v141, v214, v215
	v_cvt_pk_bf16_f32 v137, v144, v145
	ds_read_b64 v[144:145], v0 offset:104
	ds_read_b64 v[148:149], v0 offset:232
	global_store_dwordx4 v[158:159], v[134:137], off offset:-32
	global_store_dwordx4 v[158:159], v[138:141], off offset:32
	s_waitcnt vmcnt(8)
	s_waitcnt lgkmcnt(2)
	v_readlane_b32 s98, v165, 24
	v_readlane_b32 s99, v165, 25
	v_readlane_b32 vcc_lo, v165, 56
	v_readlane_b32 vcc_hi, v165, 57
	v_pk_mul_f32 v[142:143], v[154:155], v[142:143]
	v_pk_mul_f32 v[146:147], v[154:155], v[146:147]
	v_pk_mul_f32 v[142:143], v[142:143], s[98:99]
	v_pk_mul_f32 v[146:147], v[146:147], vcc
	v_pk_mul_f32 v[214:215], v[142:143], v[248:249]
	s_nop 0
	v_pk_fma_f32 v[214:215], v[146:147], v[236:237], v[214:215]
	v_pk_mul_f32 v[146:147], v[146:147], v[248:249]
	s_nop 0
	v_pk_fma_f32 v[142:143], v[142:143], v[236:237], v[146:147] neg_lo:[0,0,1] neg_hi:[0,0,1]
	v_pk_mul_f32 v[214:215], v[214:215], s[16:17] op_sel_hi:[1,0]
	v_pk_mul_f32 v[142:143], v[142:143], s[16:17] op_sel_hi:[1,0]
	v_cvt_pk_bf16_f32 v138, v214, v215
	v_cvt_pk_bf16_f32 v134, v142, v143
	ds_read_b64 v[142:143], v0 offset:112
	ds_read_b64 v[146:147], v0 offset:240
	s_waitcnt lgkmcnt(2)
	v_readlane_b32 s98, v165, 26
	v_readlane_b32 s99, v165, 27
	v_readlane_b32 vcc_lo, v165, 58
	v_readlane_b32 vcc_hi, v165, 59
	v_pk_mul_f32 v[144:145], v[154:155], v[144:145]
	v_pk_mul_f32 v[148:149], v[154:155], v[148:149]
	v_pk_mul_f32 v[144:145], v[144:145], s[98:99]
	v_pk_mul_f32 v[148:149], v[148:149], vcc
	v_pk_mul_f32 v[214:215], v[144:145], v[250:251]
	s_nop 0
	v_pk_fma_f32 v[214:215], v[148:149], v[238:239], v[214:215]
	v_pk_mul_f32 v[148:149], v[148:149], v[250:251]
	s_nop 0
	v_pk_fma_f32 v[144:145], v[144:145], v[238:239], v[148:149] neg_lo:[0,0,1] neg_hi:[0,0,1]
	v_pk_mul_f32 v[214:215], v[214:215], s[16:17] op_sel_hi:[1,0]
	v_pk_mul_f32 v[144:145], v[144:145], s[16:17] op_sel_hi:[1,0]
	v_cvt_pk_bf16_f32 v139, v214, v215
	v_cvt_pk_bf16_f32 v135, v144, v145
	ds_read_b64 v[144:145], v0 offset:120
	ds_read_b64 v[148:149], v0 offset:248
	s_waitcnt vmcnt(6)
	s_waitcnt lgkmcnt(2)
	v_readlane_b32 s98, v165, 28
	v_readlane_b32 s99, v165, 29
	v_readlane_b32 vcc_lo, v165, 60
	v_readlane_b32 vcc_hi, v165, 61
	v_pk_mul_f32 v[142:143], v[154:155], v[142:143]
	v_pk_mul_f32 v[146:147], v[154:155], v[146:147]
	v_pk_mul_f32 v[142:143], v[142:143], s[98:99]
	v_pk_mul_f32 v[146:147], v[146:147], vcc
	v_pk_mul_f32 v[214:215], v[142:143], v[130:131]
	s_nop 0
	v_pk_fma_f32 v[214:215], v[146:147], v[252:253], v[214:215]
	v_pk_mul_f32 v[146:147], v[146:147], v[130:131]
	s_nop 0
	v_pk_fma_f32 v[142:143], v[142:143], v[252:253], v[146:147] neg_lo:[0,0,1] neg_hi:[0,0,1]
	v_pk_mul_f32 v[214:215], v[214:215], s[16:17] op_sel_hi:[1,0]
	v_pk_mul_f32 v[142:143], v[142:143], s[16:17] op_sel_hi:[1,0]
	v_cvt_pk_bf16_f32 v140, v214, v215
	v_cvt_pk_bf16_f32 v136, v142, v143
	s_waitcnt lgkmcnt(0)
	v_readlane_b32 s98, v165, 30
	v_readlane_b32 s99, v165, 31
	v_readlane_b32 vcc_lo, v165, 62
	v_readlane_b32 vcc_hi, v165, 63
	v_pk_mul_f32 v[144:145], v[154:155], v[144:145]
	v_pk_mul_f32 v[148:149], v[154:155], v[148:149]
	v_pk_mul_f32 v[144:145], v[144:145], s[98:99]
	v_pk_mul_f32 v[148:149], v[148:149], vcc
	v_pk_mul_f32 v[214:215], v[144:145], v[132:133]
	s_nop 0
	v_pk_fma_f32 v[214:215], v[148:149], v[254:255], v[214:215]
	v_pk_mul_f32 v[148:149], v[148:149], v[132:133]
	s_nop 0
	v_pk_fma_f32 v[144:145], v[144:145], v[254:255], v[148:149] neg_lo:[0,0,1] neg_hi:[0,0,1]
	v_pk_mul_f32 v[214:215], v[214:215], s[16:17] op_sel_hi:[1,0]
	v_pk_mul_f32 v[144:145], v[144:145], s[16:17] op_sel_hi:[1,0]
	v_cvt_pk_bf16_f32 v141, v214, v215
	v_cvt_pk_bf16_f32 v137, v144, v145
	global_store_dwordx4 v[158:159], v[134:137], off offset:-16
	global_store_dwordx4 v[158:159], v[138:141], off offset:48

; DI int otid() { int t = threadIdx.x; asm volatile("" : "+v"(t)); return t; }
; DI void qk_epilogue(const float* st  , int m0, const float* __restrict__ gain, float scale, bf16_t* __restrict__ dst, int dstride, int dcol0,
;                     const float* __restrict__ COS, const float* __restrict__ SIN) {
;   const int tid = otid(), row = tid & 127, hd = tid >> 7;
;   const float* sp = st + row * 132 + hd * 64;
;   float ss = 0.f;
; #pragma unroll 4
;   for (int j = 0; j < 64; j += 4) { const float4 v = *(const float4*)(sp + j); ss += v.x * v.x + v.y * v.y + v.z * v.z + v.w * v.w; }
;   const float rr = rsqrtf(ss * (1.f / 64.f) + 1e-6f);
;   const size_t tok = (size_t)(m0 + row);
;   bf16_t* dp = dst + tok * dstride + dcol0 + hd * 64;
; #pragma unroll 2
;   for (int j = 0; j < 32; j += 8) {
;     float o1[8], o2[8];
; #pragma unroll
;     for (int q = 0; q < 8; ++q) {
;       const float x1 = sp[j + q] * rr * gain[j + q], x2 = sp[j + q + 32] * rr * gain[j + q + 32];
;       const float cs = COS[tok * 32 + j + q], sn = SIN[tok * 32 + j + q];
.LBB0_400:
	s_and_b64 vcc, exec, s[28:29]
	s_cbranch_vccz .LBB0_406
	v_lshlrev_b32_e32 v136, 2, v231
	s_mov_b32 vcc_lo, s59
	s_mov_b32 vcc_hi, s60
	global_load_dword v165, v136, vcc
	s_add_i32 s98, s64, s65
	v_and_b32_e32 v134, 0x7f, v216
	v_add_lshl_u32 v134, v134, s98, 7
	v_add_u32_e32 v135, 0x2178000, v134
	v_add_u32_e32 v134, 0x1f78000, v134
	global_load_dwordx4 v[150:153], v134, s[82:83]
	global_load_dwordx4 v[160:163], v135, s[82:83]
	global_load_dwordx4 v[166:169], v134, s[82:83] offset:16
	global_load_dwordx4 v[170:173], v135, s[82:83] offset:16
	global_load_dwordx4 v[174:177], v134, s[82:83] offset:32
	global_load_dwordx4 v[178:181], v135, s[82:83] offset:32
	global_load_dwordx4 v[186:189], v134, s[82:83] offset:48
	global_load_dwordx4 v[190:193], v135, s[82:83] offset:48
	global_load_dwordx4 v[194:197], v134, s[82:83] offset:64
	global_load_dwordx4 v[198:201], v135, s[82:83] offset:64
	global_load_dwordx4 v[202:205], v134, s[82:83] offset:80
	global_load_dwordx4 v[210:213], v135, s[82:83] offset:80
	global_load_dwordx4 v[236:239], v134, s[82:83] offset:96
	global_load_dwordx4 v[248:251], v135, s[82:83] offset:96
	global_load_dwordx4 v[252:255], v134, s[82:83] offset:112
	v_mov_b32_e32 v130, v216
	s_mov_b32 s9, -4
	v_and_b32_e32 v0, 0x7f, v130
	v_ashrrev_i32_e32 v130, 1, v130
	v_and_b32_e32 v130, 0xffffffc0, v130
	v_lshlrev_b32_e32 v131, 2, v130
	v_mad_u32_u24 v164, v0, s8, v131
	v_mov_b32_e32 v131, 0
	v_mov_b32_e32 v132, v164

; DI uint4 pack8(const float* v) { uint4 r; r.x = pk2(v[0], v[1]); r.y = pk2(v[2], v[3]); r.z = pk2(v[4], v[5]); r.w = pk2(v[6], v[7]); return r; }
; DI void qk_epilogue(const float* st  , int m0, const float* __restrict__ gain, float scale, bf16_t* __restrict__ dst, int dstride, int dcol0,
;                     const float* __restrict__ COS, const float* __restrict__ SIN) {
;     ...
;   for (int j = 0; j < 32; j += 8) {
;     float o1[8], o2[8];
; #pragma unroll
;     for (int q = 0; q < 8; ++q) {
;       const float x1 = sp[j + q] * rr * gain[j + q], x2 = sp[j + q + 32] * rr * gain[j + q + 32];
;       const float cs = COS[tok * 32 + j + q], sn = SIN[tok * 32 + j + q];
;       o1[q] = (x1 * cs - x2 * sn) * scale;
;       o2[q] = (x2 * cs + x1 * sn) * scale;
;     }
;     *(uint4*)(dp + j) = pack8(o1);
;     *(uint4*)(dp + j + 32) = pack8(o2);
;   }
.LBB0_404:
	s_add_i32 s98, s64, s65
	v_and_b32_e32 v134, 0x7f, v216
	v_add_lshl_u32 v134, v134, s98, 7
	v_add_u32_e32 v135, 0x2178000, v134
	v_add_u32_e32 v134, 0x1f78000, v134
	global_load_dwordx4 v[130:133], v135, s[82:83] offset:112
	ds_read_b64 v[142:143], v0
	ds_read_b64 v[146:147], v0 offset:128
	ds_read_b64 v[144:145], v0 offset:8
	ds_read_b64 v[148:149], v0 offset:136
	s_waitcnt vmcnt(14)
	s_waitcnt lgkmcnt(2)
	v_readlane_b32 s98, v165, 0
	v_readlane_b32 s99, v165, 1
	v_readlane_b32 vcc_lo, v165, 32
	v_readlane_b32 vcc_hi, v165, 33
	v_pk_mul_f32 v[142:143], v[154:155], v[142:143]
	v_pk_mul_f32 v[146:147], v[154:155], v[146:147]
	v_pk_mul_f32 v[142:143], v[142:143], s[98:99]
	v_pk_mul_f32 v[146:147], v[146:147], vcc
	v_pk_mul_f32 v[214:215], v[142:143], v[160:161]
	s_nop 0
	v_pk_fma_f32 v[214:215], v[146:147], v[150:151], v[214:215]
	v_pk_mul_f32 v[146:147], v[146:147], v[160:161]
	s_nop 0
	v_pk_fma_f32 v[142:143], v[142:143], v[150:151], v[146:147] neg_lo:[0,0,1] neg_hi:[0,0,1]
	v_pk_mul_f32 v[214:215], v[214:215], s[16:17] op_sel_hi:[1,0]
	v_pk_mul_f32 v[142:143], v[142:143], s[16:17] op_sel_hi:[1,0]
	v_cvt_pk_bf16_f32 v138, v214, v215
	v_cvt_pk_bf16_f32 v134, v142, v143
	ds_read_b64 v[142:143], v0 offset:16
	ds_read_b64 v[146:147], v0 offset:144
	s_waitcnt lgkmcnt(2)
	v_readlane_b32 s98, v165, 2
	v_readlane_b32 s99, v165, 3
	v_readlane_b32 vcc_lo, v165, 34
	v_readlane_b32 vcc_hi, v165, 35
	v_pk_mul_f32 v[144:145], v[154:155], v[144:145]
	v_pk_mul_f32 v[148:149], v[154:155], v[148:149]
	v_pk_mul_f32 v[144:145], v[144:145], s[98:99]
	v_pk_mul_f32 v[148:149], v[148:149], vcc
	v_pk_mul_f32 v[214:215], v[144:145], v[162:163]
	s_nop 0
	v_pk_fma_f32 v[214:215], v[148:149], v[152:153], v[214:215]
	v_pk_mul_f32 v[148:149], v[148:149], v[162:163]
	s_nop 0
	v_pk_fma_f32 v[144:145], v[144:145], v[152:153], v[148:149] neg_lo:[0,0,1] neg_hi:[0,0,1]
	v_pk_mul_f32 v[214:215], v[214:215], s[16:17] op_sel_hi:[1,0]
	v_pk_mul_f32 v[144:145], v[144:145], s[16:17] op_sel_hi:[1,0]
	v_cvt_pk_bf16_f32 v139, v214, v215
	v_cvt_pk_bf16_f32 v135, v144, v145
	ds_read_b64 v[144:145], v0 offset:24
	ds_read_b64 v[148:149], v0 offset:152
	s_waitcnt vmcnt(12)
	s_waitcnt lgkmcnt(2)
	v_readlane_b32 s98, v165, 4
	v_readlane_b32 s99, v165, 5
	v_readlane_b32 vcc_lo, v165, 36
	v_readlane_b32 vcc_hi, v165, 37
	v_pk_mul_f32 v[142:143], v[154:155], v[142:143]
	v_pk_mul_f32 v[146:147], v[154:155], v[146:147]
	v_pk_mul_f32 v[142:143], v[142:143], s[98:99]
	v_pk_mul_f32 v[146:147], v[146:147], vcc
	v_pk_mul_f32 v[214:215], v[142:143], v[170:171]
	s_nop 0
	v_pk_fma_f32 v[214:215], v[146:147], v[166:167], v[214:215]
	v_pk_mul_f32 v[146:147], v[146:147], v[170:171]
	s_nop 0
	v_pk_fma_f32 v[142:143], v[142:143], v[166:167], v[146:147] neg_lo:[0,0,1] neg_hi:[0,0,1]
	v_pk_mul_f32 v[214:215], v[214:215], s[16:17] op_sel_hi:[1,0]
	v_pk_mul_f32 v[142:143], v[142:143], s[16:17] op_sel_hi:[1,0]
	v_cvt_pk_bf16_f32 v140, v214, v215
	v_cvt_pk_bf16_f32 v136, v142, v143
	ds_read_b64 v[142:143], v0 offset:32
	ds_read_b64 v[146:147], v0 offset:160
	s_waitcnt lgkmcnt(2)
	v_readlane_b32 s98, v165, 6
	v_readlane_b32 s99, v165, 7
	v_readlane_b32 vcc_lo, v165, 38
	v_readlane_b32 vcc_hi, v165, 39
	v_pk_mul_f32 v[144:145], v[154:155], v[144:145]
	v_pk_mul_f32 v[148:149], v[154:155], v[148:149]
	v_pk_mul_f32 v[144:145], v[144:145], s[98:99]
	v_pk_mul_f32 v[148:149], v[148:149], vcc
	v_pk_mul_f32 v[214:215], v[144:145], v[172:173]
	s_nop 0
	v_pk_fma_f32 v[214:215], v[148:149], v[168:169], v[214:215]
	v_pk_mul_f32 v[148:149], v[148:149], v[172:173]
	s_nop 0
	v_pk_fma_f32 v[144:145], v[144:145], v[168:169], v[148:149] neg_lo:[0,0,1] neg_hi:[0,0,1]
	v_pk_mul_f32 v[214:215], v[214:215], s[16:17] op_sel_hi:[1,0]
	v_pk_mul_f32 v[144:145], v[144:145], s[16:17] op_sel_hi:[1,0]
	v_cvt_pk_bf16_f32 v141, v214, v215
	v_cvt_pk_bf16_f32 v137, v144, v145
	ds_read_b64 v[144:145], v0 offset:40
	ds_read_b64 v[148:149], v0 offset:168
	global_store_dwordx4 v[158:159], v[134:137], off offset:-64
	global_store_dwordx4 v[158:159], v[138:141], off
	s_waitcnt vmcnt(12)
	s_waitcnt lgkmcnt(2)
	v_readlane_b32 s98, v165, 8
	v_readlane_b32 s99, v165, 9
	v_readlane_b32 vcc_lo, v165, 40
	v_readlane_b32 vcc_hi, v165, 41
	v_pk_mul_f32 v[142:143], v[154:155], v[142:143]
	v_pk_mul_f32 v[146:147], v[154:155], v[146:147]
	v_pk_mul_f32 v[142:143], v[142:143], s[98:99]
	v_pk_mul_f32 v[146:147], v[146:147], vcc
	v_pk_mul_f32 v[214:215], v[142:143], v[178:179]
	s_nop 0
	v_pk_fma_f32 v[214:215], v[146:147], v[174:175], v[214:215]
	v_pk_mul_f32 v[146:147], v[146:147], v[178:179]
	s_nop 0
	v_pk_fma_f32 v[142:143], v[142:143], v[174:175], v[146:147] neg_lo:[0,0,1] neg_hi:[0,0,1]
	v_pk_mul_f32 v[214:215], v[214:215], s[16:17] op_sel_hi:[1,0]
	v_pk_mul_f32 v[142:143], v[142:143], s[16:17] op_sel_hi:[1,0]
	v_cvt_pk_bf16_f32 v138, v214, v215
	v_cvt_pk_bf16_f32 v134, v142, v143
	ds_read_b64 v[142:143], v0 offset:48
	ds_read_b64 v[146:147], v0 offset:176
	s_waitcnt lgkmcnt(2)
	v_readlane_b32 s98, v165, 10
	v_readlane_b32 s99, v165, 11
	v_readlane_b32 vcc_lo, v165, 42
	v_readlane_b32 vcc_hi, v165, 43
	v_pk_mul_f32 v[144:145], v[154:155], v[144:145]
	v_pk_mul_f32 v[148:149], v[154:155], v[148:149]
	v_pk_mul_f32 v[144:145], v[144:145], s[98:99]
	v_pk_mul_f32 v[148:149], v[148:149], vcc
	v_pk_mul_f32 v[214:215], v[144:145], v[180:181]
	s_nop 0
	v_pk_fma_f32 v[214:215], v[148:149], v[176:177], v[214:215]
	v_pk_mul_f32 v[148:149], v[148:149], v[180:181]
	s_nop 0
	v_pk_fma_f32 v[144:145], v[144:145], v[176:177], v[148:149] neg_lo:[0,0,1] neg_hi:[0,0,1]
	v_pk_mul_f32 v[214:215], v[214:215], s[16:17] op_sel_hi:[1,0]
	v_pk_mul_f32 v[144:145], v[144:145], s[16:17] op_sel_hi:[1,0]
	v_cvt_pk_bf16_f32 v139, v214, v215
	v_cvt_pk_bf16_f32 v135, v144, v145
	ds_read_b64 v[144:145], v0 offset:56
	ds_read_b64 v[148:149], v0 offset:184
	s_waitcnt vmcnt(10)
; DI uint4 pack8(const float* v) { uint4 r; r.x = pk2(v[0], v[1]); r.y = pk2(v[2], v[3]); r.z = pk2(v[4], v[5]); r.w = pk2(v[6], v[7]); return r; }
; DI void qk_epilogue(const float* st  , int m0, const float* __restrict__ gain, float scale, bf16_t* __restrict__ dst, int dstride, int dcol0,
;                     const float* __restrict__ COS, const float* __restrict__ SIN) {
;     ...
;   for (int j = 0; j < 32; j += 8) {
;     float o1[8], o2[8];
; #pragma unroll
;     for (int q = 0; q < 8; ++q) {
;       const float x1 = sp[j + q] * rr * gain[j + q], x2 = sp[j + q + 32] * rr * gain[j + q + 32];
;       const float cs = COS[tok * 32 + j + q], sn = SIN[tok * 32 + j + q];
;       o1[q] = (x1 * cs - x2 * sn) * scale;
;       o2[q] = (x2 * cs + x1 * sn) * scale;
;     }
;     *(uint4*)(dp + j) = pack8(o1);
;     *(uint4*)(dp + j + 32) = pack8(o2);
;   }
	s_waitcnt lgkmcnt(2)
	v_readlane_b32 s98, v165, 12
	v_readlane_b32 s99, v165, 13
	v_readlane_b32 vcc_lo, v165, 44
	v_readlane_b32 vcc_hi, v165, 45
	v_pk_mul_f32 v[142:143], v[154:155], v[142:143]
	v_pk_mul_f32 v[146:147], v[154:155], v[146:147]
	v_pk_mul_f32 v[142:143], v[142:143], s[98:99]
	v_pk_mul_f32 v[146:147], v[146:147], vcc
	v_pk_mul_f32 v[214:215], v[142:143], v[190:191]
	s_nop 0
	v_pk_fma_f32 v[214:215], v[146:147], v[186:187], v[214:215]
	v_pk_mul_f32 v[146:147], v[146:147], v[190:191]
	s_nop 0
	v_pk_fma_f32 v[142:143], v[142:143], v[186:187], v[146:147] neg_lo:[0,0,1] neg_hi:[0,0,1]
	v_pk_mul_f32 v[214:215], v[214:215], s[16:17] op_sel_hi:[1,0]
	v_pk_mul_f32 v[142:143], v[142:143], s[16:17] op_sel_hi:[1,0]
	v_cvt_pk_bf16_f32 v140, v214, v215
	v_cvt_pk_bf16_f32 v136, v142, v143
	ds_read_b64 v[142:143], v0 offset:64
	ds_read_b64 v[146:147], v0 offset:192
	s_waitcnt lgkmcnt(2)
	v_readlane_b32 s98, v165, 14
	v_readlane_b32 s99, v165, 15
	v_readlane_b32 vcc_lo, v165, 46
	v_readlane_b32 vcc_hi, v165, 47
	v_pk_mul_f32 v[144:145], v[154:155], v[144:145]
	v_pk_mul_f32 v[148:149], v[154:155], v[148:149]
	v_pk_mul_f32 v[144:145], v[144:145], s[98:99]
	v_pk_mul_f32 v[148:149], v[148:149], vcc
	v_pk_mul_f32 v[214:215], v[144:145], v[192:193]
	s_nop 0
	v_pk_fma_f32 v[214:215], v[148:149], v[188:189], v[214:215]
	v_pk_mul_f32 v[148:149], v[148:149], v[192:193]
	s_nop 0
	v_pk_fma_f32 v[144:145], v[144:145], v[188:189], v[148:149] neg_lo:[0,0,1] neg_hi:[0,0,1]
	v_pk_mul_f32 v[214:215], v[214:215], s[16:17] op_sel_hi:[1,0]
	v_pk_mul_f32 v[144:145], v[144:145], s[16:17] op_sel_hi:[1,0]
	v_cvt_pk_bf16_f32 v141, v214, v215
	v_cvt_pk_bf16_f32 v137, v144, v145
	ds_read_b64 v[144:145], v0 offset:72
	ds_read_b64 v[148:149], v0 offset:200
	global_store_dwordx4 v[158:159], v[134:137], off offset:-48
	global_store_dwordx4 v[158:159], v[138:141], off offset:16
	s_waitcnt vmcnt(10)
	s_waitcnt lgkmcnt(2)
	v_readlane_b32 s98, v165, 16
	v_readlane_b32 s99, v165, 17
	v_readlane_b32 vcc_lo, v165, 48
	v_readlane_b32 vcc_hi, v165, 49
	v_pk_mul_f32 v[142:143], v[154:155], v[142:143]
	v_pk_mul_f32 v[146:147], v[154:155], v[146:147]
	v_pk_mul_f32 v[142:143], v[142:143], s[98:99]
	v_pk_mul_f32 v[146:147], v[146:147], vcc
	v_pk_mul_f32 v[214:215], v[142:143], v[198:199]
	s_nop 0
	v_pk_fma_f32 v[214:215], v[146:147], v[194:195], v[214:215]
	v_pk_mul_f32 v[146:147], v[146:147], v[198:199]
	s_nop 0
	v_pk_fma_f32 v[142:143], v[142:143], v[194:195], v[146:147] neg_lo:[0,0,1] neg_hi:[0,0,1]
	v_pk_mul_f32 v[214:215], v[214:215], s[16:17] op_sel_hi:[1,0]
	v_pk_mul_f32 v[142:143], v[142:143], s[16:17] op_sel_hi:[1,0]
	v_cvt_pk_bf16_f32 v138, v214, v215
	v_cvt_pk_bf16_f32 v134, v142, v143
	ds_read_b64 v[142:143], v0 offset:80
	ds_read_b64 v[146:147], v0 offset:208
	s_waitcnt lgkmcnt(2)
	v_readlane_b32 s98, v165, 18
	v_readlane_b32 s99, v165, 19
	v_readlane_b32 vcc_lo, v165, 50
	v_readlane_b32 vcc_hi, v165, 51
	v_pk_mul_f32 v[144:145], v[154:155], v[144:145]
	v_pk_mul_f32 v[148:149], v[154:155], v[148:149]
	v_pk_mul_f32 v[144:145], v[144:145], s[98:99]
	v_pk_mul_f32 v[148:149], v[148:149], vcc
	v_pk_mul_f32 v[214:215], v[144:145], v[200:201]
	s_nop 0
	v_pk_fma_f32 v[214:215], v[148:149], v[196:197], v[214:215]
	v_pk_mul_f32 v[148:149], v[148:149], v[200:201]
	s_nop 0
	v_pk_fma_f32 v[144:145], v[144:145], v[196:197], v[148:149] neg_lo:[0,0,1] neg_hi:[0,0,1]
	v_pk_mul_f32 v[214:215], v[214:215], s[16:17] op_sel_hi:[1,0]
	v_pk_mul_f32 v[144:145], v[144:145], s[16:17] op_sel_hi:[1,0]
	v_cvt_pk_bf16_f32 v139, v214, v215
	v_cvt_pk_bf16_f32 v135, v144, v145
	ds_read_b64 v[144:145], v0 offset:88
	ds_read_b64 v[148:149], v0 offset:216
	s_waitcnt vmcnt(8)
	s_waitcnt lgkmcnt(2)
	v_readlane_b32 s98, v165, 20
	v_readlane_b32 s99, v165, 21
	v_readlane_b32 vcc_lo, v165, 52
	v_readlane_b32 vcc_hi, v165, 53
	v_pk_mul_f32 v[142:143], v[154:155], v[142:143]
	v_pk_mul_f32 v[146:147], v[154:155], v[146:147]
	v_pk_mul_f32 v[142:143], v[142:143], s[98:99]
	v_pk_mul_f32 v[146:147], v[146:147], vcc
	v_pk_mul_f32 v[214:215], v[142:143], v[210:211]
	s_nop 0
	v_pk_fma_f32 v[214:215], v[146:147], v[202:203], v[214:215]
	v_pk_mul_f32 v[146:147], v[146:147], v[210:211]
	s_nop 0
	v_pk_fma_f32 v[142:143], v[142:143], v[202:203], v[146:147] neg_lo:[0,0,1] neg_hi:[0,0,1]
	v_pk_mul_f32 v[214:215], v[214:215], s[16:17] op_sel_hi:[1,0]
	v_pk_mul_f32 v[142:143], v[142:143], s[16:17] op_sel_hi:[1,0]
	v_cvt_pk_bf16_f32 v140, v214, v215
	v_cvt_pk_bf16_f32 v136, v142, v143
	ds_read_b64 v[142:143], v0 offset:96
	ds_read_b64 v[146:147], v0 offset:224
	s_waitcnt lgkmcnt(2)
; DI uint4 pack8(const float* v) { uint4 r; r.x = pk2(v[0], v[1]); r.y = pk2(v[2], v[3]); r.z = pk2(v[4], v[5]); r.w = pk2(v[6], v[7]); return r; }
; DI void qk_epilogue(const float* st  , int m0, const float* __restrict__ gain, float scale, bf16_t* __restrict__ dst, int dstride, int dcol0,
;                     const float* __restrict__ COS, const float* __restrict__ SIN) {
;     ...
; #pragma unroll 2
;   for (int j = 0; j < 32; j += 8) {
;     float o1[8], o2[8];
; #pragma unroll
;     for (int q = 0; q < 8; ++q) {
;       const float x1 = sp[j + q] * rr * gain[j + q], x2 = sp[j + q + 32] * rr * gain[j + q + 32];
;       const float cs = COS[tok * 32 + j + q], sn = SIN[tok * 32 + j + q];
;       o1[q] = (x1 * cs - x2 * sn) * scale;
;       o2[q] = (x2 * cs + x1 * sn) * scale;
;     }
;     *(uint4*)(dp + j) = pack8(o1);
;     *(uint4*)(dp + j + 32) = pack8(o2);
;   }
	v_readlane_b32 s98, v165, 22
	v_readlane_b32 s99, v165, 23
	v_readlane_b32 vcc_lo, v165, 54
	v_readlane_b32 vcc_hi, v165, 55
	v_pk_mul_f32 v[144:145], v[154:155], v[144:145]
	v_pk_mul_f32 v[148:149], v[154:155], v[148:149]
	v_pk_mul_f32 v[144:145], v[144:145], s[98:99]
	v_pk_mul_f32 v[148:149], v[148:149], vcc
	v_pk_mul_f32 v[214:215], v[144:145], v[212:213]
	s_nop 0
	v_pk_fma_f32 v[214:215], v[148:149], v[204:205], v[214:215]
	v_pk_mul_f32 v[148:149], v[148:149], v[212:213]
	s_nop 0
	v_pk_fma_f32 v[144:145], v[144:145], v[204:205], v[148:149] neg_lo:[0,0,1] neg_hi:[0,0,1]
	v_pk_mul_f32 v[214:215], v[214:215], s[16:17] op_sel_hi:[1,0]
	v_pk_mul_f32 v[144:145], v[144:145], s[16:17] op_sel_hi:[1,0]
	v_cvt_pk_bf16_f32 v141, v214, v215
	v_cvt_pk_bf16_f32 v137, v144, v145
	ds_read_b64 v[144:145], v0 offset:104
	ds_read_b64 v[148:149], v0 offset:232
	global_store_dwordx4 v[158:159], v[134:137], off offset:-32
	global_store_dwordx4 v[158:159], v[138:141], off offset:32
	s_waitcnt vmcnt(8)
	s_waitcnt lgkmcnt(2)
	v_readlane_b32 s98, v165, 24
	v_readlane_b32 s99, v165, 25
	v_readlane_b32 vcc_lo, v165, 56
	v_readlane_b32 vcc_hi, v165, 57
	v_pk_mul_f32 v[142:143], v[154:155], v[142:143]
	v_pk_mul_f32 v[146:147], v[154:155], v[146:147]
	v_pk_mul_f32 v[142:143], v[142:143], s[98:99]
	v_pk_mul_f32 v[146:147], v[146:147], vcc
	v_pk_mul_f32 v[214:215], v[142:143], v[248:249]
	s_nop 0
	v_pk_fma_f32 v[214:215], v[146:147], v[236:237], v[214:215]
	v_pk_mul_f32 v[146:147], v[146:147], v[248:249]
	s_nop 0
	v_pk_fma_f32 v[142:143], v[142:143], v[236:237], v[146:147] neg_lo:[0,0,1] neg_hi:[0,0,1]
	v_pk_mul_f32 v[214:215], v[214:215], s[16:17] op_sel_hi:[1,0]
	v_pk_mul_f32 v[142:143], v[142:143], s[16:17] op_sel_hi:[1,0]
	v_cvt_pk_bf16_f32 v138, v214, v215
	v_cvt_pk_bf16_f32 v134, v142, v143
	ds_read_b64 v[142:143], v0 offset:112
	ds_read_b64 v[146:147], v0 offset:240
	s_waitcnt lgkmcnt(2)
	v_readlane_b32 s98, v165, 26
	v_readlane_b32 s99, v165, 27
	v_readlane_b32 vcc_lo, v165, 58
	v_readlane_b32 vcc_hi, v165, 59
	v_pk_mul_f32 v[144:145], v[154:155], v[144:145]
	v_pk_mul_f32 v[148:149], v[154:155], v[148:149]
	v_pk_mul_f32 v[144:145], v[144:145], s[98:99]
	v_pk_mul_f32 v[148:149], v[148:149], vcc
	v_pk_mul_f32 v[214:215], v[144:145], v[250:251]
	s_nop 0
	v_pk_fma_f32 v[214:215], v[148:149], v[238:239], v[214:215]
	v_pk_mul_f32 v[148:149], v[148:149], v[250:251]
	s_nop 0
	v_pk_fma_f32 v[144:145], v[144:145], v[238:239], v[148:149] neg_lo:[0,0,1] neg_hi:[0,0,1]
	v_pk_mul_f32 v[214:215], v[214:215], s[16:17] op_sel_hi:[1,0]
	v_pk_mul_f32 v[144:145], v[144:145], s[16:17] op_sel_hi:[1,0]
	v_cvt_pk_bf16_f32 v139, v214, v215
	v_cvt_pk_bf16_f32 v135, v144, v145
	ds_read_b64 v[144:145], v0 offset:120
	ds_read_b64 v[148:149], v0 offset:248
	s_waitcnt vmcnt(6)
	s_waitcnt lgkmcnt(2)
	v_readlane_b32 s98, v165, 28
	v_readlane_b32 s99, v165, 29
	v_readlane_b32 vcc_lo, v165, 60
	v_readlane_b32 vcc_hi, v165, 61
	v_pk_mul_f32 v[142:143], v[154:155], v[142:143]
	v_pk_mul_f32 v[146:147], v[154:155], v[146:147]
	v_pk_mul_f32 v[142:143], v[142:143], s[98:99]
	v_pk_mul_f32 v[146:147], v[146:147], vcc
	v_pk_mul_f32 v[214:215], v[142:143], v[130:131]
	s_nop 0
	v_pk_fma_f32 v[214:215], v[146:147], v[252:253], v[214:215]
	v_pk_mul_f32 v[146:147], v[146:147], v[130:131]
	s_nop 0
	v_pk_fma_f32 v[142:143], v[142:143], v[252:253], v[146:147] neg_lo:[0,0,1] neg_hi:[0,0,1]
	v_pk_mul_f32 v[214:215], v[214:215], s[16:17] op_sel_hi:[1,0]
	v_pk_mul_f32 v[142:143], v[142:143], s[16:17] op_sel_hi:[1,0]
	v_cvt_pk_bf16_f32 v140, v214, v215
	v_cvt_pk_bf16_f32 v136, v142, v143
	s_waitcnt lgkmcnt(0)
	v_readlane_b32 s98, v165, 30
	v_readlane_b32 s99, v165, 31
	v_readlane_b32 vcc_lo, v165, 62
	v_readlane_b32 vcc_hi, v165, 63
	v_pk_mul_f32 v[144:145], v[154:155], v[144:145]
	v_pk_mul_f32 v[148:149], v[154:155], v[148:149]
	v_pk_mul_f32 v[144:145], v[144:145], s[98:99]
	v_pk_mul_f32 v[148:149], v[148:149], vcc
	v_pk_mul_f32 v[214:215], v[144:145], v[132:133]
	s_nop 0
	v_pk_fma_f32 v[214:215], v[148:149], v[254:255], v[214:215]
	v_pk_mul_f32 v[148:149], v[148:149], v[132:133]
	s_nop 0
	v_pk_fma_f32 v[144:145], v[144:145], v[254:255], v[148:149] neg_lo:[0,0,1] neg_hi:[0,0,1]
	v_pk_mul_f32 v[214:215], v[214:215], s[16:17] op_sel_hi:[1,0]
	v_pk_mul_f32 v[144:145], v[144:145], s[16:17] op_sel_hi:[1,0]
	v_cvt_pk_bf16_f32 v141, v214, v215
	v_cvt_pk_bf16_f32 v137, v144, v145
	global_store_dwordx4 v[158:159], v[134:137], off offset:-16
	global_store_dwordx4 v[158:159], v[138:141], off offset:48
	s_mov_b32 s50, 0x9b78000

; DI int otid() { int t = threadIdx.x; asm volatile("" : "+v"(t)); return t; }
; DI void qk_epilogue(const float* st  , int m0, const float* __restrict__ gain, float scale, bf16_t* __restrict__ dst, int dstride, int dcol0,
;                     const float* __restrict__ COS, const float* __restrict__ SIN) {
;   const int tid = otid(), row = tid & 127, hd = tid >> 7;
;   const float* sp = st + row * 132 + hd * 64;
;   float ss = 0.f;
; #pragma unroll 4
;   for (int j = 0; j < 64; j += 4) { const float4 v = *(const float4*)(sp + j); ss += v.x * v.x + v.y * v.y + v.z * v.z + v.w * v.w; }
;   const float rr = rsqrtf(ss * (1.f / 64.f) + 1e-6f);
;   const size_t tok = (size_t)(m0 + row);
;   bf16_t* dp = dst + tok * dstride + dcol0 + hd * 64;
; #pragma unroll 2
;   for (int j = 0; j < 32; j += 8) {
;     float o1[8], o2[8];
; #pragma unroll
;     for (int q = 0; q < 8; ++q) {
;       const float x1 = sp[j + q] * rr * gain[j + q], x2 = sp[j + q + 32] * rr * gain[j + q + 32];
;       const float cs = COS[tok * 32 + j + q], sn = SIN[tok * 32 + j + q];
.LBB0_428:
	s_andn2_b64 vcc, exec, s[28:29]
	s_cbranch_vccnz .LBB0_433
	v_lshlrev_b32_e32 v4, 2, v231
	s_mov_b32 vcc_lo, s55
	s_mov_b32 vcc_hi, s56
	global_load_dword v37, v4, vcc
	s_add_i32 s98, s64, s65
	s_addk_i32 s98, 0x80
	v_and_b32_e32 v2, 0x7f, v216
	v_add_lshl_u32 v2, v2, s98, 7
	v_add_u32_e32 v3, 0x2178000, v2
	v_add_u32_e32 v2, 0x1f78000, v2
	global_load_dwordx4 v[22:25], v2, s[82:83]
	global_load_dwordx4 v[32:35], v3, s[82:83]
	global_load_dwordx4 v[38:41], v2, s[82:83] offset:16
	global_load_dwordx4 v[42:45], v3, s[82:83] offset:16
	global_load_dwordx4 v[46:49], v2, s[82:83] offset:32
	global_load_dwordx4 v[50:53], v3, s[82:83] offset:32
	global_load_dwordx4 v[54:57], v2, s[82:83] offset:48
	global_load_dwordx4 v[58:61], v3, s[82:83] offset:48
	global_load_dwordx4 v[62:65], v2, s[82:83] offset:64
	global_load_dwordx4 v[66:69], v3, s[82:83] offset:64
	global_load_dwordx4 v[70:73], v2, s[82:83] offset:80
	global_load_dwordx4 v[74:77], v3, s[82:83] offset:80
	global_load_dwordx4 v[78:81], v2, s[82:83] offset:96
	global_load_dwordx4 v[82:85], v3, s[82:83] offset:96
	global_load_dwordx4 v[86:89], v2, s[82:83] offset:112
	global_load_dwordx4 v[90:93], v3, s[82:83] offset:112
	v_mov_b32_e32 v2, v216
	s_mov_b32 s9, -4
	v_and_b32_e32 v0, 0x7f, v2
	v_ashrrev_i32_e32 v2, 1, v2
	v_and_b32_e32 v2, 0xffffffc0, v2
	v_lshlrev_b32_e32 v3, 2, v2
	v_mad_u32_u24 v36, v0, s8, v3
	v_mov_b32_e32 v3, 0
	v_mov_b32_e32 v4, v36

; DI uint4 pack8(const float* v) { uint4 r; r.x = pk2(v[0], v[1]); r.y = pk2(v[2], v[3]); r.z = pk2(v[4], v[5]); r.w = pk2(v[6], v[7]); return r; }
; DI void qk_epilogue(const float* st  , int m0, const float* __restrict__ gain, float scale, bf16_t* __restrict__ dst, int dstride, int dcol0,
;                     const float* __restrict__ COS, const float* __restrict__ SIN) {
;     ...
;   for (int j = 0; j < 32; j += 8) {
;     float o1[8], o2[8];
; #pragma unroll
;     for (int q = 0; q < 8; ++q) {
;       const float x1 = sp[j + q] * rr * gain[j + q], x2 = sp[j + q + 32] * rr * gain[j + q + 32];
;       const float cs = COS[tok * 32 + j + q], sn = SIN[tok * 32 + j + q];
;       o1[q] = (x1 * cs - x2 * sn) * scale;
;       o2[q] = (x2 * cs + x1 * sn) * scale;
;     }
;     *(uint4*)(dp + j) = pack8(o1);
;     *(uint4*)(dp + j + 32) = pack8(o2);
.LBB0_432:
	ds_read_b64 v[10:11], v0
	ds_read_b64 v[14:15], v0 offset:128
	ds_read_b64 v[12:13], v0 offset:8
	ds_read_b64 v[16:17], v0 offset:136
	s_waitcnt vmcnt(14)
	s_waitcnt lgkmcnt(2)
	v_readlane_b32 s98, v37, 0
	v_readlane_b32 s99, v37, 1
	v_readlane_b32 vcc_lo, v37, 32
	v_readlane_b32 vcc_hi, v37, 33
	v_pk_mul_f32 v[10:11], v[26:27], v[10:11]
	v_pk_mul_f32 v[14:15], v[26:27], v[14:15]
	v_pk_mul_f32 v[10:11], v[10:11], s[98:99]
	v_pk_mul_f32 v[14:15], v[14:15], vcc
	v_pk_mul_f32 v[18:19], v[10:11], v[32:33]
	s_nop 0
	v_pk_fma_f32 v[18:19], v[14:15], v[22:23], v[18:19]
	v_pk_mul_f32 v[14:15], v[14:15], v[32:33]
	s_nop 0
	v_pk_fma_f32 v[10:11], v[10:11], v[22:23], v[14:15] neg_lo:[0,0,1] neg_hi:[0,0,1]
	v_cvt_pk_bf16_f32 v6, v18, v19
	v_cvt_pk_bf16_f32 v2, v10, v11
	ds_read_b64 v[10:11], v0 offset:16
	ds_read_b64 v[14:15], v0 offset:144
	s_waitcnt lgkmcnt(2)
	v_readlane_b32 s98, v37, 2
	v_readlane_b32 s99, v37, 3
	v_readlane_b32 vcc_lo, v37, 34
	v_readlane_b32 vcc_hi, v37, 35
	v_pk_mul_f32 v[12:13], v[26:27], v[12:13]
	v_pk_mul_f32 v[16:17], v[26:27], v[16:17]
	v_pk_mul_f32 v[12:13], v[12:13], s[98:99]
	v_pk_mul_f32 v[16:17], v[16:17], vcc
	v_pk_mul_f32 v[18:19], v[12:13], v[34:35]
	s_nop 0
	v_pk_fma_f32 v[18:19], v[16:17], v[24:25], v[18:19]
	v_pk_mul_f32 v[16:17], v[16:17], v[34:35]
	s_nop 0
	v_pk_fma_f32 v[12:13], v[12:13], v[24:25], v[16:17] neg_lo:[0,0,1] neg_hi:[0,0,1]
	v_cvt_pk_bf16_f32 v7, v18, v19
	v_cvt_pk_bf16_f32 v3, v12, v13
	ds_read_b64 v[12:13], v0 offset:24
	ds_read_b64 v[16:17], v0 offset:152
	s_waitcnt vmcnt(12)
	s_waitcnt lgkmcnt(2)
	v_readlane_b32 s98, v37, 4
	v_readlane_b32 s99, v37, 5
	v_readlane_b32 vcc_lo, v37, 36
	v_readlane_b32 vcc_hi, v37, 37
	v_pk_mul_f32 v[10:11], v[26:27], v[10:11]
	v_pk_mul_f32 v[14:15], v[26:27], v[14:15]
	v_pk_mul_f32 v[10:11], v[10:11], s[98:99]
	v_pk_mul_f32 v[14:15], v[14:15], vcc
	v_pk_mul_f32 v[18:19], v[10:11], v[42:43]
	s_nop 0
	v_pk_fma_f32 v[18:19], v[14:15], v[38:39], v[18:19]
	v_pk_mul_f32 v[14:15], v[14:15], v[42:43]
	s_nop 0
	v_pk_fma_f32 v[10:11], v[10:11], v[38:39], v[14:15] neg_lo:[0,0,1] neg_hi:[0,0,1]
	v_cvt_pk_bf16_f32 v8, v18, v19
	v_cvt_pk_bf16_f32 v4, v10, v11
	ds_read_b64 v[10:11], v0 offset:32
	ds_read_b64 v[14:15], v0 offset:160
	s_waitcnt lgkmcnt(2)
	v_readlane_b32 s98, v37, 6
	v_readlane_b32 s99, v37, 7
	v_readlane_b32 vcc_lo, v37, 38
	v_readlane_b32 vcc_hi, v37, 39
	v_pk_mul_f32 v[12:13], v[26:27], v[12:13]
	v_pk_mul_f32 v[16:17], v[26:27], v[16:17]
	v_pk_mul_f32 v[12:13], v[12:13], s[98:99]
	v_pk_mul_f32 v[16:17], v[16:17], vcc
	v_pk_mul_f32 v[18:19], v[12:13], v[44:45]
	s_nop 0
	v_pk_fma_f32 v[18:19], v[16:17], v[40:41], v[18:19]
	v_pk_mul_f32 v[16:17], v[16:17], v[44:45]
	s_nop 0
	v_pk_fma_f32 v[12:13], v[12:13], v[40:41], v[16:17] neg_lo:[0,0,1] neg_hi:[0,0,1]
	v_cvt_pk_bf16_f32 v9, v18, v19
	v_cvt_pk_bf16_f32 v5, v12, v13
	ds_read_b64 v[12:13], v0 offset:40
	ds_read_b64 v[16:17], v0 offset:168
	global_store_dwordx4 v[30:31], v[2:5], off offset:-64
	global_store_dwordx4 v[30:31], v[6:9], off
	s_waitcnt vmcnt(12)
	s_waitcnt lgkmcnt(2)
	v_readlane_b32 s98, v37, 8
	v_readlane_b32 s99, v37, 9
	v_readlane_b32 vcc_lo, v37, 40
	v_readlane_b32 vcc_hi, v37, 41
	v_pk_mul_f32 v[10:11], v[26:27], v[10:11]
	v_pk_mul_f32 v[14:15], v[26:27], v[14:15]
	v_pk_mul_f32 v[10:11], v[10:11], s[98:99]
	v_pk_mul_f32 v[14:15], v[14:15], vcc
	v_pk_mul_f32 v[18:19], v[10:11], v[50:51]
	s_nop 0
	v_pk_fma_f32 v[18:19], v[14:15], v[46:47], v[18:19]
	v_pk_mul_f32 v[14:15], v[14:15], v[50:51]
	s_nop 0
	v_pk_fma_f32 v[10:11], v[10:11], v[46:47], v[14:15] neg_lo:[0,0,1] neg_hi:[0,0,1]
	v_cvt_pk_bf16_f32 v6, v18, v19
	v_cvt_pk_bf16_f32 v2, v10, v11
	ds_read_b64 v[10:11], v0 offset:48
	ds_read_b64 v[14:15], v0 offset:176
	s_waitcnt lgkmcnt(2)
	v_readlane_b32 s98, v37, 10
	v_readlane_b32 s99, v37, 11
	v_readlane_b32 vcc_lo, v37, 42
	v_readlane_b32 vcc_hi, v37, 43
	v_pk_mul_f32 v[12:13], v[26:27], v[12:13]
	v_pk_mul_f32 v[16:17], v[26:27], v[16:17]
	v_pk_mul_f32 v[12:13], v[12:13], s[98:99]
	v_pk_mul_f32 v[16:17], v[16:17], vcc
	v_pk_mul_f32 v[18:19], v[12:13], v[52:53]
	s_nop 0
	v_pk_fma_f32 v[18:19], v[16:17], v[48:49], v[18:19]
	v_pk_mul_f32 v[16:17], v[16:17], v[52:53]
	s_nop 0
	v_pk_fma_f32 v[12:13], v[12:13], v[48:49], v[16:17] neg_lo:[0,0,1] neg_hi:[0,0,1]
	v_cvt_pk_bf16_f32 v7, v18, v19
	v_cvt_pk_bf16_f32 v3, v12, v13
	ds_read_b64 v[12:13], v0 offset:56
	ds_read_b64 v[16:17], v0 offset:184
	s_waitcnt vmcnt(10)
	s_waitcnt lgkmcnt(2)
	v_readlane_b32 s98, v37, 12
	v_readlane_b32 s99, v37, 13
	v_readlane_b32 vcc_lo, v37, 44
	v_readlane_b32 vcc_hi, v37, 45
	v_pk_mul_f32 v[10:11], v[26:27], v[10:11]
	v_pk_mul_f32 v[14:15], v[26:27], v[14:15]
	v_pk_mul_f32 v[10:11], v[10:11], s[98:99]
	v_pk_mul_f32 v[14:15], v[14:15], vcc
	v_pk_mul_f32 v[18:19], v[10:11], v[58:59]
	s_nop 0
	v_pk_fma_f32 v[18:19], v[14:15], v[54:55], v[18:19]
	v_pk_mul_f32 v[14:15], v[14:15], v[58:59]
	s_nop 0
	v_pk_fma_f32 v[10:11], v[10:11], v[54:55], v[14:15] neg_lo:[0,0,1] neg_hi:[0,0,1]
	v_cvt_pk_bf16_f32 v8, v18, v19
	v_cvt_pk_bf16_f32 v4, v10, v11
	ds_read_b64 v[10:11], v0 offset:64
	ds_read_b64 v[14:15], v0 offset:192
	s_waitcnt lgkmcnt(2)
	v_readlane_b32 s98, v37, 14
	v_readlane_b32 s99, v37, 15
	v_readlane_b32 vcc_lo, v37, 46
	v_readlane_b32 vcc_hi, v37, 47
	v_pk_mul_f32 v[12:13], v[26:27], v[12:13]
	v_pk_mul_f32 v[16:17], v[26:27], v[16:17]
	v_pk_mul_f32 v[12:13], v[12:13], s[98:99]
	v_pk_mul_f32 v[16:17], v[16:17], vcc
	v_pk_mul_f32 v[18:19], v[12:13], v[60:61]
	s_nop 0
	v_pk_fma_f32 v[18:19], v[16:17], v[56:57], v[18:19]
	v_pk_mul_f32 v[16:17], v[16:17], v[60:61]
	s_nop 0
	v_pk_fma_f32 v[12:13], v[12:13], v[56:57], v[16:17] neg_lo:[0,0,1] neg_hi:[0,0,1]
	v_cvt_pk_bf16_f32 v9, v18, v19
	v_cvt_pk_bf16_f32 v5, v12, v13
	ds_read_b64 v[12:13], v0 offset:72
	ds_read_b64 v[16:17], v0 offset:200
	global_store_dwordx4 v[30:31], v[2:5], off offset:-48
	global_store_dwordx4 v[30:31], v[6:9], off offset:16
	s_waitcnt vmcnt(10)
; DI uint4 pack8(const float* v) { uint4 r; r.x = pk2(v[0], v[1]); r.y = pk2(v[2], v[3]); r.z = pk2(v[4], v[5]); r.w = pk2(v[6], v[7]); return r; }
; DI void qk_epilogue(const float* st  , int m0, const float* __restrict__ gain, float scale, bf16_t* __restrict__ dst, int dstride, int dcol0,
;                     const float* __restrict__ COS, const float* __restrict__ SIN) {
;     ...
;   for (int j = 0; j < 32; j += 8) {
;     float o1[8], o2[8];
; #pragma unroll
;     for (int q = 0; q < 8; ++q) {
;       const float x1 = sp[j + q] * rr * gain[j + q], x2 = sp[j + q + 32] * rr * gain[j + q + 32];
;       const float cs = COS[tok * 32 + j + q], sn = SIN[tok * 32 + j + q];
;       o1[q] = (x1 * cs - x2 * sn) * scale;
;       o2[q] = (x2 * cs + x1 * sn) * scale;
;     }
;     *(uint4*)(dp + j) = pack8(o1);
;     *(uint4*)(dp + j + 32) = pack8(o2);
	s_waitcnt lgkmcnt(2)
	v_readlane_b32 s98, v37, 16
	v_readlane_b32 s99, v37, 17
	v_readlane_b32 vcc_lo, v37, 48
	v_readlane_b32 vcc_hi, v37, 49
	v_pk_mul_f32 v[10:11], v[26:27], v[10:11]
	v_pk_mul_f32 v[14:15], v[26:27], v[14:15]
	v_pk_mul_f32 v[10:11], v[10:11], s[98:99]
	v_pk_mul_f32 v[14:15], v[14:15], vcc
	v_pk_mul_f32 v[18:19], v[10:11], v[66:67]
	s_nop 0
	v_pk_fma_f32 v[18:19], v[14:15], v[62:63], v[18:19]
	v_pk_mul_f32 v[14:15], v[14:15], v[66:67]
	s_nop 0
	v_pk_fma_f32 v[10:11], v[10:11], v[62:63], v[14:15] neg_lo:[0,0,1] neg_hi:[0,0,1]
	v_cvt_pk_bf16_f32 v6, v18, v19
	v_cvt_pk_bf16_f32 v2, v10, v11
	ds_read_b64 v[10:11], v0 offset:80
	ds_read_b64 v[14:15], v0 offset:208
	s_waitcnt lgkmcnt(2)
	v_readlane_b32 s98, v37, 18
	v_readlane_b32 s99, v37, 19
	v_readlane_b32 vcc_lo, v37, 50
	v_readlane_b32 vcc_hi, v37, 51
	v_pk_mul_f32 v[12:13], v[26:27], v[12:13]
	v_pk_mul_f32 v[16:17], v[26:27], v[16:17]
	v_pk_mul_f32 v[12:13], v[12:13], s[98:99]
	v_pk_mul_f32 v[16:17], v[16:17], vcc
	v_pk_mul_f32 v[18:19], v[12:13], v[68:69]
	s_nop 0
	v_pk_fma_f32 v[18:19], v[16:17], v[64:65], v[18:19]
	v_pk_mul_f32 v[16:17], v[16:17], v[68:69]
	s_nop 0
	v_pk_fma_f32 v[12:13], v[12:13], v[64:65], v[16:17] neg_lo:[0,0,1] neg_hi:[0,0,1]
	v_cvt_pk_bf16_f32 v7, v18, v19
	v_cvt_pk_bf16_f32 v3, v12, v13
	ds_read_b64 v[12:13], v0 offset:88
	ds_read_b64 v[16:17], v0 offset:216
	s_waitcnt vmcnt(8)
	s_waitcnt lgkmcnt(2)
	v_readlane_b32 s98, v37, 20
	v_readlane_b32 s99, v37, 21
	v_readlane_b32 vcc_lo, v37, 52
	v_readlane_b32 vcc_hi, v37, 53
	v_pk_mul_f32 v[10:11], v[26:27], v[10:11]
	v_pk_mul_f32 v[14:15], v[26:27], v[14:15]
	v_pk_mul_f32 v[10:11], v[10:11], s[98:99]
	v_pk_mul_f32 v[14:15], v[14:15], vcc
	v_pk_mul_f32 v[18:19], v[10:11], v[74:75]
	s_nop 0
	v_pk_fma_f32 v[18:19], v[14:15], v[70:71], v[18:19]
	v_pk_mul_f32 v[14:15], v[14:15], v[74:75]
	s_nop 0
	v_pk_fma_f32 v[10:11], v[10:11], v[70:71], v[14:15] neg_lo:[0,0,1] neg_hi:[0,0,1]
	v_cvt_pk_bf16_f32 v8, v18, v19
	v_cvt_pk_bf16_f32 v4, v10, v11
	ds_read_b64 v[10:11], v0 offset:96
	ds_read_b64 v[14:15], v0 offset:224
	s_waitcnt lgkmcnt(2)
	v_readlane_b32 s98, v37, 22
	v_readlane_b32 s99, v37, 23
	v_readlane_b32 vcc_lo, v37, 54
	v_readlane_b32 vcc_hi, v37, 55
	v_pk_mul_f32 v[12:13], v[26:27], v[12:13]
	v_pk_mul_f32 v[16:17], v[26:27], v[16:17]
	v_pk_mul_f32 v[12:13], v[12:13], s[98:99]
	v_pk_mul_f32 v[16:17], v[16:17], vcc
	v_pk_mul_f32 v[18:19], v[12:13], v[76:77]
	s_nop 0
	v_pk_fma_f32 v[18:19], v[16:17], v[72:73], v[18:19]
	v_pk_mul_f32 v[16:17], v[16:17], v[76:77]
	s_nop 0
	v_pk_fma_f32 v[12:13], v[12:13], v[72:73], v[16:17] neg_lo:[0,0,1] neg_hi:[0,0,1]
	v_cvt_pk_bf16_f32 v9, v18, v19
	v_cvt_pk_bf16_f32 v5, v12, v13
	ds_read_b64 v[12:13], v0 offset:104
	ds_read_b64 v[16:17], v0 offset:232
	global_store_dwordx4 v[30:31], v[2:5], off offset:-32
	global_store_dwordx4 v[30:31], v[6:9], off offset:32
	s_waitcnt vmcnt(8)
	s_waitcnt lgkmcnt(2)
	v_readlane_b32 s98, v37, 24
	v_readlane_b32 s99, v37, 25
	v_readlane_b32 vcc_lo, v37, 56
	v_readlane_b32 vcc_hi, v37, 57
	v_pk_mul_f32 v[10:11], v[26:27], v[10:11]
	v_pk_mul_f32 v[14:15], v[26:27], v[14:15]
	v_pk_mul_f32 v[10:11], v[10:11], s[98:99]
	v_pk_mul_f32 v[14:15], v[14:15], vcc
	v_pk_mul_f32 v[18:19], v[10:11], v[82:83]
	s_nop 0
	v_pk_fma_f32 v[18:19], v[14:15], v[78:79], v[18:19]
	v_pk_mul_f32 v[14:15], v[14:15], v[82:83]
	s_nop 0
	v_pk_fma_f32 v[10:11], v[10:11], v[78:79], v[14:15] neg_lo:[0,0,1] neg_hi:[0,0,1]
	v_cvt_pk_bf16_f32 v6, v18, v19
	v_cvt_pk_bf16_f32 v2, v10, v11
	ds_read_b64 v[10:11], v0 offset:112
	ds_read_b64 v[14:15], v0 offset:240
	s_waitcnt lgkmcnt(2)
	v_readlane_b32 s98, v37, 26
	v_readlane_b32 s99, v37, 27
	v_readlane_b32 vcc_lo, v37, 58
	v_readlane_b32 vcc_hi, v37, 59
	v_pk_mul_f32 v[12:13], v[26:27], v[12:13]
	v_pk_mul_f32 v[16:17], v[26:27], v[16:17]
	v_pk_mul_f32 v[12:13], v[12:13], s[98:99]
	v_pk_mul_f32 v[16:17], v[16:17], vcc
	v_pk_mul_f32 v[18:19], v[12:13], v[84:85]
	s_nop 0
	v_pk_fma_f32 v[18:19], v[16:17], v[80:81], v[18:19]
	v_pk_mul_f32 v[16:17], v[16:17], v[84:85]
	s_nop 0
	v_pk_fma_f32 v[12:13], v[12:13], v[80:81], v[16:17] neg_lo:[0,0,1] neg_hi:[0,0,1]
	v_cvt_pk_bf16_f32 v7, v18, v19
	v_cvt_pk_bf16_f32 v3, v12, v13
	ds_read_b64 v[12:13], v0 offset:120
	ds_read_b64 v[16:17], v0 offset:248
	s_waitcnt vmcnt(6)
	s_waitcnt lgkmcnt(2)
	v_readlane_b32 s98, v37, 28
	v_readlane_b32 s99, v37, 29
	v_readlane_b32 vcc_lo, v37, 60
	v_readlane_b32 vcc_hi, v37, 61
	v_pk_mul_f32 v[10:11], v[26:27], v[10:11]
	v_pk_mul_f32 v[14:15], v[26:27], v[14:15]
	v_pk_mul_f32 v[10:11], v[10:11], s[98:99]
	v_pk_mul_f32 v[14:15], v[14:15], vcc
	v_pk_mul_f32 v[18:19], v[10:11], v[90:91]
	s_nop 0
	v_pk_fma_f32 v[18:19], v[14:15], v[86:87], v[18:19]
	v_pk_mul_f32 v[14:15], v[14:15], v[90:91]
	s_nop 0
	v_pk_fma_f32 v[10:11], v[10:11], v[86:87], v[14:15] neg_lo:[0,0,1] neg_hi:[0,0,1]
	v_cvt_pk_bf16_f32 v8, v18, v19
	v_cvt_pk_bf16_f32 v4, v10, v11
	s_waitcnt lgkmcnt(0)
	v_readlane_b32 s98, v37, 30
	v_readlane_b32 s99, v37, 31
	v_readlane_b32 vcc_lo, v37, 62
	v_readlane_b32 vcc_hi, v37, 63
	v_pk_mul_f32 v[12:13], v[26:27], v[12:13]
	v_pk_mul_f32 v[16:17], v[26:27], v[16:17]
	v_pk_mul_f32 v[12:13], v[12:13], s[98:99]
	v_pk_mul_f32 v[16:17], v[16:17], vcc
	v_pk_mul_f32 v[18:19], v[12:13], v[92:93]
	s_nop 0
	v_pk_fma_f32 v[18:19], v[16:17], v[88:89], v[18:19]
	v_pk_mul_f32 v[16:17], v[16:17], v[92:93]
	s_nop 0
	v_pk_fma_f32 v[12:13], v[12:13], v[88:89], v[16:17] neg_lo:[0,0,1] neg_hi:[0,0,1]
	v_cvt_pk_bf16_f32 v9, v18, v19
	v_cvt_pk_bf16_f32 v5, v12, v13
	global_store_dwordx4 v[30:31], v[2:5], off offset:-16
	global_store_dwordx4 v[30:31], v[6:9], off offset:48

; DI int otid() { int t = threadIdx.x; asm volatile("" : "+v"(t)); return t; }
; DI void qk_epilogue(const float* st  , int m0, const float* __restrict__ gain, float scale, bf16_t* __restrict__ dst, int dstride, int dcol0,
;                     const float* __restrict__ COS, const float* __restrict__ SIN) {
;   const int tid = otid(), row = tid & 127, hd = tid >> 7;
;   const float* sp = st + row * 132 + hd * 64;
;   float ss = 0.f;
; #pragma unroll 4
;   for (int j = 0; j < 64; j += 4) { const float4 v = *(const float4*)(sp + j); ss += v.x * v.x + v.y * v.y + v.z * v.z + v.w * v.w; }
;   const float rr = rsqrtf(ss * (1.f / 64.f) + 1e-6f);
;   const size_t tok = (size_t)(m0 + row);
;   bf16_t* dp = dst + tok * dstride + dcol0 + hd * 64;
; #pragma unroll 2
;   for (int j = 0; j < 32; j += 8) {
;     float o1[8], o2[8];
; #pragma unroll
;     for (int q = 0; q < 8; ++q) {
;       const float x1 = sp[j + q] * rr * gain[j + q], x2 = sp[j + q + 32] * rr * gain[j + q + 32];
;       const float cs = COS[tok * 32 + j + q], sn = SIN[tok * 32 + j + q];
.LBB0_434:
	s_andn2_b64 vcc, exec, s[28:29]
	s_cbranch_vccnz .LBB0_439
	v_lshlrev_b32_e32 v4, 2, v231
	s_mov_b32 vcc_lo, s57
	s_mov_b32 vcc_hi, s58
	global_load_dword v37, v4, vcc
	s_add_i32 s98, s64, s65
	s_addk_i32 s98, 0x80
	v_and_b32_e32 v2, 0x7f, v216
	v_add_lshl_u32 v2, v2, s98, 7
	v_add_u32_e32 v3, 0x2178000, v2
	v_add_u32_e32 v2, 0x1f78000, v2
	global_load_dwordx4 v[22:25], v2, s[82:83]
	global_load_dwordx4 v[32:35], v3, s[82:83]
	global_load_dwordx4 v[38:41], v2, s[82:83] offset:16
	global_load_dwordx4 v[42:45], v3, s[82:83] offset:16
	global_load_dwordx4 v[46:49], v2, s[82:83] offset:32
	global_load_dwordx4 v[50:53], v3, s[82:83] offset:32
	global_load_dwordx4 v[54:57], v2, s[82:83] offset:48
	global_load_dwordx4 v[58:61], v3, s[82:83] offset:48
	global_load_dwordx4 v[62:65], v2, s[82:83] offset:64
	global_load_dwordx4 v[66:69], v3, s[82:83] offset:64
	global_load_dwordx4 v[70:73], v2, s[82:83] offset:80
	global_load_dwordx4 v[74:77], v3, s[82:83] offset:80
	global_load_dwordx4 v[78:81], v2, s[82:83] offset:96
	global_load_dwordx4 v[82:85], v3, s[82:83] offset:96
	global_load_dwordx4 v[86:89], v2, s[82:83] offset:112
	global_load_dwordx4 v[90:93], v3, s[82:83] offset:112
	v_mov_b32_e32 v2, v216
	s_mov_b32 s9, -4
	v_and_b32_e32 v0, 0x7f, v2
	v_ashrrev_i32_e32 v2, 1, v2
	v_and_b32_e32 v2, 0xffffffc0, v2
	v_lshlrev_b32_e32 v3, 2, v2
	v_mad_u32_u24 v36, v0, s8, v3
	v_mov_b32_e32 v3, 0
	v_mov_b32_e32 v4, v36

; DI uint4 pack8(const float* v) { uint4 r; r.x = pk2(v[0], v[1]); r.y = pk2(v[2], v[3]); r.z = pk2(v[4], v[5]); r.w = pk2(v[6], v[7]); return r; }
; DI void qk_epilogue(const float* st  , int m0, const float* __restrict__ gain, float scale, bf16_t* __restrict__ dst, int dstride, int dcol0,
;                     const float* __restrict__ COS, const float* __restrict__ SIN) {
;     ...
;   for (int j = 0; j < 32; j += 8) {
;     float o1[8], o2[8];
; #pragma unroll
;     for (int q = 0; q < 8; ++q) {
;       const float x1 = sp[j + q] * rr * gain[j + q], x2 = sp[j + q + 32] * rr * gain[j + q + 32];
;       const float cs = COS[tok * 32 + j + q], sn = SIN[tok * 32 + j + q];
;       o1[q] = (x1 * cs - x2 * sn) * scale;
;       o2[q] = (x2 * cs + x1 * sn) * scale;
;     }
;     *(uint4*)(dp + j) = pack8(o1);
;     *(uint4*)(dp + j + 32) = pack8(o2);
;   }
.LBB0_438:
	ds_read_b64 v[10:11], v0
	ds_read_b64 v[14:15], v0 offset:128
	ds_read_b64 v[12:13], v0 offset:8
	ds_read_b64 v[16:17], v0 offset:136
	s_waitcnt vmcnt(14)
	s_waitcnt lgkmcnt(2)
	v_readlane_b32 s98, v37, 0
	v_readlane_b32 s99, v37, 1
	v_readlane_b32 vcc_lo, v37, 32
	v_readlane_b32 vcc_hi, v37, 33
	v_pk_mul_f32 v[10:11], v[26:27], v[10:11]
	v_pk_mul_f32 v[14:15], v[26:27], v[14:15]
	v_pk_mul_f32 v[10:11], v[10:11], s[98:99]
	v_pk_mul_f32 v[14:15], v[14:15], vcc
	v_pk_mul_f32 v[18:19], v[10:11], v[32:33]
	s_nop 0
	v_pk_fma_f32 v[18:19], v[14:15], v[22:23], v[18:19]
	v_pk_mul_f32 v[14:15], v[14:15], v[32:33]
	s_nop 0
	v_pk_fma_f32 v[10:11], v[10:11], v[22:23], v[14:15] neg_lo:[0,0,1] neg_hi:[0,0,1]
	v_pk_mul_f32 v[18:19], v[18:19], s[16:17] op_sel_hi:[1,0]
	v_pk_mul_f32 v[10:11], v[10:11], s[16:17] op_sel_hi:[1,0]
	v_cvt_pk_bf16_f32 v6, v18, v19
	v_cvt_pk_bf16_f32 v2, v10, v11
	ds_read_b64 v[10:11], v0 offset:16
	ds_read_b64 v[14:15], v0 offset:144
	s_waitcnt lgkmcnt(2)
	v_readlane_b32 s98, v37, 2
	v_readlane_b32 s99, v37, 3
	v_readlane_b32 vcc_lo, v37, 34
	v_readlane_b32 vcc_hi, v37, 35
	v_pk_mul_f32 v[12:13], v[26:27], v[12:13]
	v_pk_mul_f32 v[16:17], v[26:27], v[16:17]
	v_pk_mul_f32 v[12:13], v[12:13], s[98:99]
	v_pk_mul_f32 v[16:17], v[16:17], vcc
	v_pk_mul_f32 v[18:19], v[12:13], v[34:35]
	s_nop 0
	v_pk_fma_f32 v[18:19], v[16:17], v[24:25], v[18:19]
	v_pk_mul_f32 v[16:17], v[16:17], v[34:35]
	s_nop 0
	v_pk_fma_f32 v[12:13], v[12:13], v[24:25], v[16:17] neg_lo:[0,0,1] neg_hi:[0,0,1]
	v_pk_mul_f32 v[18:19], v[18:19], s[16:17] op_sel_hi:[1,0]
	v_pk_mul_f32 v[12:13], v[12:13], s[16:17] op_sel_hi:[1,0]
	v_cvt_pk_bf16_f32 v7, v18, v19
	v_cvt_pk_bf16_f32 v3, v12, v13
	ds_read_b64 v[12:13], v0 offset:24
	ds_read_b64 v[16:17], v0 offset:152
	s_waitcnt vmcnt(12)
	s_waitcnt lgkmcnt(2)
	v_readlane_b32 s98, v37, 4
	v_readlane_b32 s99, v37, 5
	v_readlane_b32 vcc_lo, v37, 36
	v_readlane_b32 vcc_hi, v37, 37
	v_pk_mul_f32 v[10:11], v[26:27], v[10:11]
	v_pk_mul_f32 v[14:15], v[26:27], v[14:15]
	v_pk_mul_f32 v[10:11], v[10:11], s[98:99]
	v_pk_mul_f32 v[14:15], v[14:15], vcc
	v_pk_mul_f32 v[18:19], v[10:11], v[42:43]
	s_nop 0
	v_pk_fma_f32 v[18:19], v[14:15], v[38:39], v[18:19]
	v_pk_mul_f32 v[14:15], v[14:15], v[42:43]
	s_nop 0
	v_pk_fma_f32 v[10:11], v[10:11], v[38:39], v[14:15] neg_lo:[0,0,1] neg_hi:[0,0,1]
	v_pk_mul_f32 v[18:19], v[18:19], s[16:17] op_sel_hi:[1,0]
	v_pk_mul_f32 v[10:11], v[10:11], s[16:17] op_sel_hi:[1,0]
	v_cvt_pk_bf16_f32 v8, v18, v19
	v_cvt_pk_bf16_f32 v4, v10, v11
	ds_read_b64 v[10:11], v0 offset:32
	ds_read_b64 v[14:15], v0 offset:160
	s_waitcnt lgkmcnt(2)
	v_readlane_b32 s98, v37, 6
	v_readlane_b32 s99, v37, 7
	v_readlane_b32 vcc_lo, v37, 38
	v_readlane_b32 vcc_hi, v37, 39
	v_pk_mul_f32 v[12:13], v[26:27], v[12:13]
	v_pk_mul_f32 v[16:17], v[26:27], v[16:17]
	v_pk_mul_f32 v[12:13], v[12:13], s[98:99]
	v_pk_mul_f32 v[16:17], v[16:17], vcc
	v_pk_mul_f32 v[18:19], v[12:13], v[44:45]
	s_nop 0
	v_pk_fma_f32 v[18:19], v[16:17], v[40:41], v[18:19]
	v_pk_mul_f32 v[16:17], v[16:17], v[44:45]
	s_nop 0
	v_pk_fma_f32 v[12:13], v[12:13], v[40:41], v[16:17] neg_lo:[0,0,1] neg_hi:[0,0,1]
	v_pk_mul_f32 v[18:19], v[18:19], s[16:17] op_sel_hi:[1,0]
	v_pk_mul_f32 v[12:13], v[12:13], s[16:17] op_sel_hi:[1,0]
	v_cvt_pk_bf16_f32 v9, v18, v19
	v_cvt_pk_bf16_f32 v5, v12, v13
	ds_read_b64 v[12:13], v0 offset:40
	ds_read_b64 v[16:17], v0 offset:168
	global_store_dwordx4 v[30:31], v[2:5], off offset:-64
	global_store_dwordx4 v[30:31], v[6:9], off
	s_waitcnt vmcnt(12)
	s_waitcnt lgkmcnt(2)
	v_readlane_b32 s98, v37, 8
	v_readlane_b32 s99, v37, 9
	v_readlane_b32 vcc_lo, v37, 40
	v_readlane_b32 vcc_hi, v37, 41
	v_pk_mul_f32 v[10:11], v[26:27], v[10:11]
	v_pk_mul_f32 v[14:15], v[26:27], v[14:15]
	v_pk_mul_f32 v[10:11], v[10:11], s[98:99]
	v_pk_mul_f32 v[14:15], v[14:15], vcc
	v_pk_mul_f32 v[18:19], v[10:11], v[50:51]
	s_nop 0
	v_pk_fma_f32 v[18:19], v[14:15], v[46:47], v[18:19]
	v_pk_mul_f32 v[14:15], v[14:15], v[50:51]
	s_nop 0
	v_pk_fma_f32 v[10:11], v[10:11], v[46:47], v[14:15] neg_lo:[0,0,1] neg_hi:[0,0,1]
	v_pk_mul_f32 v[18:19], v[18:19], s[16:17] op_sel_hi:[1,0]
	v_pk_mul_f32 v[10:11], v[10:11], s[16:17] op_sel_hi:[1,0]
	v_cvt_pk_bf16_f32 v6, v18, v19
	v_cvt_pk_bf16_f32 v2, v10, v11
	ds_read_b64 v[10:11], v0 offset:48
	ds_read_b64 v[14:15], v0 offset:176
	s_waitcnt lgkmcnt(2)
	v_readlane_b32 s98, v37, 10
	v_readlane_b32 s99, v37, 11
	v_readlane_b32 vcc_lo, v37, 42
	v_readlane_b32 vcc_hi, v37, 43
	v_pk_mul_f32 v[12:13], v[26:27], v[12:13]
	v_pk_mul_f32 v[16:17], v[26:27], v[16:17]
	v_pk_mul_f32 v[12:13], v[12:13], s[98:99]
	v_pk_mul_f32 v[16:17], v[16:17], vcc
	v_pk_mul_f32 v[18:19], v[12:13], v[52:53]
	s_nop 0
	v_pk_fma_f32 v[18:19], v[16:17], v[48:49], v[18:19]
	v_pk_mul_f32 v[16:17], v[16:17], v[52:53]
	s_nop 0
	v_pk_fma_f32 v[12:13], v[12:13], v[48:49], v[16:17] neg_lo:[0,0,1] neg_hi:[0,0,1]
	v_pk_mul_f32 v[18:19], v[18:19], s[16:17] op_sel_hi:[1,0]
	v_pk_mul_f32 v[12:13], v[12:13], s[16:17] op_sel_hi:[1,0]
	v_cvt_pk_bf16_f32 v7, v18, v19
	v_cvt_pk_bf16_f32 v3, v12, v13
	ds_read_b64 v[12:13], v0 offset:56
	ds_read_b64 v[16:17], v0 offset:184
	s_waitcnt vmcnt(10)
	s_waitcnt lgkmcnt(2)
	v_readlane_b32 s98, v37, 12
	v_readlane_b32 s99, v37, 13
	v_readlane_b32 vcc_lo, v37, 44
	v_readlane_b32 vcc_hi, v37, 45
	v_pk_mul_f32 v[10:11], v[26:27], v[10:11]
	v_pk_mul_f32 v[14:15], v[26:27], v[14:15]
	v_pk_mul_f32 v[10:11], v[10:11], s[98:99]
	v_pk_mul_f32 v[14:15], v[14:15], vcc
	v_pk_mul_f32 v[18:19], v[10:11], v[58:59]
	s_nop 0
	v_pk_fma_f32 v[18:19], v[14:15], v[54:55], v[18:19]
	v_pk_mul_f32 v[14:15], v[14:15], v[58:59]
	s_nop 0
	v_pk_fma_f32 v[10:11], v[10:11], v[54:55], v[14:15] neg_lo:[0,0,1] neg_hi:[0,0,1]
	v_pk_mul_f32 v[18:19], v[18:19], s[16:17] op_sel_hi:[1,0]
	v_pk_mul_f32 v[10:11], v[10:11], s[16:17] op_sel_hi:[1,0]
	v_cvt_pk_bf16_f32 v8, v18, v19
	v_cvt_pk_bf16_f32 v4, v10, v11
	ds_read_b64 v[10:11], v0 offset:64
	ds_read_b64 v[14:15], v0 offset:192
	s_waitcnt lgkmcnt(2)
; DI uint4 pack8(const float* v) { uint4 r; r.x = pk2(v[0], v[1]); r.y = pk2(v[2], v[3]); r.z = pk2(v[4], v[5]); r.w = pk2(v[6], v[7]); return r; }
; DI void qk_epilogue(const float* st  , int m0, const float* __restrict__ gain, float scale, bf16_t* __restrict__ dst, int dstride, int dcol0,
;                     const float* __restrict__ COS, const float* __restrict__ SIN) {
;     ...
;   for (int j = 0; j < 32; j += 8) {
;     float o1[8], o2[8];
; #pragma unroll
;     for (int q = 0; q < 8; ++q) {
;       const float x1 = sp[j + q] * rr * gain[j + q], x2 = sp[j + q + 32] * rr * gain[j + q + 32];
;       const float cs = COS[tok * 32 + j + q], sn = SIN[tok * 32 + j + q];
;       o1[q] = (x1 * cs - x2 * sn) * scale;
;       o2[q] = (x2 * cs + x1 * sn) * scale;
;     }
;     *(uint4*)(dp + j) = pack8(o1);
;     *(uint4*)(dp + j + 32) = pack8(o2);
;   }
	v_readlane_b32 s98, v37, 14
	v_readlane_b32 s99, v37, 15
	v_readlane_b32 vcc_lo, v37, 46
	v_readlane_b32 vcc_hi, v37, 47
	v_pk_mul_f32 v[12:13], v[26:27], v[12:13]
	v_pk_mul_f32 v[16:17], v[26:27], v[16:17]
	v_pk_mul_f32 v[12:13], v[12:13], s[98:99]
	v_pk_mul_f32 v[16:17], v[16:17], vcc
	v_pk_mul_f32 v[18:19], v[12:13], v[60:61]
	s_nop 0
	v_pk_fma_f32 v[18:19], v[16:17], v[56:57], v[18:19]
	v_pk_mul_f32 v[16:17], v[16:17], v[60:61]
	s_nop 0
	v_pk_fma_f32 v[12:13], v[12:13], v[56:57], v[16:17] neg_lo:[0,0,1] neg_hi:[0,0,1]
	v_pk_mul_f32 v[18:19], v[18:19], s[16:17] op_sel_hi:[1,0]
	v_pk_mul_f32 v[12:13], v[12:13], s[16:17] op_sel_hi:[1,0]
	v_cvt_pk_bf16_f32 v9, v18, v19
	v_cvt_pk_bf16_f32 v5, v12, v13
	ds_read_b64 v[12:13], v0 offset:72
	ds_read_b64 v[16:17], v0 offset:200
	global_store_dwordx4 v[30:31], v[2:5], off offset:-48
	global_store_dwordx4 v[30:31], v[6:9], off offset:16
	s_waitcnt vmcnt(10)
	s_waitcnt lgkmcnt(2)
	v_readlane_b32 s98, v37, 16
	v_readlane_b32 s99, v37, 17
	v_readlane_b32 vcc_lo, v37, 48
	v_readlane_b32 vcc_hi, v37, 49
	v_pk_mul_f32 v[10:11], v[26:27], v[10:11]
	v_pk_mul_f32 v[14:15], v[26:27], v[14:15]
	v_pk_mul_f32 v[10:11], v[10:11], s[98:99]
	v_pk_mul_f32 v[14:15], v[14:15], vcc
	v_pk_mul_f32 v[18:19], v[10:11], v[66:67]
	s_nop 0
	v_pk_fma_f32 v[18:19], v[14:15], v[62:63], v[18:19]
	v_pk_mul_f32 v[14:15], v[14:15], v[66:67]
	s_nop 0
	v_pk_fma_f32 v[10:11], v[10:11], v[62:63], v[14:15] neg_lo:[0,0,1] neg_hi:[0,0,1]
	v_pk_mul_f32 v[18:19], v[18:19], s[16:17] op_sel_hi:[1,0]
	v_pk_mul_f32 v[10:11], v[10:11], s[16:17] op_sel_hi:[1,0]
	v_cvt_pk_bf16_f32 v6, v18, v19
	v_cvt_pk_bf16_f32 v2, v10, v11
	ds_read_b64 v[10:11], v0 offset:80
	ds_read_b64 v[14:15], v0 offset:208
	s_waitcnt lgkmcnt(2)
	v_readlane_b32 s98, v37, 18
	v_readlane_b32 s99, v37, 19
	v_readlane_b32 vcc_lo, v37, 50
	v_readlane_b32 vcc_hi, v37, 51
	v_pk_mul_f32 v[12:13], v[26:27], v[12:13]
	v_pk_mul_f32 v[16:17], v[26:27], v[16:17]
	v_pk_mul_f32 v[12:13], v[12:13], s[98:99]
	v_pk_mul_f32 v[16:17], v[16:17], vcc
	v_pk_mul_f32 v[18:19], v[12:13], v[68:69]
	s_nop 0
	v_pk_fma_f32 v[18:19], v[16:17], v[64:65], v[18:19]
	v_pk_mul_f32 v[16:17], v[16:17], v[68:69]
	s_nop 0
	v_pk_fma_f32 v[12:13], v[12:13], v[64:65], v[16:17] neg_lo:[0,0,1] neg_hi:[0,0,1]
	v_pk_mul_f32 v[18:19], v[18:19], s[16:17] op_sel_hi:[1,0]
	v_pk_mul_f32 v[12:13], v[12:13], s[16:17] op_sel_hi:[1,0]
	v_cvt_pk_bf16_f32 v7, v18, v19
	v_cvt_pk_bf16_f32 v3, v12, v13
	ds_read_b64 v[12:13], v0 offset:88
	ds_read_b64 v[16:17], v0 offset:216
	s_waitcnt vmcnt(8)
	s_waitcnt lgkmcnt(2)
	v_readlane_b32 s98, v37, 20
	v_readlane_b32 s99, v37, 21
	v_readlane_b32 vcc_lo, v37, 52
	v_readlane_b32 vcc_hi, v37, 53
	v_pk_mul_f32 v[10:11], v[26:27], v[10:11]
	v_pk_mul_f32 v[14:15], v[26:27], v[14:15]
	v_pk_mul_f32 v[10:11], v[10:11], s[98:99]
	v_pk_mul_f32 v[14:15], v[14:15], vcc
	v_pk_mul_f32 v[18:19], v[10:11], v[74:75]
	s_nop 0
	v_pk_fma_f32 v[18:19], v[14:15], v[70:71], v[18:19]
	v_pk_mul_f32 v[14:15], v[14:15], v[74:75]
	s_nop 0
	v_pk_fma_f32 v[10:11], v[10:11], v[70:71], v[14:15] neg_lo:[0,0,1] neg_hi:[0,0,1]
	v_pk_mul_f32 v[18:19], v[18:19], s[16:17] op_sel_hi:[1,0]
	v_pk_mul_f32 v[10:11], v[10:11], s[16:17] op_sel_hi:[1,0]
	v_cvt_pk_bf16_f32 v8, v18, v19
	v_cvt_pk_bf16_f32 v4, v10, v11
	ds_read_b64 v[10:11], v0 offset:96
	ds_read_b64 v[14:15], v0 offset:224
	s_waitcnt lgkmcnt(2)
; DI uint4 pack8(const float* v) { uint4 r; r.x = pk2(v[0], v[1]); r.y = pk2(v[2], v[3]); r.z = pk2(v[4], v[5]); r.w = pk2(v[6], v[7]); return r; }
; DI void qk_epilogue(const float* st  , int m0, const float* __restrict__ gain, float scale, bf16_t* __restrict__ dst, int dstride, int dcol0,
;                     const float* __restrict__ COS, const float* __restrict__ SIN) {
;     ...
;   for (int j = 0; j < 32; j += 8) {
;     float o1[8], o2[8];
; #pragma unroll
;     for (int q = 0; q < 8; ++q) {
;       const float x1 = sp[j + q] * rr * gain[j + q], x2 = sp[j + q + 32] * rr * gain[j + q + 32];
;       const float cs = COS[tok * 32 + j + q], sn = SIN[tok * 32 + j + q];
;       o1[q] = (x1 * cs - x2 * sn) * scale;
;       o2[q] = (x2 * cs + x1 * sn) * scale;
;     }
;     *(uint4*)(dp + j) = pack8(o1);
;     *(uint4*)(dp + j + 32) = pack8(o2);
;   }
	v_readlane_b32 s98, v37, 22
	v_readlane_b32 s99, v37, 23
	v_readlane_b32 vcc_lo, v37, 54
	v_readlane_b32 vcc_hi, v37, 55
	v_pk_mul_f32 v[12:13], v[26:27], v[12:13]
	v_pk_mul_f32 v[16:17], v[26:27], v[16:17]
	v_pk_mul_f32 v[12:13], v[12:13], s[98:99]
	v_pk_mul_f32 v[16:17], v[16:17], vcc
	v_pk_mul_f32 v[18:19], v[12:13], v[76:77]
	s_nop 0
	v_pk_fma_f32 v[18:19], v[16:17], v[72:73], v[18:19]
	v_pk_mul_f32 v[16:17], v[16:17], v[76:77]
	s_nop 0
	v_pk_fma_f32 v[12:13], v[12:13], v[72:73], v[16:17] neg_lo:[0,0,1] neg_hi:[0,0,1]
	v_pk_mul_f32 v[18:19], v[18:19], s[16:17] op_sel_hi:[1,0]
	v_pk_mul_f32 v[12:13], v[12:13], s[16:17] op_sel_hi:[1,0]
	v_cvt_pk_bf16_f32 v9, v18, v19
	v_cvt_pk_bf16_f32 v5, v12, v13
	ds_read_b64 v[12:13], v0 offset:104
	ds_read_b64 v[16:17], v0 offset:232
	global_store_dwordx4 v[30:31], v[2:5], off offset:-32
	global_store_dwordx4 v[30:31], v[6:9], off offset:32
	s_waitcnt vmcnt(8)
	s_waitcnt lgkmcnt(2)
	v_readlane_b32 s98, v37, 24
	v_readlane_b32 s99, v37, 25
	v_readlane_b32 vcc_lo, v37, 56
	v_readlane_b32 vcc_hi, v37, 57
	v_pk_mul_f32 v[10:11], v[26:27], v[10:11]
	v_pk_mul_f32 v[14:15], v[26:27], v[14:15]
	v_pk_mul_f32 v[10:11], v[10:11], s[98:99]
	v_pk_mul_f32 v[14:15], v[14:15], vcc
	v_pk_mul_f32 v[18:19], v[10:11], v[82:83]
	s_nop 0
	v_pk_fma_f32 v[18:19], v[14:15], v[78:79], v[18:19]
	v_pk_mul_f32 v[14:15], v[14:15], v[82:83]
	s_nop 0
	v_pk_fma_f32 v[10:11], v[10:11], v[78:79], v[14:15] neg_lo:[0,0,1] neg_hi:[0,0,1]
	v_pk_mul_f32 v[18:19], v[18:19], s[16:17] op_sel_hi:[1,0]
	v_pk_mul_f32 v[10:11], v[10:11], s[16:17] op_sel_hi:[1,0]
	v_cvt_pk_bf16_f32 v6, v18, v19
	v_cvt_pk_bf16_f32 v2, v10, v11
	ds_read_b64 v[10:11], v0 offset:112
	ds_read_b64 v[14:15], v0 offset:240
	s_waitcnt lgkmcnt(2)
	v_readlane_b32 s98, v37, 26
	v_readlane_b32 s99, v37, 27
	v_readlane_b32 vcc_lo, v37, 58
	v_readlane_b32 vcc_hi, v37, 59
	v_pk_mul_f32 v[12:13], v[26:27], v[12:13]
	v_pk_mul_f32 v[16:17], v[26:27], v[16:17]
	v_pk_mul_f32 v[12:13], v[12:13], s[98:99]
	v_pk_mul_f32 v[16:17], v[16:17], vcc
	v_pk_mul_f32 v[18:19], v[12:13], v[84:85]
	s_nop 0
	v_pk_fma_f32 v[18:19], v[16:17], v[80:81], v[18:19]
	v_pk_mul_f32 v[16:17], v[16:17], v[84:85]
	s_nop 0
	v_pk_fma_f32 v[12:13], v[12:13], v[80:81], v[16:17] neg_lo:[0,0,1] neg_hi:[0,0,1]
	v_pk_mul_f32 v[18:19], v[18:19], s[16:17] op_sel_hi:[1,0]
	v_pk_mul_f32 v[12:13], v[12:13], s[16:17] op_sel_hi:[1,0]
	v_cvt_pk_bf16_f32 v7, v18, v19
	v_cvt_pk_bf16_f32 v3, v12, v13
	ds_read_b64 v[12:13], v0 offset:120
	ds_read_b64 v[16:17], v0 offset:248
	s_waitcnt vmcnt(6)
	s_waitcnt lgkmcnt(2)
	v_readlane_b32 s98, v37, 28
	v_readlane_b32 s99, v37, 29
	v_readlane_b32 vcc_lo, v37, 60
	v_readlane_b32 vcc_hi, v37, 61
	v_pk_mul_f32 v[10:11], v[26:27], v[10:11]
	v_pk_mul_f32 v[14:15], v[26:27], v[14:15]
	v_pk_mul_f32 v[10:11], v[10:11], s[98:99]
	v_pk_mul_f32 v[14:15], v[14:15], vcc
	v_pk_mul_f32 v[18:19], v[10:11], v[90:91]
	s_nop 0
	v_pk_fma_f32 v[18:19], v[14:15], v[86:87], v[18:19]
	v_pk_mul_f32 v[14:15], v[14:15], v[90:91]
	s_nop 0
	v_pk_fma_f32 v[10:11], v[10:11], v[86:87], v[14:15] neg_lo:[0,0,1] neg_hi:[0,0,1]
	v_pk_mul_f32 v[18:19], v[18:19], s[16:17] op_sel_hi:[1,0]
	v_pk_mul_f32 v[10:11], v[10:11], s[16:17] op_sel_hi:[1,0]
	v_cvt_pk_bf16_f32 v8, v18, v19
	v_cvt_pk_bf16_f32 v4, v10, v11
	s_waitcnt lgkmcnt(0)
	v_readlane_b32 s98, v37, 30
	v_readlane_b32 s99, v37, 31
	v_readlane_b32 vcc_lo, v37, 62
	v_readlane_b32 vcc_hi, v37, 63
	v_pk_mul_f32 v[12:13], v[26:27], v[12:13]
	v_pk_mul_f32 v[16:17], v[26:27], v[16:17]
	v_pk_mul_f32 v[12:13], v[12:13], s[98:99]
	v_pk_mul_f32 v[16:17], v[16:17], vcc
	v_pk_mul_f32 v[18:19], v[12:13], v[92:93]
	s_nop 0
	v_pk_fma_f32 v[18:19], v[16:17], v[88:89], v[18:19]
	v_pk_mul_f32 v[16:17], v[16:17], v[92:93]
	s_nop 0
	v_pk_fma_f32 v[12:13], v[12:13], v[88:89], v[16:17] neg_lo:[0,0,1] neg_hi:[0,0,1]
	v_pk_mul_f32 v[18:19], v[18:19], s[16:17] op_sel_hi:[1,0]
	v_pk_mul_f32 v[12:13], v[12:13], s[16:17] op_sel_hi:[1,0]
	v_cvt_pk_bf16_f32 v9, v18, v19
	v_cvt_pk_bf16_f32 v5, v12, v13
	global_store_dwordx4 v[30:31], v[2:5], off offset:-16
	global_store_dwordx4 v[30:31], v[6:9], off offset:48

; DI int otid() { int t = threadIdx.x; asm volatile("" : "+v"(t)); return t; }
; DI void qk_epilogue(const float* st  , int m0, const float* __restrict__ gain, float scale, bf16_t* __restrict__ dst, int dstride, int dcol0,
;                     const float* __restrict__ COS, const float* __restrict__ SIN) {
;   const int tid = otid(), row = tid & 127, hd = tid >> 7;
;   const float* sp = st + row * 132 + hd * 64;
;   float ss = 0.f;
; #pragma unroll 4
;   for (int j = 0; j < 64; j += 4) { const float4 v = *(const float4*)(sp + j); ss += v.x * v.x + v.y * v.y + v.z * v.z + v.w * v.w; }
;   const float rr = rsqrtf(ss * (1.f / 64.f) + 1e-6f);
;   const size_t tok = (size_t)(m0 + row);
;   bf16_t* dp = dst + tok * dstride + dcol0 + hd * 64;
; #pragma unroll 2
;   for (int j = 0; j < 32; j += 8) {
;     float o1[8], o2[8];
; #pragma unroll
;     for (int q = 0; q < 8; ++q) {
;       const float x1 = sp[j + q] * rr * gain[j + q], x2 = sp[j + q + 32] * rr * gain[j + q + 32];
;       const float cs = COS[tok * 32 + j + q], sn = SIN[tok * 32 + j + q];
.LBB0_444:
	s_mov_b32 s42, s27
	s_andn2_b64 vcc, exec, s[28:29]
	s_mov_b32 s37, 0x9f78000
	s_cbranch_vccnz .LBB0_449
	v_lshlrev_b32_e32 v4, 2, v231
	s_mov_b32 vcc_lo, s53
	s_mov_b32 vcc_hi, s54
	global_load_dword v94, v4, vcc
	s_add_i32 s98, s64, s65
	s_addk_i32 s98, 0x80
	v_and_b32_e32 v2, 0x7f, v216
	v_add_lshl_u32 v2, v2, s98, 7
	v_add_u32_e32 v3, 0x2178000, v2
	v_add_u32_e32 v2, 0x1f78000, v2
	global_load_dwordx4 v[22:25], v2, s[82:83]
	global_load_dwordx4 v[26:29], v3, s[82:83]
	global_load_dwordx4 v[36:39], v2, s[82:83] offset:16
	global_load_dwordx4 v[40:43], v3, s[82:83] offset:16
	global_load_dwordx4 v[46:49], v2, s[82:83] offset:32
	global_load_dwordx4 v[50:53], v3, s[82:83] offset:32
	global_load_dwordx4 v[54:57], v2, s[82:83] offset:48
	global_load_dwordx4 v[58:61], v3, s[82:83] offset:48
	global_load_dwordx4 v[62:65], v2, s[82:83] offset:64
	global_load_dwordx4 v[66:69], v3, s[82:83] offset:64
	global_load_dwordx4 v[70:73], v2, s[82:83] offset:80
	global_load_dwordx4 v[74:77], v3, s[82:83] offset:80
	global_load_dwordx4 v[78:81], v2, s[82:83] offset:96
	global_load_dwordx4 v[82:85], v3, s[82:83] offset:96
	global_load_dwordx4 v[86:89], v2, s[82:83] offset:112
	global_load_dwordx4 v[90:93], v3, s[82:83] offset:112
	v_mov_b32_e32 v2, v216
	s_mov_b32 s9, -4
	v_and_b32_e32 v0, 0x7f, v2
	v_ashrrev_i32_e32 v2, 1, v2
	v_and_b32_e32 v2, 0xffffffc0, v2
	v_lshlrev_b32_e32 v3, 2, v2
	v_mad_u32_u24 v44, v0, s8, v3
	v_mov_b32_e32 v3, 0
	v_mov_b32_e32 v4, v44

; DI uint4 pack8(const float* v) { uint4 r; r.x = pk2(v[0], v[1]); r.y = pk2(v[2], v[3]); r.z = pk2(v[4], v[5]); r.w = pk2(v[6], v[7]); return r; }
; DI void qk_epilogue(const float* st  , int m0, const float* __restrict__ gain, float scale, bf16_t* __restrict__ dst, int dstride, int dcol0,
;                     const float* __restrict__ COS, const float* __restrict__ SIN) {
;     ...
;   for (int j = 0; j < 32; j += 8) {
;     float o1[8], o2[8];
; #pragma unroll
;     for (int q = 0; q < 8; ++q) {
;       const float x1 = sp[j + q] * rr * gain[j + q], x2 = sp[j + q + 32] * rr * gain[j + q + 32];
;       const float cs = COS[tok * 32 + j + q], sn = SIN[tok * 32 + j + q];
;       o1[q] = (x1 * cs - x2 * sn) * scale;
;       o2[q] = (x2 * cs + x1 * sn) * scale;
;     }
;     *(uint4*)(dp + j) = pack8(o1);
;     *(uint4*)(dp + j + 32) = pack8(o2);
;   }
.LBB0_448:
	v_lshl_add_u64 v[32:33], s[82:83], 0, v[32:33]
	v_add_co_u32_e32 v32, vcc, s37, v32
	v_addc_co_u32_e32 v33, vcc, 0, v33, vcc
	ds_read_b64 v[10:11], v45
	ds_read_b64 v[14:15], v45 offset:128
	ds_read_b64 v[12:13], v45 offset:8
	ds_read_b64 v[16:17], v45 offset:136
	s_waitcnt vmcnt(14)
	s_waitcnt lgkmcnt(2)
	v_readlane_b32 s98, v94, 0
	v_readlane_b32 s99, v94, 1
	v_readlane_b32 vcc_lo, v94, 32
	v_readlane_b32 vcc_hi, v94, 33
	v_pk_mul_f32 v[10:11], v[30:31], v[10:11]
	v_pk_mul_f32 v[14:15], v[30:31], v[14:15]
	v_pk_mul_f32 v[10:11], v[10:11], s[98:99]
	v_pk_mul_f32 v[14:15], v[14:15], vcc
	v_pk_mul_f32 v[18:19], v[10:11], v[26:27]
	s_nop 0
	v_pk_fma_f32 v[18:19], v[14:15], v[22:23], v[18:19]
	v_pk_mul_f32 v[14:15], v[14:15], v[26:27]
	s_nop 0
	v_pk_fma_f32 v[10:11], v[10:11], v[22:23], v[14:15] neg_lo:[0,0,1] neg_hi:[0,0,1]
	v_cvt_pk_bf16_f32 v6, v18, v19
	v_cvt_pk_bf16_f32 v2, v10, v11
	ds_read_b64 v[10:11], v45 offset:16
	ds_read_b64 v[14:15], v45 offset:144
	s_waitcnt lgkmcnt(2)
	v_readlane_b32 s98, v94, 2
	v_readlane_b32 s99, v94, 3
	v_readlane_b32 vcc_lo, v94, 34
	v_readlane_b32 vcc_hi, v94, 35
	v_pk_mul_f32 v[12:13], v[30:31], v[12:13]
	v_pk_mul_f32 v[16:17], v[30:31], v[16:17]
	v_pk_mul_f32 v[12:13], v[12:13], s[98:99]
	v_pk_mul_f32 v[16:17], v[16:17], vcc
	v_pk_mul_f32 v[18:19], v[12:13], v[28:29]
	s_nop 0
	v_pk_fma_f32 v[18:19], v[16:17], v[24:25], v[18:19]
	v_pk_mul_f32 v[16:17], v[16:17], v[28:29]
	s_nop 0
	v_pk_fma_f32 v[12:13], v[12:13], v[24:25], v[16:17] neg_lo:[0,0,1] neg_hi:[0,0,1]
	v_cvt_pk_bf16_f32 v7, v18, v19
	v_cvt_pk_bf16_f32 v3, v12, v13
	ds_read_b64 v[12:13], v45 offset:24
	ds_read_b64 v[16:17], v45 offset:152
	s_waitcnt vmcnt(12)
	s_waitcnt lgkmcnt(2)
	v_readlane_b32 s98, v94, 4
	v_readlane_b32 s99, v94, 5
	v_readlane_b32 vcc_lo, v94, 36
	v_readlane_b32 vcc_hi, v94, 37
	v_pk_mul_f32 v[10:11], v[30:31], v[10:11]
	v_pk_mul_f32 v[14:15], v[30:31], v[14:15]
	v_pk_mul_f32 v[10:11], v[10:11], s[98:99]
	v_pk_mul_f32 v[14:15], v[14:15], vcc
	v_pk_mul_f32 v[18:19], v[10:11], v[40:41]
	s_nop 0
	v_pk_fma_f32 v[18:19], v[14:15], v[36:37], v[18:19]
	v_pk_mul_f32 v[14:15], v[14:15], v[40:41]
	s_nop 0
	v_pk_fma_f32 v[10:11], v[10:11], v[36:37], v[14:15] neg_lo:[0,0,1] neg_hi:[0,0,1]
	v_cvt_pk_bf16_f32 v8, v18, v19
	v_cvt_pk_bf16_f32 v4, v10, v11
	ds_read_b64 v[10:11], v45 offset:32
	ds_read_b64 v[14:15], v45 offset:160
	s_waitcnt lgkmcnt(2)
	v_readlane_b32 s98, v94, 6
	v_readlane_b32 s99, v94, 7
	v_readlane_b32 vcc_lo, v94, 38
	v_readlane_b32 vcc_hi, v94, 39
	v_pk_mul_f32 v[12:13], v[30:31], v[12:13]
	v_pk_mul_f32 v[16:17], v[30:31], v[16:17]
	v_pk_mul_f32 v[12:13], v[12:13], s[98:99]
	v_pk_mul_f32 v[16:17], v[16:17], vcc
	v_pk_mul_f32 v[18:19], v[12:13], v[42:43]
	s_nop 0
	v_pk_fma_f32 v[18:19], v[16:17], v[38:39], v[18:19]
	v_pk_mul_f32 v[16:17], v[16:17], v[42:43]
	s_nop 0
	v_pk_fma_f32 v[12:13], v[12:13], v[38:39], v[16:17] neg_lo:[0,0,1] neg_hi:[0,0,1]
	v_cvt_pk_bf16_f32 v9, v18, v19
	v_cvt_pk_bf16_f32 v5, v12, v13
	ds_read_b64 v[12:13], v45 offset:40
	ds_read_b64 v[16:17], v45 offset:168
	global_store_dwordx4 v[32:33], v[2:5], off
	global_store_dwordx4 v[32:33], v[6:9], off offset:64
	s_waitcnt vmcnt(12)
	s_waitcnt lgkmcnt(2)
	v_readlane_b32 s98, v94, 8
	v_readlane_b32 s99, v94, 9
	v_readlane_b32 vcc_lo, v94, 40
	v_readlane_b32 vcc_hi, v94, 41
	v_pk_mul_f32 v[10:11], v[30:31], v[10:11]
	v_pk_mul_f32 v[14:15], v[30:31], v[14:15]
	v_pk_mul_f32 v[10:11], v[10:11], s[98:99]
	v_pk_mul_f32 v[14:15], v[14:15], vcc
	v_pk_mul_f32 v[18:19], v[10:11], v[50:51]
	s_nop 0
	v_pk_fma_f32 v[18:19], v[14:15], v[46:47], v[18:19]
	v_pk_mul_f32 v[14:15], v[14:15], v[50:51]
	s_nop 0
	v_pk_fma_f32 v[10:11], v[10:11], v[46:47], v[14:15] neg_lo:[0,0,1] neg_hi:[0,0,1]
	v_cvt_pk_bf16_f32 v6, v18, v19
	v_cvt_pk_bf16_f32 v2, v10, v11
	ds_read_b64 v[10:11], v45 offset:48
	ds_read_b64 v[14:15], v45 offset:176
	s_waitcnt lgkmcnt(2)
	v_readlane_b32 s98, v94, 10
	v_readlane_b32 s99, v94, 11
	v_readlane_b32 vcc_lo, v94, 42
	v_readlane_b32 vcc_hi, v94, 43
	v_pk_mul_f32 v[12:13], v[30:31], v[12:13]
	v_pk_mul_f32 v[16:17], v[30:31], v[16:17]
	v_pk_mul_f32 v[12:13], v[12:13], s[98:99]
	v_pk_mul_f32 v[16:17], v[16:17], vcc
	v_pk_mul_f32 v[18:19], v[12:13], v[52:53]
	s_nop 0
	v_pk_fma_f32 v[18:19], v[16:17], v[48:49], v[18:19]
	v_pk_mul_f32 v[16:17], v[16:17], v[52:53]
	s_nop 0
	v_pk_fma_f32 v[12:13], v[12:13], v[48:49], v[16:17] neg_lo:[0,0,1] neg_hi:[0,0,1]
	v_cvt_pk_bf16_f32 v7, v18, v19
	v_cvt_pk_bf16_f32 v3, v12, v13
	ds_read_b64 v[12:13], v45 offset:56
	ds_read_b64 v[16:17], v45 offset:184
	s_waitcnt vmcnt(10)
	s_waitcnt lgkmcnt(2)
	v_readlane_b32 s98, v94, 12
	v_readlane_b32 s99, v94, 13
	v_readlane_b32 vcc_lo, v94, 44
	v_readlane_b32 vcc_hi, v94, 45
	v_pk_mul_f32 v[10:11], v[30:31], v[10:11]
	v_pk_mul_f32 v[14:15], v[30:31], v[14:15]
	v_pk_mul_f32 v[10:11], v[10:11], s[98:99]
	v_pk_mul_f32 v[14:15], v[14:15], vcc
	v_pk_mul_f32 v[18:19], v[10:11], v[58:59]
	s_nop 0
	v_pk_fma_f32 v[18:19], v[14:15], v[54:55], v[18:19]
	v_pk_mul_f32 v[14:15], v[14:15], v[58:59]
	s_nop 0
	v_pk_fma_f32 v[10:11], v[10:11], v[54:55], v[14:15] neg_lo:[0,0,1] neg_hi:[0,0,1]
	v_cvt_pk_bf16_f32 v8, v18, v19
	v_cvt_pk_bf16_f32 v4, v10, v11
	ds_read_b64 v[10:11], v45 offset:64
	ds_read_b64 v[14:15], v45 offset:192
	s_waitcnt lgkmcnt(2)
; DI uint4 pack8(const float* v) { uint4 r; r.x = pk2(v[0], v[1]); r.y = pk2(v[2], v[3]); r.z = pk2(v[4], v[5]); r.w = pk2(v[6], v[7]); return r; }
; DI void qk_epilogue(const float* st  , int m0, const float* __restrict__ gain, float scale, bf16_t* __restrict__ dst, int dstride, int dcol0,
;                     const float* __restrict__ COS, const float* __restrict__ SIN) {
;     ...
;   for (int j = 0; j < 32; j += 8) {
;     float o1[8], o2[8];
; #pragma unroll
;     for (int q = 0; q < 8; ++q) {
;       const float x1 = sp[j + q] * rr * gain[j + q], x2 = sp[j + q + 32] * rr * gain[j + q + 32];
;       const float cs = COS[tok * 32 + j + q], sn = SIN[tok * 32 + j + q];
;       o1[q] = (x1 * cs - x2 * sn) * scale;
;       o2[q] = (x2 * cs + x1 * sn) * scale;
;     }
;     *(uint4*)(dp + j) = pack8(o1);
;     *(uint4*)(dp + j + 32) = pack8(o2);
;   }
	v_readlane_b32 s98, v94, 14
	v_readlane_b32 s99, v94, 15
	v_readlane_b32 vcc_lo, v94, 46
	v_readlane_b32 vcc_hi, v94, 47
	v_pk_mul_f32 v[12:13], v[30:31], v[12:13]
	v_pk_mul_f32 v[16:17], v[30:31], v[16:17]
	v_pk_mul_f32 v[12:13], v[12:13], s[98:99]
	v_pk_mul_f32 v[16:17], v[16:17], vcc
	v_pk_mul_f32 v[18:19], v[12:13], v[60:61]
	s_nop 0
	v_pk_fma_f32 v[18:19], v[16:17], v[56:57], v[18:19]
	v_pk_mul_f32 v[16:17], v[16:17], v[60:61]
	s_nop 0
	v_pk_fma_f32 v[12:13], v[12:13], v[56:57], v[16:17] neg_lo:[0,0,1] neg_hi:[0,0,1]
	v_cvt_pk_bf16_f32 v9, v18, v19
	v_cvt_pk_bf16_f32 v5, v12, v13
	ds_read_b64 v[12:13], v45 offset:72
	ds_read_b64 v[16:17], v45 offset:200
	global_store_dwordx4 v[32:33], v[2:5], off offset:16
	global_store_dwordx4 v[32:33], v[6:9], off offset:80
	s_waitcnt vmcnt(10)
	s_waitcnt lgkmcnt(2)
	v_readlane_b32 s98, v94, 16
	v_readlane_b32 s99, v94, 17
	v_readlane_b32 vcc_lo, v94, 48
	v_readlane_b32 vcc_hi, v94, 49
	v_pk_mul_f32 v[10:11], v[30:31], v[10:11]
	v_pk_mul_f32 v[14:15], v[30:31], v[14:15]
	v_pk_mul_f32 v[10:11], v[10:11], s[98:99]
	v_pk_mul_f32 v[14:15], v[14:15], vcc
	v_pk_mul_f32 v[18:19], v[10:11], v[66:67]
	s_nop 0
	v_pk_fma_f32 v[18:19], v[14:15], v[62:63], v[18:19]
	v_pk_mul_f32 v[14:15], v[14:15], v[66:67]
	s_nop 0
	v_pk_fma_f32 v[10:11], v[10:11], v[62:63], v[14:15] neg_lo:[0,0,1] neg_hi:[0,0,1]
	v_cvt_pk_bf16_f32 v6, v18, v19
	v_cvt_pk_bf16_f32 v2, v10, v11
	ds_read_b64 v[10:11], v45 offset:80
	ds_read_b64 v[14:15], v45 offset:208
	s_waitcnt lgkmcnt(2)
	v_readlane_b32 s98, v94, 18
	v_readlane_b32 s99, v94, 19
	v_readlane_b32 vcc_lo, v94, 50
	v_readlane_b32 vcc_hi, v94, 51
	v_pk_mul_f32 v[12:13], v[30:31], v[12:13]
	v_pk_mul_f32 v[16:17], v[30:31], v[16:17]
	v_pk_mul_f32 v[12:13], v[12:13], s[98:99]
	v_pk_mul_f32 v[16:17], v[16:17], vcc
	v_pk_mul_f32 v[18:19], v[12:13], v[68:69]
	s_nop 0
	v_pk_fma_f32 v[18:19], v[16:17], v[64:65], v[18:19]
	v_pk_mul_f32 v[16:17], v[16:17], v[68:69]
	s_nop 0
	v_pk_fma_f32 v[12:13], v[12:13], v[64:65], v[16:17] neg_lo:[0,0,1] neg_hi:[0,0,1]
	v_cvt_pk_bf16_f32 v7, v18, v19
	v_cvt_pk_bf16_f32 v3, v12, v13
	ds_read_b64 v[12:13], v45 offset:88
	ds_read_b64 v[16:17], v45 offset:216
	s_waitcnt vmcnt(8)
	s_waitcnt lgkmcnt(2)
	v_readlane_b32 s98, v94, 20
	v_readlane_b32 s99, v94, 21
	v_readlane_b32 vcc_lo, v94, 52
	v_readlane_b32 vcc_hi, v94, 53
	v_pk_mul_f32 v[10:11], v[30:31], v[10:11]
	v_pk_mul_f32 v[14:15], v[30:31], v[14:15]
	v_pk_mul_f32 v[10:11], v[10:11], s[98:99]
	v_pk_mul_f32 v[14:15], v[14:15], vcc
	v_pk_mul_f32 v[18:19], v[10:11], v[74:75]
	s_nop 0
	v_pk_fma_f32 v[18:19], v[14:15], v[70:71], v[18:19]
	v_pk_mul_f32 v[14:15], v[14:15], v[74:75]
	s_nop 0
	v_pk_fma_f32 v[10:11], v[10:11], v[70:71], v[14:15] neg_lo:[0,0,1] neg_hi:[0,0,1]
	v_cvt_pk_bf16_f32 v8, v18, v19
	v_cvt_pk_bf16_f32 v4, v10, v11
	ds_read_b64 v[10:11], v45 offset:96
	ds_read_b64 v[14:15], v45 offset:224
	s_waitcnt lgkmcnt(2)
	v_readlane_b32 s98, v94, 22
	v_readlane_b32 s99, v94, 23
	v_readlane_b32 vcc_lo, v94, 54
	v_readlane_b32 vcc_hi, v94, 55
	v_pk_mul_f32 v[12:13], v[30:31], v[12:13]
	v_pk_mul_f32 v[16:17], v[30:31], v[16:17]
	v_pk_mul_f32 v[12:13], v[12:13], s[98:99]
	v_pk_mul_f32 v[16:17], v[16:17], vcc
	v_pk_mul_f32 v[18:19], v[12:13], v[76:77]
	s_nop 0
	v_pk_fma_f32 v[18:19], v[16:17], v[72:73], v[18:19]
	v_pk_mul_f32 v[16:17], v[16:17], v[76:77]
	s_nop 0
	v_pk_fma_f32 v[12:13], v[12:13], v[72:73], v[16:17] neg_lo:[0,0,1] neg_hi:[0,0,1]
	v_cvt_pk_bf16_f32 v9, v18, v19
	v_cvt_pk_bf16_f32 v5, v12, v13
	ds_read_b64 v[12:13], v45 offset:104
	ds_read_b64 v[16:17], v45 offset:232
	global_store_dwordx4 v[32:33], v[2:5], off offset:32
	global_store_dwordx4 v[32:33], v[6:9], off offset:96
	s_waitcnt vmcnt(8)
	s_waitcnt lgkmcnt(2)
	v_readlane_b32 s98, v94, 24
	v_readlane_b32 s99, v94, 25
	v_readlane_b32 vcc_lo, v94, 56
	v_readlane_b32 vcc_hi, v94, 57
	v_pk_mul_f32 v[10:11], v[30:31], v[10:11]
	v_pk_mul_f32 v[14:15], v[30:31], v[14:15]
	v_pk_mul_f32 v[10:11], v[10:11], s[98:99]
	v_pk_mul_f32 v[14:15], v[14:15], vcc
	v_pk_mul_f32 v[18:19], v[10:11], v[82:83]
	s_nop 0
	v_pk_fma_f32 v[18:19], v[14:15], v[78:79], v[18:19]
	v_pk_mul_f32 v[14:15], v[14:15], v[82:83]
	s_nop 0
	v_pk_fma_f32 v[10:11], v[10:11], v[78:79], v[14:15] neg_lo:[0,0,1] neg_hi:[0,0,1]
	v_cvt_pk_bf16_f32 v6, v18, v19
	v_cvt_pk_bf16_f32 v2, v10, v11
	ds_read_b64 v[10:11], v45 offset:112
	ds_read_b64 v[14:15], v45 offset:240
	s_waitcnt lgkmcnt(2)
	v_readlane_b32 s98, v94, 26
	v_readlane_b32 s99, v94, 27
	v_readlane_b32 vcc_lo, v94, 58
	v_readlane_b32 vcc_hi, v94, 59
	v_pk_mul_f32 v[12:13], v[30:31], v[12:13]
	v_pk_mul_f32 v[16:17], v[30:31], v[16:17]
	v_pk_mul_f32 v[12:13], v[12:13], s[98:99]
	v_pk_mul_f32 v[16:17], v[16:17], vcc
	v_pk_mul_f32 v[18:19], v[12:13], v[84:85]
	s_nop 0
	v_pk_fma_f32 v[18:19], v[16:17], v[80:81], v[18:19]
	v_pk_mul_f32 v[16:17], v[16:17], v[84:85]
	s_nop 0
	v_pk_fma_f32 v[12:13], v[12:13], v[80:81], v[16:17] neg_lo:[0,0,1] neg_hi:[0,0,1]
	v_cvt_pk_bf16_f32 v7, v18, v19
	v_cvt_pk_bf16_f32 v3, v12, v13
	ds_read_b64 v[12:13], v45 offset:120
	ds_read_b64 v[16:17], v45 offset:248
	s_waitcnt vmcnt(6)
	s_waitcnt lgkmcnt(2)
	v_readlane_b32 s98, v94, 28
	v_readlane_b32 s99, v94, 29
	v_readlane_b32 vcc_lo, v94, 60
	v_readlane_b32 vcc_hi, v94, 61
	v_pk_mul_f32 v[10:11], v[30:31], v[10:11]
	v_pk_mul_f32 v[14:15], v[30:31], v[14:15]
	v_pk_mul_f32 v[10:11], v[10:11], s[98:99]
	v_pk_mul_f32 v[14:15], v[14:15], vcc
	v_pk_mul_f32 v[18:19], v[10:11], v[90:91]
	s_nop 0
	v_pk_fma_f32 v[18:19], v[14:15], v[86:87], v[18:19]
	v_pk_mul_f32 v[14:15], v[14:15], v[90:91]
	s_nop 0
	v_pk_fma_f32 v[10:11], v[10:11], v[86:87], v[14:15] neg_lo:[0,0,1] neg_hi:[0,0,1]
	v_cvt_pk_bf16_f32 v8, v18, v19
	v_cvt_pk_bf16_f32 v4, v10, v11
	s_waitcnt lgkmcnt(0)
	v_readlane_b32 s98, v94, 30
	v_readlane_b32 s99, v94, 31
	v_readlane_b32 vcc_lo, v94, 62
	v_readlane_b32 vcc_hi, v94, 63
	v_pk_mul_f32 v[12:13], v[30:31], v[12:13]
	v_pk_mul_f32 v[16:17], v[30:31], v[16:17]
	v_pk_mul_f32 v[12:13], v[12:13], s[98:99]
	v_pk_mul_f32 v[16:17], v[16:17], vcc
	v_pk_mul_f32 v[18:19], v[12:13], v[92:93]
	s_nop 0
	v_pk_fma_f32 v[18:19], v[16:17], v[88:89], v[18:19]
	v_pk_mul_f32 v[16:17], v[16:17], v[92:93]
	s_nop 0
	v_pk_fma_f32 v[12:13], v[12:13], v[88:89], v[16:17] neg_lo:[0,0,1] neg_hi:[0,0,1]
	v_cvt_pk_bf16_f32 v9, v18, v19
	v_cvt_pk_bf16_f32 v5, v12, v13
	global_store_dwordx4 v[32:33], v[2:5], off offset:48
	global_store_dwordx4 v[32:33], v[6:9], off offset:112

; DI int otid() { int t = threadIdx.x; asm volatile("" : "+v"(t)); return t; }
; DI void qk_epilogue(const float* st  , int m0, const float* __restrict__ gain, float scale, bf16_t* __restrict__ dst, int dstride, int dcol0,
;                     const float* __restrict__ COS, const float* __restrict__ SIN) {
;   const int tid = otid(), row = tid & 127, hd = tid >> 7;
;   const float* sp = st + row * 132 + hd * 64;
;   float ss = 0.f;
; #pragma unroll 4
;   for (int j = 0; j < 64; j += 4) { const float4 v = *(const float4*)(sp + j); ss += v.x * v.x + v.y * v.y + v.z * v.z + v.w * v.w; }
;   const float rr = rsqrtf(ss * (1.f / 64.f) + 1e-6f);
;   const size_t tok = (size_t)(m0 + row);
;   bf16_t* dp = dst + tok * dstride + dcol0 + hd * 64;
; #pragma unroll 2
;   for (int j = 0; j < 32; j += 8) {
;     float o1[8], o2[8];
; #pragma unroll
;     for (int q = 0; q < 8; ++q) {
;       const float x1 = sp[j + q] * rr * gain[j + q], x2 = sp[j + q + 32] * rr * gain[j + q + 32];
;       const float cs = COS[tok * 32 + j + q], sn = SIN[tok * 32 + j + q];
; DI void in_epilogue_half(const Params& p, int l, const float* st, int m0, int nt) {
;     ...
;   if (nt < 4) qk_epilogue(st, m0, p.in[8] + l * 64, 0.125f, (bf16_t*)(ws + O_QA), 512, nt * 128, COS, SIN);
;   else if (nt == 4) raw_epilogue(st, m0, (bf16_t*)(ws + O_KC), 128, 0, false);
;   else if (nt == 5) raw_epilogue(st, m0, (bf16_t*)(ws + O_VC), 128, 0, false);
;   else if (nt == 6) qk_epilogue(st, m0, p.in[9] + l * 64, 1.f, (bf16_t*)(ws + O_KS), 128, 0, COS, SIN);
;   else if (nt == 7) vt_epilogue(st, m0, (bf16_t*)(ws + O_VST), 2, 0);
;   else if (nt == 8) qk_epilogue(st, m0, p.in[9] + l * 64, 1.f, (bf16_t*)(ws + O_KW), 128, 0, COS, SIN);
.LBB0_454:
	s_andn2_b64 vcc, exec, s[28:29]
	s_cbranch_vccnz .LBB0_469
	s_cmp_lt_i32 s0, 5
	s_mov_b64 s[26:27], -1
	s_cbranch_scc1 .LBB0_466
	s_cmp_gt_i32 s0, 5
	s_cbranch_scc0 .LBB0_462
	v_lshlrev_b32_e32 v4, 2, v231
	s_mov_b32 vcc_lo, s53
	s_mov_b32 vcc_hi, s54
	global_load_dword v94, v4, vcc
	s_add_i32 s98, s64, s65
	s_addk_i32 s98, 0x80
	v_and_b32_e32 v2, 0x7f, v216
	v_add_lshl_u32 v2, v2, s98, 7
	v_add_u32_e32 v3, 0x2178000, v2
	v_add_u32_e32 v2, 0x1f78000, v2
	global_load_dwordx4 v[22:25], v2, s[82:83]
	global_load_dwordx4 v[26:29], v3, s[82:83]
	global_load_dwordx4 v[36:39], v2, s[82:83] offset:16
	global_load_dwordx4 v[40:43], v3, s[82:83] offset:16
	global_load_dwordx4 v[46:49], v2, s[82:83] offset:32
	global_load_dwordx4 v[50:53], v3, s[82:83] offset:32
	global_load_dwordx4 v[54:57], v2, s[82:83] offset:48
	global_load_dwordx4 v[58:61], v3, s[82:83] offset:48
	global_load_dwordx4 v[62:65], v2, s[82:83] offset:64
	global_load_dwordx4 v[66:69], v3, s[82:83] offset:64
	global_load_dwordx4 v[70:73], v2, s[82:83] offset:80
	global_load_dwordx4 v[74:77], v3, s[82:83] offset:80
	global_load_dwordx4 v[78:81], v2, s[82:83] offset:96
	global_load_dwordx4 v[82:85], v3, s[82:83] offset:96
	global_load_dwordx4 v[86:89], v2, s[82:83] offset:112
	global_load_dwordx4 v[90:93], v3, s[82:83] offset:112
	v_mov_b32_e32 v2, v216
	s_mov_b32 s0, -4
	v_and_b32_e32 v0, 0x7f, v2
	v_ashrrev_i32_e32 v2, 1, v2
	v_and_b32_e32 v2, 0xffffffc0, v2
	v_lshlrev_b32_e32 v3, 2, v2
	v_mad_u32_u24 v44, v0, s8, v3
	v_mov_b32_e32 v3, 0
	v_mov_b32_e32 v4, v44

; DI uint4 pack8(const float* v) { uint4 r; r.x = pk2(v[0], v[1]); r.y = pk2(v[2], v[3]); r.z = pk2(v[4], v[5]); r.w = pk2(v[6], v[7]); return r; }
; DI void qk_epilogue(const float* st  , int m0, const float* __restrict__ gain, float scale, bf16_t* __restrict__ dst, int dstride, int dcol0,
;                     const float* __restrict__ COS, const float* __restrict__ SIN) {
;     ...
;   for (int j = 0; j < 32; j += 8) {
;     float o1[8], o2[8];
; #pragma unroll
;     for (int q = 0; q < 8; ++q) {
;       const float x1 = sp[j + q] * rr * gain[j + q], x2 = sp[j + q + 32] * rr * gain[j + q + 32];
;       const float cs = COS[tok * 32 + j + q], sn = SIN[tok * 32 + j + q];
;       o1[q] = (x1 * cs - x2 * sn) * scale;
;       o2[q] = (x2 * cs + x1 * sn) * scale;
;     }
;     *(uint4*)(dp + j) = pack8(o1);
;     *(uint4*)(dp + j + 32) = pack8(o2);
;   }
.LBB0_460:
	v_lshl_add_u64 v[32:33], s[82:83], 0, v[32:33]
	v_add_co_u32_e32 v32, vcc, s50, v32
	v_addc_co_u32_e32 v33, vcc, 0, v33, vcc
	ds_read_b64 v[10:11], v45
	ds_read_b64 v[14:15], v45 offset:128
	ds_read_b64 v[12:13], v45 offset:8
	ds_read_b64 v[16:17], v45 offset:136
	s_waitcnt vmcnt(14)
	s_waitcnt lgkmcnt(2)
	v_readlane_b32 s98, v94, 0
	v_readlane_b32 s99, v94, 1
	v_readlane_b32 vcc_lo, v94, 32
	v_readlane_b32 vcc_hi, v94, 33
	v_pk_mul_f32 v[10:11], v[30:31], v[10:11]
	v_pk_mul_f32 v[14:15], v[30:31], v[14:15]
	v_pk_mul_f32 v[10:11], v[10:11], s[98:99]
	v_pk_mul_f32 v[14:15], v[14:15], vcc
	v_pk_mul_f32 v[18:19], v[10:11], v[26:27]
	s_nop 0
	v_pk_fma_f32 v[18:19], v[14:15], v[22:23], v[18:19]
	v_pk_mul_f32 v[14:15], v[14:15], v[26:27]
	s_nop 0
	v_pk_fma_f32 v[10:11], v[10:11], v[22:23], v[14:15] neg_lo:[0,0,1] neg_hi:[0,0,1]
	v_cvt_pk_bf16_f32 v6, v18, v19
	v_cvt_pk_bf16_f32 v2, v10, v11
	ds_read_b64 v[10:11], v45 offset:16
	ds_read_b64 v[14:15], v45 offset:144
	s_waitcnt lgkmcnt(2)
	v_readlane_b32 s98, v94, 2
	v_readlane_b32 s99, v94, 3
	v_readlane_b32 vcc_lo, v94, 34
	v_readlane_b32 vcc_hi, v94, 35
	v_pk_mul_f32 v[12:13], v[30:31], v[12:13]
	v_pk_mul_f32 v[16:17], v[30:31], v[16:17]
	v_pk_mul_f32 v[12:13], v[12:13], s[98:99]
	v_pk_mul_f32 v[16:17], v[16:17], vcc
	v_pk_mul_f32 v[18:19], v[12:13], v[28:29]
	s_nop 0
	v_pk_fma_f32 v[18:19], v[16:17], v[24:25], v[18:19]
	v_pk_mul_f32 v[16:17], v[16:17], v[28:29]
	s_nop 0
	v_pk_fma_f32 v[12:13], v[12:13], v[24:25], v[16:17] neg_lo:[0,0,1] neg_hi:[0,0,1]
	v_cvt_pk_bf16_f32 v7, v18, v19
	v_cvt_pk_bf16_f32 v3, v12, v13
	ds_read_b64 v[12:13], v45 offset:24
	ds_read_b64 v[16:17], v45 offset:152
	s_waitcnt vmcnt(12)
	s_waitcnt lgkmcnt(2)
	v_readlane_b32 s98, v94, 4
	v_readlane_b32 s99, v94, 5
	v_readlane_b32 vcc_lo, v94, 36
	v_readlane_b32 vcc_hi, v94, 37
	v_pk_mul_f32 v[10:11], v[30:31], v[10:11]
	v_pk_mul_f32 v[14:15], v[30:31], v[14:15]
	v_pk_mul_f32 v[10:11], v[10:11], s[98:99]
	v_pk_mul_f32 v[14:15], v[14:15], vcc
	v_pk_mul_f32 v[18:19], v[10:11], v[40:41]
	s_nop 0
	v_pk_fma_f32 v[18:19], v[14:15], v[36:37], v[18:19]
	v_pk_mul_f32 v[14:15], v[14:15], v[40:41]
	s_nop 0
	v_pk_fma_f32 v[10:11], v[10:11], v[36:37], v[14:15] neg_lo:[0,0,1] neg_hi:[0,0,1]
	v_cvt_pk_bf16_f32 v8, v18, v19
	v_cvt_pk_bf16_f32 v4, v10, v11
	ds_read_b64 v[10:11], v45 offset:32
	ds_read_b64 v[14:15], v45 offset:160
	s_waitcnt lgkmcnt(2)
	v_readlane_b32 s98, v94, 6
	v_readlane_b32 s99, v94, 7
	v_readlane_b32 vcc_lo, v94, 38
	v_readlane_b32 vcc_hi, v94, 39
	v_pk_mul_f32 v[12:13], v[30:31], v[12:13]
	v_pk_mul_f32 v[16:17], v[30:31], v[16:17]
	v_pk_mul_f32 v[12:13], v[12:13], s[98:99]
	v_pk_mul_f32 v[16:17], v[16:17], vcc
	v_pk_mul_f32 v[18:19], v[12:13], v[42:43]
	s_nop 0
	v_pk_fma_f32 v[18:19], v[16:17], v[38:39], v[18:19]
	v_pk_mul_f32 v[16:17], v[16:17], v[42:43]
	s_nop 0
	v_pk_fma_f32 v[12:13], v[12:13], v[38:39], v[16:17] neg_lo:[0,0,1] neg_hi:[0,0,1]
	v_cvt_pk_bf16_f32 v9, v18, v19
	v_cvt_pk_bf16_f32 v5, v12, v13
	ds_read_b64 v[12:13], v45 offset:40
	ds_read_b64 v[16:17], v45 offset:168
	global_store_dwordx4 v[32:33], v[2:5], off
	global_store_dwordx4 v[32:33], v[6:9], off offset:64
	s_waitcnt vmcnt(12)
	s_waitcnt lgkmcnt(2)
	v_readlane_b32 s98, v94, 8
	v_readlane_b32 s99, v94, 9
	v_readlane_b32 vcc_lo, v94, 40
	v_readlane_b32 vcc_hi, v94, 41
	v_pk_mul_f32 v[10:11], v[30:31], v[10:11]
	v_pk_mul_f32 v[14:15], v[30:31], v[14:15]
	v_pk_mul_f32 v[10:11], v[10:11], s[98:99]
	v_pk_mul_f32 v[14:15], v[14:15], vcc
	v_pk_mul_f32 v[18:19], v[10:11], v[50:51]
	s_nop 0
	v_pk_fma_f32 v[18:19], v[14:15], v[46:47], v[18:19]
	v_pk_mul_f32 v[14:15], v[14:15], v[50:51]
	s_nop 0
	v_pk_fma_f32 v[10:11], v[10:11], v[46:47], v[14:15] neg_lo:[0,0,1] neg_hi:[0,0,1]
	v_cvt_pk_bf16_f32 v6, v18, v19
	v_cvt_pk_bf16_f32 v2, v10, v11
	ds_read_b64 v[10:11], v45 offset:48
	ds_read_b64 v[14:15], v45 offset:176
	s_waitcnt lgkmcnt(2)
	v_readlane_b32 s98, v94, 10
	v_readlane_b32 s99, v94, 11
	v_readlane_b32 vcc_lo, v94, 42
	v_readlane_b32 vcc_hi, v94, 43
	v_pk_mul_f32 v[12:13], v[30:31], v[12:13]
	v_pk_mul_f32 v[16:17], v[30:31], v[16:17]
	v_pk_mul_f32 v[12:13], v[12:13], s[98:99]
	v_pk_mul_f32 v[16:17], v[16:17], vcc
	v_pk_mul_f32 v[18:19], v[12:13], v[52:53]
	s_nop 0
	v_pk_fma_f32 v[18:19], v[16:17], v[48:49], v[18:19]
	v_pk_mul_f32 v[16:17], v[16:17], v[52:53]
	s_nop 0
	v_pk_fma_f32 v[12:13], v[12:13], v[48:49], v[16:17] neg_lo:[0,0,1] neg_hi:[0,0,1]
	v_cvt_pk_bf16_f32 v7, v18, v19
	v_cvt_pk_bf16_f32 v3, v12, v13
	ds_read_b64 v[12:13], v45 offset:56
	ds_read_b64 v[16:17], v45 offset:184
	s_waitcnt vmcnt(10)
	s_waitcnt lgkmcnt(2)
	v_readlane_b32 s98, v94, 12
	v_readlane_b32 s99, v94, 13
	v_readlane_b32 vcc_lo, v94, 44
	v_readlane_b32 vcc_hi, v94, 45
	v_pk_mul_f32 v[10:11], v[30:31], v[10:11]
	v_pk_mul_f32 v[14:15], v[30:31], v[14:15]
	v_pk_mul_f32 v[10:11], v[10:11], s[98:99]
	v_pk_mul_f32 v[14:15], v[14:15], vcc
	v_pk_mul_f32 v[18:19], v[10:11], v[58:59]
	s_nop 0
	v_pk_fma_f32 v[18:19], v[14:15], v[54:55], v[18:19]
	v_pk_mul_f32 v[14:15], v[14:15], v[58:59]
	s_nop 0
	v_pk_fma_f32 v[10:11], v[10:11], v[54:55], v[14:15] neg_lo:[0,0,1] neg_hi:[0,0,1]
	v_cvt_pk_bf16_f32 v8, v18, v19
	v_cvt_pk_bf16_f32 v4, v10, v11
	ds_read_b64 v[10:11], v45 offset:64
	ds_read_b64 v[14:15], v45 offset:192
	s_waitcnt lgkmcnt(2)
; DI uint4 pack8(const float* v) { uint4 r; r.x = pk2(v[0], v[1]); r.y = pk2(v[2], v[3]); r.z = pk2(v[4], v[5]); r.w = pk2(v[6], v[7]); return r; }
; DI void qk_epilogue(const float* st  , int m0, const float* __restrict__ gain, float scale, bf16_t* __restrict__ dst, int dstride, int dcol0,
;                     const float* __restrict__ COS, const float* __restrict__ SIN) {
;     ...
;   for (int j = 0; j < 32; j += 8) {
;     float o1[8], o2[8];
; #pragma unroll
;     for (int q = 0; q < 8; ++q) {
;       const float x1 = sp[j + q] * rr * gain[j + q], x2 = sp[j + q + 32] * rr * gain[j + q + 32];
;       const float cs = COS[tok * 32 + j + q], sn = SIN[tok * 32 + j + q];
;       o1[q] = (x1 * cs - x2 * sn) * scale;
;       o2[q] = (x2 * cs + x1 * sn) * scale;
;     }
;     *(uint4*)(dp + j) = pack8(o1);
;     *(uint4*)(dp + j + 32) = pack8(o2);
;   }
	v_readlane_b32 s98, v94, 14
	v_readlane_b32 s99, v94, 15
	v_readlane_b32 vcc_lo, v94, 46
	v_readlane_b32 vcc_hi, v94, 47
	v_pk_mul_f32 v[12:13], v[30:31], v[12:13]
	v_pk_mul_f32 v[16:17], v[30:31], v[16:17]
	v_pk_mul_f32 v[12:13], v[12:13], s[98:99]
	v_pk_mul_f32 v[16:17], v[16:17], vcc
	v_pk_mul_f32 v[18:19], v[12:13], v[60:61]
	s_nop 0
	v_pk_fma_f32 v[18:19], v[16:17], v[56:57], v[18:19]
	v_pk_mul_f32 v[16:17], v[16:17], v[60:61]
	s_nop 0
	v_pk_fma_f32 v[12:13], v[12:13], v[56:57], v[16:17] neg_lo:[0,0,1] neg_hi:[0,0,1]
	v_cvt_pk_bf16_f32 v9, v18, v19
	v_cvt_pk_bf16_f32 v5, v12, v13
	ds_read_b64 v[12:13], v45 offset:72
	ds_read_b64 v[16:17], v45 offset:200
	global_store_dwordx4 v[32:33], v[2:5], off offset:16
	global_store_dwordx4 v[32:33], v[6:9], off offset:80
	s_waitcnt vmcnt(10)
	s_waitcnt lgkmcnt(2)
	v_readlane_b32 s98, v94, 16
	v_readlane_b32 s99, v94, 17
	v_readlane_b32 vcc_lo, v94, 48
	v_readlane_b32 vcc_hi, v94, 49
	v_pk_mul_f32 v[10:11], v[30:31], v[10:11]
	v_pk_mul_f32 v[14:15], v[30:31], v[14:15]
	v_pk_mul_f32 v[10:11], v[10:11], s[98:99]
	v_pk_mul_f32 v[14:15], v[14:15], vcc
	v_pk_mul_f32 v[18:19], v[10:11], v[66:67]
	s_nop 0
	v_pk_fma_f32 v[18:19], v[14:15], v[62:63], v[18:19]
	v_pk_mul_f32 v[14:15], v[14:15], v[66:67]
	s_nop 0
	v_pk_fma_f32 v[10:11], v[10:11], v[62:63], v[14:15] neg_lo:[0,0,1] neg_hi:[0,0,1]
	v_cvt_pk_bf16_f32 v6, v18, v19
	v_cvt_pk_bf16_f32 v2, v10, v11
	ds_read_b64 v[10:11], v45 offset:80
	ds_read_b64 v[14:15], v45 offset:208
	s_waitcnt lgkmcnt(2)
	v_readlane_b32 s98, v94, 18
	v_readlane_b32 s99, v94, 19
	v_readlane_b32 vcc_lo, v94, 50
	v_readlane_b32 vcc_hi, v94, 51
	v_pk_mul_f32 v[12:13], v[30:31], v[12:13]
	v_pk_mul_f32 v[16:17], v[30:31], v[16:17]
	v_pk_mul_f32 v[12:13], v[12:13], s[98:99]
	v_pk_mul_f32 v[16:17], v[16:17], vcc
	v_pk_mul_f32 v[18:19], v[12:13], v[68:69]
	s_nop 0
	v_pk_fma_f32 v[18:19], v[16:17], v[64:65], v[18:19]
	v_pk_mul_f32 v[16:17], v[16:17], v[68:69]
	s_nop 0
	v_pk_fma_f32 v[12:13], v[12:13], v[64:65], v[16:17] neg_lo:[0,0,1] neg_hi:[0,0,1]
	v_cvt_pk_bf16_f32 v7, v18, v19
	v_cvt_pk_bf16_f32 v3, v12, v13
	ds_read_b64 v[12:13], v45 offset:88
	ds_read_b64 v[16:17], v45 offset:216
	s_waitcnt vmcnt(8)
	s_waitcnt lgkmcnt(2)
	v_readlane_b32 s98, v94, 20
	v_readlane_b32 s99, v94, 21
	v_readlane_b32 vcc_lo, v94, 52
	v_readlane_b32 vcc_hi, v94, 53
	v_pk_mul_f32 v[10:11], v[30:31], v[10:11]
	v_pk_mul_f32 v[14:15], v[30:31], v[14:15]
	v_pk_mul_f32 v[10:11], v[10:11], s[98:99]
	v_pk_mul_f32 v[14:15], v[14:15], vcc
	v_pk_mul_f32 v[18:19], v[10:11], v[74:75]
	s_nop 0
	v_pk_fma_f32 v[18:19], v[14:15], v[70:71], v[18:19]
	v_pk_mul_f32 v[14:15], v[14:15], v[74:75]
	s_nop 0
	v_pk_fma_f32 v[10:11], v[10:11], v[70:71], v[14:15] neg_lo:[0,0,1] neg_hi:[0,0,1]
	v_cvt_pk_bf16_f32 v8, v18, v19
	v_cvt_pk_bf16_f32 v4, v10, v11
	ds_read_b64 v[10:11], v45 offset:96
	ds_read_b64 v[14:15], v45 offset:224
	s_waitcnt lgkmcnt(2)
	v_readlane_b32 s98, v94, 22
	v_readlane_b32 s99, v94, 23
	v_readlane_b32 vcc_lo, v94, 54
	v_readlane_b32 vcc_hi, v94, 55
	v_pk_mul_f32 v[12:13], v[30:31], v[12:13]
	v_pk_mul_f32 v[16:17], v[30:31], v[16:17]
	v_pk_mul_f32 v[12:13], v[12:13], s[98:99]
	v_pk_mul_f32 v[16:17], v[16:17], vcc
	v_pk_mul_f32 v[18:19], v[12:13], v[76:77]
	s_nop 0
	v_pk_fma_f32 v[18:19], v[16:17], v[72:73], v[18:19]
	v_pk_mul_f32 v[16:17], v[16:17], v[76:77]
	s_nop 0
	v_pk_fma_f32 v[12:13], v[12:13], v[72:73], v[16:17] neg_lo:[0,0,1] neg_hi:[0,0,1]
	v_cvt_pk_bf16_f32 v9, v18, v19
	v_cvt_pk_bf16_f32 v5, v12, v13
	ds_read_b64 v[12:13], v45 offset:104
	ds_read_b64 v[16:17], v45 offset:232
	global_store_dwordx4 v[32:33], v[2:5], off offset:32
	global_store_dwordx4 v[32:33], v[6:9], off offset:96
	s_waitcnt vmcnt(8)
	s_waitcnt lgkmcnt(2)
	v_readlane_b32 s98, v94, 24
	v_readlane_b32 s99, v94, 25
	v_readlane_b32 vcc_lo, v94, 56
	v_readlane_b32 vcc_hi, v94, 57
	v_pk_mul_f32 v[10:11], v[30:31], v[10:11]
	v_pk_mul_f32 v[14:15], v[30:31], v[14:15]
	v_pk_mul_f32 v[10:11], v[10:11], s[98:99]
	v_pk_mul_f32 v[14:15], v[14:15], vcc
	v_pk_mul_f32 v[18:19], v[10:11], v[82:83]
	s_nop 0
	v_pk_fma_f32 v[18:19], v[14:15], v[78:79], v[18:19]
	v_pk_mul_f32 v[14:15], v[14:15], v[82:83]
	s_nop 0
	v_pk_fma_f32 v[10:11], v[10:11], v[78:79], v[14:15] neg_lo:[0,0,1] neg_hi:[0,0,1]
	v_cvt_pk_bf16_f32 v6, v18, v19
	v_cvt_pk_bf16_f32 v2, v10, v11
	ds_read_b64 v[10:11], v45 offset:112
	ds_read_b64 v[14:15], v45 offset:240
	s_waitcnt lgkmcnt(2)
	v_readlane_b32 s98, v94, 26
	v_readlane_b32 s99, v94, 27
	v_readlane_b32 vcc_lo, v94, 58
	v_readlane_b32 vcc_hi, v94, 59
	v_pk_mul_f32 v[12:13], v[30:31], v[12:13]
	v_pk_mul_f32 v[16:17], v[30:31], v[16:17]
	v_pk_mul_f32 v[12:13], v[12:13], s[98:99]
	v_pk_mul_f32 v[16:17], v[16:17], vcc
	v_pk_mul_f32 v[18:19], v[12:13], v[84:85]
	s_nop 0
	v_pk_fma_f32 v[18:19], v[16:17], v[80:81], v[18:19]
	v_pk_mul_f32 v[16:17], v[16:17], v[84:85]
	s_nop 0
	v_pk_fma_f32 v[12:13], v[12:13], v[80:81], v[16:17] neg_lo:[0,0,1] neg_hi:[0,0,1]
	v_cvt_pk_bf16_f32 v7, v18, v19
	v_cvt_pk_bf16_f32 v3, v12, v13
	ds_read_b64 v[12:13], v45 offset:120
	ds_read_b64 v[16:17], v45 offset:248
	s_waitcnt vmcnt(6)
	s_waitcnt lgkmcnt(2)
	v_readlane_b32 s98, v94, 28
	v_readlane_b32 s99, v94, 29
	v_readlane_b32 vcc_lo, v94, 60
	v_readlane_b32 vcc_hi, v94, 61
	v_pk_mul_f32 v[10:11], v[30:31], v[10:11]
	v_pk_mul_f32 v[14:15], v[30:31], v[14:15]
	v_pk_mul_f32 v[10:11], v[10:11], s[98:99]
	v_pk_mul_f32 v[14:15], v[14:15], vcc
	v_pk_mul_f32 v[18:19], v[10:11], v[90:91]
	s_nop 0
	v_pk_fma_f32 v[18:19], v[14:15], v[86:87], v[18:19]
	v_pk_mul_f32 v[14:15], v[14:15], v[90:91]
	s_nop 0
	v_pk_fma_f32 v[10:11], v[10:11], v[86:87], v[14:15] neg_lo:[0,0,1] neg_hi:[0,0,1]
	v_cvt_pk_bf16_f32 v8, v18, v19
	v_cvt_pk_bf16_f32 v4, v10, v11
	s_waitcnt lgkmcnt(0)
	v_readlane_b32 s98, v94, 30
	v_readlane_b32 s99, v94, 31
	v_readlane_b32 vcc_lo, v94, 62
	v_readlane_b32 vcc_hi, v94, 63
	v_pk_mul_f32 v[12:13], v[30:31], v[12:13]
	v_pk_mul_f32 v[16:17], v[30:31], v[16:17]
	v_pk_mul_f32 v[12:13], v[12:13], s[98:99]
	v_pk_mul_f32 v[16:17], v[16:17], vcc
	v_pk_mul_f32 v[18:19], v[12:13], v[92:93]
	s_nop 0
	v_pk_fma_f32 v[18:19], v[16:17], v[88:89], v[18:19]
	v_pk_mul_f32 v[16:17], v[16:17], v[92:93]
	s_nop 0
	v_pk_fma_f32 v[12:13], v[12:13], v[88:89], v[16:17] neg_lo:[0,0,1] neg_hi:[0,0,1]
	v_cvt_pk_bf16_f32 v9, v18, v19
	v_cvt_pk_bf16_f32 v5, v12, v13
	global_store_dwordx4 v[32:33], v[2:5], off offset:48
	global_store_dwordx4 v[32:33], v[6:9], off offset:112
	s_mov_b64 s[26:27], 0

; DI int otid() { int t = threadIdx.x; asm volatile("" : "+v"(t)); return t; }
; DI void qk_epilogue(const float* st  , int m0, const float* __restrict__ gain, float scale, bf16_t* __restrict__ dst, int dstride, int dcol0,
;                     const float* __restrict__ COS, const float* __restrict__ SIN) {
;   const int tid = otid(), row = tid & 127, hd = tid >> 7;
;   const float* sp = st + row * 132 + hd * 64;
;   float ss = 0.f;
; #pragma unroll 4
;   for (int j = 0; j < 64; j += 4) { const float4 v = *(const float4*)(sp + j); ss += v.x * v.x + v.y * v.y + v.z * v.z + v.w * v.w; }
;   const float rr = rsqrtf(ss * (1.f / 64.f) + 1e-6f);
;   const size_t tok = (size_t)(m0 + row);
;   bf16_t* dp = dst + tok * dstride + dcol0 + hd * 64;
; #pragma unroll 2
;   for (int j = 0; j < 32; j += 8) {
;     float o1[8], o2[8];
; #pragma unroll
;     for (int q = 0; q < 8; ++q) {
;       const float x1 = sp[j + q] * rr * gain[j + q], x2 = sp[j + q + 32] * rr * gain[j + q + 32];
;       const float cs = COS[tok * 32 + j + q], sn = SIN[tok * 32 + j + q];
.LBB0_470:
	s_and_b64 vcc, exec, s[28:29]
	s_cbranch_vccz .LBB0_329
	v_lshlrev_b32_e32 v4, 2, v231
	s_mov_b32 vcc_lo, s59
	s_mov_b32 vcc_hi, s60
	global_load_dword v37, v4, vcc
	s_add_i32 s98, s64, s65
	s_addk_i32 s98, 0x80
	v_and_b32_e32 v2, 0x7f, v216
	v_add_lshl_u32 v2, v2, s98, 7
	v_add_u32_e32 v3, 0x2178000, v2
	v_add_u32_e32 v2, 0x1f78000, v2
	global_load_dwordx4 v[22:25], v2, s[82:83]
	global_load_dwordx4 v[32:35], v3, s[82:83]
	global_load_dwordx4 v[38:41], v2, s[82:83] offset:16
	global_load_dwordx4 v[42:45], v3, s[82:83] offset:16
	global_load_dwordx4 v[46:49], v2, s[82:83] offset:32
	global_load_dwordx4 v[50:53], v3, s[82:83] offset:32
	global_load_dwordx4 v[54:57], v2, s[82:83] offset:48
	global_load_dwordx4 v[58:61], v3, s[82:83] offset:48
	global_load_dwordx4 v[62:65], v2, s[82:83] offset:64
	global_load_dwordx4 v[66:69], v3, s[82:83] offset:64
	global_load_dwordx4 v[70:73], v2, s[82:83] offset:80
	global_load_dwordx4 v[74:77], v3, s[82:83] offset:80
	global_load_dwordx4 v[78:81], v2, s[82:83] offset:96
	global_load_dwordx4 v[82:85], v3, s[82:83] offset:96
	global_load_dwordx4 v[86:89], v2, s[82:83] offset:112
	global_load_dwordx4 v[90:93], v3, s[82:83] offset:112
	v_mov_b32_e32 v2, v216
	v_mov_b32_e32 v4, 0
	v_and_b32_e32 v0, 0x7f, v2
	v_ashrrev_i32_e32 v2, 1, v2
	v_and_b32_e32 v2, 0xffffffc0, v2
	v_lshlrev_b32_e32 v3, 2, v2
	v_mad_u32_u24 v36, v0, s8, v3
	s_mov_b32 s0, -4
	v_mov_b32_e32 v3, v36

; DI uint4 pack8(const float* v) { uint4 r; r.x = pk2(v[0], v[1]); r.y = pk2(v[2], v[3]); r.z = pk2(v[4], v[5]); r.w = pk2(v[6], v[7]); return r; }
; DI void qk_epilogue(const float* st  , int m0, const float* __restrict__ gain, float scale, bf16_t* __restrict__ dst, int dstride, int dcol0,
;                     const float* __restrict__ COS, const float* __restrict__ SIN) {
;     ...
;   for (int j = 0; j < 32; j += 8) {
;     float o1[8], o2[8];
; #pragma unroll
;     for (int q = 0; q < 8; ++q) {
;       const float x1 = sp[j + q] * rr * gain[j + q], x2 = sp[j + q + 32] * rr * gain[j + q + 32];
;       const float cs = COS[tok * 32 + j + q], sn = SIN[tok * 32 + j + q];
;       o1[q] = (x1 * cs - x2 * sn) * scale;
;       o2[q] = (x2 * cs + x1 * sn) * scale;
;     }
;     *(uint4*)(dp + j) = pack8(o1);
;     *(uint4*)(dp + j + 32) = pack8(o2);
;   }
.LBB0_474:
	ds_read_b64 v[10:11], v0
	ds_read_b64 v[14:15], v0 offset:128
	ds_read_b64 v[12:13], v0 offset:8
	ds_read_b64 v[16:17], v0 offset:136
	s_waitcnt vmcnt(14)
	s_waitcnt lgkmcnt(2)
	v_readlane_b32 s98, v37, 0
	v_readlane_b32 s99, v37, 1
	v_readlane_b32 vcc_lo, v37, 32
	v_readlane_b32 vcc_hi, v37, 33
	v_pk_mul_f32 v[10:11], v[26:27], v[10:11]
	v_pk_mul_f32 v[14:15], v[26:27], v[14:15]
	v_pk_mul_f32 v[10:11], v[10:11], s[98:99]
	v_pk_mul_f32 v[14:15], v[14:15], vcc
	v_pk_mul_f32 v[18:19], v[10:11], v[32:33]
	s_nop 0
	v_pk_fma_f32 v[18:19], v[14:15], v[22:23], v[18:19]
	v_pk_mul_f32 v[14:15], v[14:15], v[32:33]
	s_nop 0
	v_pk_fma_f32 v[10:11], v[10:11], v[22:23], v[14:15] neg_lo:[0,0,1] neg_hi:[0,0,1]
	v_pk_mul_f32 v[18:19], v[18:19], s[16:17] op_sel_hi:[1,0]
	v_pk_mul_f32 v[10:11], v[10:11], s[16:17] op_sel_hi:[1,0]
	v_cvt_pk_bf16_f32 v6, v18, v19
	v_cvt_pk_bf16_f32 v2, v10, v11
	ds_read_b64 v[10:11], v0 offset:16
	ds_read_b64 v[14:15], v0 offset:144
	s_waitcnt lgkmcnt(2)
	v_readlane_b32 s98, v37, 2
	v_readlane_b32 s99, v37, 3
	v_readlane_b32 vcc_lo, v37, 34
	v_readlane_b32 vcc_hi, v37, 35
	v_pk_mul_f32 v[12:13], v[26:27], v[12:13]
	v_pk_mul_f32 v[16:17], v[26:27], v[16:17]
	v_pk_mul_f32 v[12:13], v[12:13], s[98:99]
	v_pk_mul_f32 v[16:17], v[16:17], vcc
	v_pk_mul_f32 v[18:19], v[12:13], v[34:35]
	s_nop 0
	v_pk_fma_f32 v[18:19], v[16:17], v[24:25], v[18:19]
	v_pk_mul_f32 v[16:17], v[16:17], v[34:35]
	s_nop 0
	v_pk_fma_f32 v[12:13], v[12:13], v[24:25], v[16:17] neg_lo:[0,0,1] neg_hi:[0,0,1]
	v_pk_mul_f32 v[18:19], v[18:19], s[16:17] op_sel_hi:[1,0]
	v_pk_mul_f32 v[12:13], v[12:13], s[16:17] op_sel_hi:[1,0]
	v_cvt_pk_bf16_f32 v7, v18, v19
	v_cvt_pk_bf16_f32 v3, v12, v13
	ds_read_b64 v[12:13], v0 offset:24
	ds_read_b64 v[16:17], v0 offset:152
	s_waitcnt vmcnt(12)
	s_waitcnt lgkmcnt(2)
	v_readlane_b32 s98, v37, 4
	v_readlane_b32 s99, v37, 5
	v_readlane_b32 vcc_lo, v37, 36
	v_readlane_b32 vcc_hi, v37, 37
	v_pk_mul_f32 v[10:11], v[26:27], v[10:11]
	v_pk_mul_f32 v[14:15], v[26:27], v[14:15]
	v_pk_mul_f32 v[10:11], v[10:11], s[98:99]
	v_pk_mul_f32 v[14:15], v[14:15], vcc
	v_pk_mul_f32 v[18:19], v[10:11], v[42:43]
	s_nop 0
	v_pk_fma_f32 v[18:19], v[14:15], v[38:39], v[18:19]
	v_pk_mul_f32 v[14:15], v[14:15], v[42:43]
	s_nop 0
	v_pk_fma_f32 v[10:11], v[10:11], v[38:39], v[14:15] neg_lo:[0,0,1] neg_hi:[0,0,1]
	v_pk_mul_f32 v[18:19], v[18:19], s[16:17] op_sel_hi:[1,0]
	v_pk_mul_f32 v[10:11], v[10:11], s[16:17] op_sel_hi:[1,0]
	v_cvt_pk_bf16_f32 v8, v18, v19
	v_cvt_pk_bf16_f32 v4, v10, v11
	ds_read_b64 v[10:11], v0 offset:32
	ds_read_b64 v[14:15], v0 offset:160
	s_waitcnt lgkmcnt(2)
	v_readlane_b32 s98, v37, 6
	v_readlane_b32 s99, v37, 7
	v_readlane_b32 vcc_lo, v37, 38
	v_readlane_b32 vcc_hi, v37, 39
	v_pk_mul_f32 v[12:13], v[26:27], v[12:13]
	v_pk_mul_f32 v[16:17], v[26:27], v[16:17]
	v_pk_mul_f32 v[12:13], v[12:13], s[98:99]
	v_pk_mul_f32 v[16:17], v[16:17], vcc
	v_pk_mul_f32 v[18:19], v[12:13], v[44:45]
	s_nop 0
	v_pk_fma_f32 v[18:19], v[16:17], v[40:41], v[18:19]
	v_pk_mul_f32 v[16:17], v[16:17], v[44:45]
	s_nop 0
	v_pk_fma_f32 v[12:13], v[12:13], v[40:41], v[16:17] neg_lo:[0,0,1] neg_hi:[0,0,1]
	v_pk_mul_f32 v[18:19], v[18:19], s[16:17] op_sel_hi:[1,0]
	v_pk_mul_f32 v[12:13], v[12:13], s[16:17] op_sel_hi:[1,0]
	v_cvt_pk_bf16_f32 v9, v18, v19
	v_cvt_pk_bf16_f32 v5, v12, v13
	ds_read_b64 v[12:13], v0 offset:40
	ds_read_b64 v[16:17], v0 offset:168
	global_store_dwordx4 v[30:31], v[2:5], off offset:-64
	global_store_dwordx4 v[30:31], v[6:9], off
	s_waitcnt vmcnt(12)
	s_waitcnt lgkmcnt(2)
	v_readlane_b32 s98, v37, 8
	v_readlane_b32 s99, v37, 9
	v_readlane_b32 vcc_lo, v37, 40
	v_readlane_b32 vcc_hi, v37, 41
	v_pk_mul_f32 v[10:11], v[26:27], v[10:11]
	v_pk_mul_f32 v[14:15], v[26:27], v[14:15]
	v_pk_mul_f32 v[10:11], v[10:11], s[98:99]
	v_pk_mul_f32 v[14:15], v[14:15], vcc
	v_pk_mul_f32 v[18:19], v[10:11], v[50:51]
	s_nop 0
	v_pk_fma_f32 v[18:19], v[14:15], v[46:47], v[18:19]
	v_pk_mul_f32 v[14:15], v[14:15], v[50:51]
	s_nop 0
	v_pk_fma_f32 v[10:11], v[10:11], v[46:47], v[14:15] neg_lo:[0,0,1] neg_hi:[0,0,1]
	v_pk_mul_f32 v[18:19], v[18:19], s[16:17] op_sel_hi:[1,0]
	v_pk_mul_f32 v[10:11], v[10:11], s[16:17] op_sel_hi:[1,0]
	v_cvt_pk_bf16_f32 v6, v18, v19
	v_cvt_pk_bf16_f32 v2, v10, v11
	ds_read_b64 v[10:11], v0 offset:48
	ds_read_b64 v[14:15], v0 offset:176
	s_waitcnt lgkmcnt(2)
	v_readlane_b32 s98, v37, 10
	v_readlane_b32 s99, v37, 11
	v_readlane_b32 vcc_lo, v37, 42
	v_readlane_b32 vcc_hi, v37, 43
	v_pk_mul_f32 v[12:13], v[26:27], v[12:13]
	v_pk_mul_f32 v[16:17], v[26:27], v[16:17]
	v_pk_mul_f32 v[12:13], v[12:13], s[98:99]
	v_pk_mul_f32 v[16:17], v[16:17], vcc
	v_pk_mul_f32 v[18:19], v[12:13], v[52:53]
	s_nop 0
	v_pk_fma_f32 v[18:19], v[16:17], v[48:49], v[18:19]
	v_pk_mul_f32 v[16:17], v[16:17], v[52:53]
	s_nop 0
	v_pk_fma_f32 v[12:13], v[12:13], v[48:49], v[16:17] neg_lo:[0,0,1] neg_hi:[0,0,1]
	v_pk_mul_f32 v[18:19], v[18:19], s[16:17] op_sel_hi:[1,0]
	v_pk_mul_f32 v[12:13], v[12:13], s[16:17] op_sel_hi:[1,0]
	v_cvt_pk_bf16_f32 v7, v18, v19
	v_cvt_pk_bf16_f32 v3, v12, v13
	ds_read_b64 v[12:13], v0 offset:56
	ds_read_b64 v[16:17], v0 offset:184
	s_waitcnt vmcnt(10)
	s_waitcnt lgkmcnt(2)
	v_readlane_b32 s98, v37, 12
	v_readlane_b32 s99, v37, 13
	v_readlane_b32 vcc_lo, v37, 44
	v_readlane_b32 vcc_hi, v37, 45
	v_pk_mul_f32 v[10:11], v[26:27], v[10:11]
	v_pk_mul_f32 v[14:15], v[26:27], v[14:15]
	v_pk_mul_f32 v[10:11], v[10:11], s[98:99]
	v_pk_mul_f32 v[14:15], v[14:15], vcc
	v_pk_mul_f32 v[18:19], v[10:11], v[58:59]
	s_nop 0
	v_pk_fma_f32 v[18:19], v[14:15], v[54:55], v[18:19]
	v_pk_mul_f32 v[14:15], v[14:15], v[58:59]
	s_nop 0
	v_pk_fma_f32 v[10:11], v[10:11], v[54:55], v[14:15] neg_lo:[0,0,1] neg_hi:[0,0,1]
	v_pk_mul_f32 v[18:19], v[18:19], s[16:17] op_sel_hi:[1,0]
	v_pk_mul_f32 v[10:11], v[10:11], s[16:17] op_sel_hi:[1,0]
	v_cvt_pk_bf16_f32 v8, v18, v19
	v_cvt_pk_bf16_f32 v4, v10, v11
	ds_read_b64 v[10:11], v0 offset:64
	ds_read_b64 v[14:15], v0 offset:192
	s_waitcnt lgkmcnt(2)
; DI uint4 pack8(const float* v) { uint4 r; r.x = pk2(v[0], v[1]); r.y = pk2(v[2], v[3]); r.z = pk2(v[4], v[5]); r.w = pk2(v[6], v[7]); return r; }
; DI void qk_epilogue(const float* st  , int m0, const float* __restrict__ gain, float scale, bf16_t* __restrict__ dst, int dstride, int dcol0,
;                     const float* __restrict__ COS, const float* __restrict__ SIN) {
;     ...
;   for (int j = 0; j < 32; j += 8) {
;     float o1[8], o2[8];
; #pragma unroll
;     for (int q = 0; q < 8; ++q) {
;       const float x1 = sp[j + q] * rr * gain[j + q], x2 = sp[j + q + 32] * rr * gain[j + q + 32];
;       const float cs = COS[tok * 32 + j + q], sn = SIN[tok * 32 + j + q];
;       o1[q] = (x1 * cs - x2 * sn) * scale;
;       o2[q] = (x2 * cs + x1 * sn) * scale;
;     }
;     *(uint4*)(dp + j) = pack8(o1);
;     *(uint4*)(dp + j + 32) = pack8(o2);
;   }
	v_readlane_b32 s98, v37, 14
	v_readlane_b32 s99, v37, 15
	v_readlane_b32 vcc_lo, v37, 46
	v_readlane_b32 vcc_hi, v37, 47
	v_pk_mul_f32 v[12:13], v[26:27], v[12:13]
	v_pk_mul_f32 v[16:17], v[26:27], v[16:17]
	v_pk_mul_f32 v[12:13], v[12:13], s[98:99]
	v_pk_mul_f32 v[16:17], v[16:17], vcc
	v_pk_mul_f32 v[18:19], v[12:13], v[60:61]
	s_nop 0
	v_pk_fma_f32 v[18:19], v[16:17], v[56:57], v[18:19]
	v_pk_mul_f32 v[16:17], v[16:17], v[60:61]
	s_nop 0
	v_pk_fma_f32 v[12:13], v[12:13], v[56:57], v[16:17] neg_lo:[0,0,1] neg_hi:[0,0,1]
	v_pk_mul_f32 v[18:19], v[18:19], s[16:17] op_sel_hi:[1,0]
	v_pk_mul_f32 v[12:13], v[12:13], s[16:17] op_sel_hi:[1,0]
	v_cvt_pk_bf16_f32 v9, v18, v19
	v_cvt_pk_bf16_f32 v5, v12, v13
	ds_read_b64 v[12:13], v0 offset:72
	ds_read_b64 v[16:17], v0 offset:200
	global_store_dwordx4 v[30:31], v[2:5], off offset:-48
	global_store_dwordx4 v[30:31], v[6:9], off offset:16
	s_waitcnt vmcnt(10)
	s_waitcnt lgkmcnt(2)
	v_readlane_b32 s98, v37, 16
	v_readlane_b32 s99, v37, 17
	v_readlane_b32 vcc_lo, v37, 48
	v_readlane_b32 vcc_hi, v37, 49
	v_pk_mul_f32 v[10:11], v[26:27], v[10:11]
	v_pk_mul_f32 v[14:15], v[26:27], v[14:15]
	v_pk_mul_f32 v[10:11], v[10:11], s[98:99]
	v_pk_mul_f32 v[14:15], v[14:15], vcc
	v_pk_mul_f32 v[18:19], v[10:11], v[66:67]
	s_nop 0
	v_pk_fma_f32 v[18:19], v[14:15], v[62:63], v[18:19]
	v_pk_mul_f32 v[14:15], v[14:15], v[66:67]
	s_nop 0
	v_pk_fma_f32 v[10:11], v[10:11], v[62:63], v[14:15] neg_lo:[0,0,1] neg_hi:[0,0,1]
	v_pk_mul_f32 v[18:19], v[18:19], s[16:17] op_sel_hi:[1,0]
	v_pk_mul_f32 v[10:11], v[10:11], s[16:17] op_sel_hi:[1,0]
	v_cvt_pk_bf16_f32 v6, v18, v19
	v_cvt_pk_bf16_f32 v2, v10, v11
	ds_read_b64 v[10:11], v0 offset:80
	ds_read_b64 v[14:15], v0 offset:208
	s_waitcnt lgkmcnt(2)
	v_readlane_b32 s98, v37, 18
	v_readlane_b32 s99, v37, 19
	v_readlane_b32 vcc_lo, v37, 50
	v_readlane_b32 vcc_hi, v37, 51
	v_pk_mul_f32 v[12:13], v[26:27], v[12:13]
	v_pk_mul_f32 v[16:17], v[26:27], v[16:17]
	v_pk_mul_f32 v[12:13], v[12:13], s[98:99]
	v_pk_mul_f32 v[16:17], v[16:17], vcc
	v_pk_mul_f32 v[18:19], v[12:13], v[68:69]
	s_nop 0
	v_pk_fma_f32 v[18:19], v[16:17], v[64:65], v[18:19]
	v_pk_mul_f32 v[16:17], v[16:17], v[68:69]
	s_nop 0
	v_pk_fma_f32 v[12:13], v[12:13], v[64:65], v[16:17] neg_lo:[0,0,1] neg_hi:[0,0,1]
	v_pk_mul_f32 v[18:19], v[18:19], s[16:17] op_sel_hi:[1,0]
	v_pk_mul_f32 v[12:13], v[12:13], s[16:17] op_sel_hi:[1,0]
	v_cvt_pk_bf16_f32 v7, v18, v19
	v_cvt_pk_bf16_f32 v3, v12, v13
	ds_read_b64 v[12:13], v0 offset:88
	ds_read_b64 v[16:17], v0 offset:216
	s_waitcnt vmcnt(8)
	s_waitcnt lgkmcnt(2)
	v_readlane_b32 s98, v37, 20
	v_readlane_b32 s99, v37, 21
	v_readlane_b32 vcc_lo, v37, 52
	v_readlane_b32 vcc_hi, v37, 53
	v_pk_mul_f32 v[10:11], v[26:27], v[10:11]
	v_pk_mul_f32 v[14:15], v[26:27], v[14:15]
	v_pk_mul_f32 v[10:11], v[10:11], s[98:99]
	v_pk_mul_f32 v[14:15], v[14:15], vcc
	v_pk_mul_f32 v[18:19], v[10:11], v[74:75]
	s_nop 0
	v_pk_fma_f32 v[18:19], v[14:15], v[70:71], v[18:19]
	v_pk_mul_f32 v[14:15], v[14:15], v[74:75]
	s_nop 0
	v_pk_fma_f32 v[10:11], v[10:11], v[70:71], v[14:15] neg_lo:[0,0,1] neg_hi:[0,0,1]
	v_pk_mul_f32 v[18:19], v[18:19], s[16:17] op_sel_hi:[1,0]
	v_pk_mul_f32 v[10:11], v[10:11], s[16:17] op_sel_hi:[1,0]
	v_cvt_pk_bf16_f32 v8, v18, v19
	v_cvt_pk_bf16_f32 v4, v10, v11
	ds_read_b64 v[10:11], v0 offset:96
	ds_read_b64 v[14:15], v0 offset:224
	s_waitcnt lgkmcnt(2)
; DI uint4 pack8(const float* v) { uint4 r; r.x = pk2(v[0], v[1]); r.y = pk2(v[2], v[3]); r.z = pk2(v[4], v[5]); r.w = pk2(v[6], v[7]); return r; }
; DI void qk_epilogue(const float* st  , int m0, const float* __restrict__ gain, float scale, bf16_t* __restrict__ dst, int dstride, int dcol0,
;                     const float* __restrict__ COS, const float* __restrict__ SIN) {
;     ...
;   for (int j = 0; j < 32; j += 8) {
;     float o1[8], o2[8];
; #pragma unroll
;     for (int q = 0; q < 8; ++q) {
;       const float x1 = sp[j + q] * rr * gain[j + q], x2 = sp[j + q + 32] * rr * gain[j + q + 32];
;       const float cs = COS[tok * 32 + j + q], sn = SIN[tok * 32 + j + q];
;       o1[q] = (x1 * cs - x2 * sn) * scale;
;       o2[q] = (x2 * cs + x1 * sn) * scale;
;     }
;     *(uint4*)(dp + j) = pack8(o1);
;     *(uint4*)(dp + j + 32) = pack8(o2);
;   }
	v_readlane_b32 s98, v37, 22
	v_readlane_b32 s99, v37, 23
	v_readlane_b32 vcc_lo, v37, 54
	v_readlane_b32 vcc_hi, v37, 55
	v_pk_mul_f32 v[12:13], v[26:27], v[12:13]
	v_pk_mul_f32 v[16:17], v[26:27], v[16:17]
	v_pk_mul_f32 v[12:13], v[12:13], s[98:99]
	v_pk_mul_f32 v[16:17], v[16:17], vcc
	v_pk_mul_f32 v[18:19], v[12:13], v[76:77]
	s_nop 0
	v_pk_fma_f32 v[18:19], v[16:17], v[72:73], v[18:19]
	v_pk_mul_f32 v[16:17], v[16:17], v[76:77]
	s_nop 0
	v_pk_fma_f32 v[12:13], v[12:13], v[72:73], v[16:17] neg_lo:[0,0,1] neg_hi:[0,0,1]
	v_pk_mul_f32 v[18:19], v[18:19], s[16:17] op_sel_hi:[1,0]
	v_pk_mul_f32 v[12:13], v[12:13], s[16:17] op_sel_hi:[1,0]
	v_cvt_pk_bf16_f32 v9, v18, v19
	v_cvt_pk_bf16_f32 v5, v12, v13
	ds_read_b64 v[12:13], v0 offset:104
	ds_read_b64 v[16:17], v0 offset:232
	global_store_dwordx4 v[30:31], v[2:5], off offset:-32
	global_store_dwordx4 v[30:31], v[6:9], off offset:32
	s_waitcnt vmcnt(8)
	s_waitcnt lgkmcnt(2)
	v_readlane_b32 s98, v37, 24
	v_readlane_b32 s99, v37, 25
	v_readlane_b32 vcc_lo, v37, 56
	v_readlane_b32 vcc_hi, v37, 57
	v_pk_mul_f32 v[10:11], v[26:27], v[10:11]
	v_pk_mul_f32 v[14:15], v[26:27], v[14:15]
	v_pk_mul_f32 v[10:11], v[10:11], s[98:99]
	v_pk_mul_f32 v[14:15], v[14:15], vcc
	v_pk_mul_f32 v[18:19], v[10:11], v[82:83]
	s_nop 0
	v_pk_fma_f32 v[18:19], v[14:15], v[78:79], v[18:19]
	v_pk_mul_f32 v[14:15], v[14:15], v[82:83]
	s_nop 0
	v_pk_fma_f32 v[10:11], v[10:11], v[78:79], v[14:15] neg_lo:[0,0,1] neg_hi:[0,0,1]
	v_pk_mul_f32 v[18:19], v[18:19], s[16:17] op_sel_hi:[1,0]
	v_pk_mul_f32 v[10:11], v[10:11], s[16:17] op_sel_hi:[1,0]
	v_cvt_pk_bf16_f32 v6, v18, v19
	v_cvt_pk_bf16_f32 v2, v10, v11
	ds_read_b64 v[10:11], v0 offset:112
	ds_read_b64 v[14:15], v0 offset:240
	s_waitcnt lgkmcnt(2)
	v_readlane_b32 s98, v37, 26
	v_readlane_b32 s99, v37, 27
	v_readlane_b32 vcc_lo, v37, 58
	v_readlane_b32 vcc_hi, v37, 59
	v_pk_mul_f32 v[12:13], v[26:27], v[12:13]
	v_pk_mul_f32 v[16:17], v[26:27], v[16:17]
	v_pk_mul_f32 v[12:13], v[12:13], s[98:99]
	v_pk_mul_f32 v[16:17], v[16:17], vcc
	v_pk_mul_f32 v[18:19], v[12:13], v[84:85]
	s_nop 0
	v_pk_fma_f32 v[18:19], v[16:17], v[80:81], v[18:19]
	v_pk_mul_f32 v[16:17], v[16:17], v[84:85]
	s_nop 0
	v_pk_fma_f32 v[12:13], v[12:13], v[80:81], v[16:17] neg_lo:[0,0,1] neg_hi:[0,0,1]
	v_pk_mul_f32 v[18:19], v[18:19], s[16:17] op_sel_hi:[1,0]
	v_pk_mul_f32 v[12:13], v[12:13], s[16:17] op_sel_hi:[1,0]
	v_cvt_pk_bf16_f32 v7, v18, v19
	v_cvt_pk_bf16_f32 v3, v12, v13
	ds_read_b64 v[12:13], v0 offset:120
	ds_read_b64 v[16:17], v0 offset:248
	s_waitcnt vmcnt(6)
	s_waitcnt lgkmcnt(2)
	v_readlane_b32 s98, v37, 28
	v_readlane_b32 s99, v37, 29
	v_readlane_b32 vcc_lo, v37, 60
	v_readlane_b32 vcc_hi, v37, 61
	v_pk_mul_f32 v[10:11], v[26:27], v[10:11]
	v_pk_mul_f32 v[14:15], v[26:27], v[14:15]
	v_pk_mul_f32 v[10:11], v[10:11], s[98:99]
	v_pk_mul_f32 v[14:15], v[14:15], vcc
	v_pk_mul_f32 v[18:19], v[10:11], v[90:91]
	s_nop 0
	v_pk_fma_f32 v[18:19], v[14:15], v[86:87], v[18:19]
	v_pk_mul_f32 v[14:15], v[14:15], v[90:91]
	s_nop 0
	v_pk_fma_f32 v[10:11], v[10:11], v[86:87], v[14:15] neg_lo:[0,0,1] neg_hi:[0,0,1]
	v_pk_mul_f32 v[18:19], v[18:19], s[16:17] op_sel_hi:[1,0]
	v_pk_mul_f32 v[10:11], v[10:11], s[16:17] op_sel_hi:[1,0]
	v_cvt_pk_bf16_f32 v8, v18, v19
	v_cvt_pk_bf16_f32 v4, v10, v11
	s_waitcnt lgkmcnt(0)
	v_readlane_b32 s98, v37, 30
	v_readlane_b32 s99, v37, 31
	v_readlane_b32 vcc_lo, v37, 62
	v_readlane_b32 vcc_hi, v37, 63
	v_pk_mul_f32 v[12:13], v[26:27], v[12:13]
	v_pk_mul_f32 v[16:17], v[26:27], v[16:17]
	v_pk_mul_f32 v[12:13], v[12:13], s[98:99]
	v_pk_mul_f32 v[16:17], v[16:17], vcc
	v_pk_mul_f32 v[18:19], v[12:13], v[92:93]
	s_nop 0
	v_pk_fma_f32 v[18:19], v[16:17], v[88:89], v[18:19]
	v_pk_mul_f32 v[16:17], v[16:17], v[92:93]
	s_nop 0
	v_pk_fma_f32 v[12:13], v[12:13], v[88:89], v[16:17] neg_lo:[0,0,1] neg_hi:[0,0,1]
	v_pk_mul_f32 v[18:19], v[18:19], s[16:17] op_sel_hi:[1,0]
	v_pk_mul_f32 v[12:13], v[12:13], s[16:17] op_sel_hi:[1,0]
	v_cvt_pk_bf16_f32 v9, v18, v19
	v_cvt_pk_bf16_f32 v5, v12, v13
	global_store_dwordx4 v[30:31], v[2:5], off offset:-16
	global_store_dwordx4 v[30:31], v[6:9], off offset:48
	s_branch .LBB0_329
